# v17: v15 + lever 4: one static s_setprio 1 for waves 4-7 over each GEMM phase, all 192 per-segment s_setprio flips deleted
# speedup vs baseline: 1.0005x; 1.0005x over previous
; __global__ void __launch_bounds__(NWAVES * 64, 2) mk_fwd(Args args) {
;     ...
;     if (IN(G_WIN)) {
;         {
;             pg8::Gemm g{(const bf16*)(ws + WS_X8), (const bf16*)(ws + WS_WIN8), M, NQKV, D / 2, D / 2, D / 2, 0}; pg8::StaticOrder S; S.init(M, NQKV, F.G, bx);
;             pg8::EpiWin8 E{(bf16*)(ws + WS_QKV), (bf16*)(ws + WS_Z), (bf16*)(ws + WS_GT), RSTD, (const float*)(ws + WS_SX), (const float*)(ws + WS_SW), 0};
;             pg8::gemm_phase<pg8::EpiWin8, pg8::StaticOrder, true, true, true>(F.lds + RING_OFF, g, S, E);
.LBB0_471:
	s_cmp_lt_i32 s4, 2
	s_cselect_b64 s[0:1], -1, 0
	s_cmp_gt_i32 s5, 1
	s_cselect_b64 s[2:3], -1, 0
	s_and_b64 s[0:1], s[0:1], s[2:3]
	s_andn2_b64 vcc, exec, s[0:1]
	s_cbranch_vccnz .LBB0_708
	v_readfirstlane_b32 s98, v0
	s_nop 3
	s_and_b32 s98, s98, 0x3ff
	s_lshr_b32 s98, s98, 6
	s_cmp_ge_u32 s98, 4
	s_cbranch_scc0 .Lprio_gwin
	s_setprio 1

; #define PG8_STAGE(bufoff, gbase, voff) do { _Pragma("unroll") for (int _i = 0; _i < 2; ++_i) \
;         __builtin_amdgcn_global_load_lds((const unsigned*)((const char*)(gbase) + (voff)[_i]), (PG8_LAS unsigned*)(lds + (bufoff) + ldsw + _i * 8192), 16, 0, 0); } while (0)
; #define PG8_LDA(dst, b, h) do { _Pragma("unroll") for (int m = 0; m < 4; ++m) _Pragma("unroll") for (int k = 0; k < 2; ++k) dst[m][k] = *(const PG8_LAS bf16x8*)(lds + PG8_SA(b, h) + aoff + m * 2048 + k * 1024); } while (0)
; #define PG8_LDB(dst, b, h) do { _Pragma("unroll") for (int n = 0; n < 2; ++n) _Pragma("unroll") for (int k = 0; k < 2; ++k) dst[n][k] = *(const PG8_LAS bf16x8*)(lds + PG8_SB(b, h) + boff + n * 2048 + k * 1024); } while (0)
; #define PG8_MMA(ai, bj, At, Bt) do { __builtin_amdgcn_s_setprio(1); _Pragma("unroll") for (int m = 0; m < 4; ++m) _Pragma("unroll") for (int n = 0; n < 2; ++n) _Pragma("unroll") for (int k = 0; k < 2; ++k) \
;         acc[ai][bj][m][n] = mma_<I8>(Bt[n][k], At[m][k], acc[ai][bj][m][n]); __builtin_amdgcn_s_setprio(0); } while (0)
; #define PG8_WAIT_V(n) asm volatile("s_waitcnt vmcnt(" #n ")" ::: "memory")
; #define PG8_WAIT_L(n) asm volatile("s_waitcnt lgkmcnt(" #n ")" ::: "memory")
; #define PG8_BAR __builtin_amdgcn_s_barrier()
; #define PG8_SCHED __builtin_amdgcn_sched_barrier(0)
; template <class Epi, class Sched, bool ALIGN_EPI = false, bool SP2 = false, bool I8 = false>
; __device__ __forceinline__ void gemm_phase(PG8_LAS unsigned char* lds, const Gemm g, const Sched& S, const Epi& E) {
;     ...
;             if constexpr (SP2) {
;             PG8_LDB(B0, 0, 0); PG8_LDB(B1, 0, 1); PG8_SCHED; PG8_LDA(At, 0, 0); PG8_STAGE(PG8_SA(1, 1), a1 + hstepA, voffA);
;             PG8_WAIT_V(8); PG8_WAIT_L(0); PG8_BAR; PG8_MMA(0, 0, At, B0); PG8_MMA(0, 1, At, B1); PG8_BAR; PG8_SCHED;
;             PG8_LDA(At, 0, 1); PG8_STAGE(PG8_SB(0, 0), b2, voffB); PG8_STAGE(PG8_SB(0, 1), b2 + hstepB, voffB); PG8_STAGE(PG8_SA(0, 0), a2, voffA);
.LBB0_483:
	ds_read_b128 v[58:61], v187
	ds_read_b128 v[62:65], v187 offset:1024
	ds_read_b128 v[74:77], v187 offset:2048
	ds_read_b128 v[78:81], v187 offset:3072
	ds_read_b128 v[162:165], v188
	ds_read_b128 v[166:169], v188 offset:1024
	ds_read_b128 v[170:173], v188 offset:2048
	ds_read_b128 v[190:193], v188 offset:3072
	s_add_u32 s34, s2, 0xfff80080
	s_addc_u32 s35, s3, -1
	s_cmp_eq_u32 s40, 28
	s_cselect_b32 s37, s7, s35
	s_cselect_b32 s36, s25, s34
	s_cselect_b32 s35, s23, s39
	s_cselect_b32 s34, s33, s38
	v_lshl_add_u64 v[174:175], s[2:3], 0, v[154:155]
	s_add_i32 m0, s31, 0xc000
	ds_read_b128 v[194:197], v189
	ds_read_b128 v[198:201], v189 offset:1024
	ds_read_b128 v[202:205], v189 offset:2048
	ds_read_b128 v[206:209], v189 offset:3072
	ds_read_b128 v[210:213], v189 offset:4096
	ds_read_b128 v[214:217], v189 offset:5120
	ds_read_b128 v[218:221], v189 offset:6144
	ds_read_b128 v[222:225], v189 offset:7168
	global_load_lds_dwordx4 v[174:175], off
	v_lshl_add_u64 v[174:175], s[2:3], 0, v[156:157]
	s_add_i32 m0, s31, 0xe000
	s_nop 0
	global_load_lds_dwordx4 v[174:175], off
	s_waitcnt vmcnt(8)
	s_waitcnt lgkmcnt(0)
	s_barrier
	s_waitcnt lgkmcnt(0)
	v_mfma_i32_16x16x64_i8 v[142:145], v[58:61], v[194:197], v[142:145]
	v_mfma_i32_16x16x64_i8 v[138:141], v[74:77], v[194:197], v[138:141]
	v_mfma_i32_16x16x64_i8 v[126:129], v[58:61], v[202:205], v[126:129]
	v_mfma_i32_16x16x64_i8 v[122:125], v[74:77], v[202:205], v[122:125]
	v_mfma_i32_16x16x64_i8 v[110:113], v[58:61], v[210:213], v[110:113]
	v_mfma_i32_16x16x64_i8 v[106:109], v[74:77], v[210:213], v[106:109]
	v_mfma_i32_16x16x64_i8 v[94:97], v[58:61], v[218:221], v[94:97]
	v_mfma_i32_16x16x64_i8 v[90:93], v[74:77], v[218:221], v[90:93]
	v_mfma_i32_16x16x64_i8 v[142:145], v[62:65], v[198:201], v[142:145]
	v_mfma_i32_16x16x64_i8 v[138:141], v[78:81], v[198:201], v[138:141]
	v_mfma_i32_16x16x64_i8 v[126:129], v[62:65], v[206:209], v[126:129]
	v_mfma_i32_16x16x64_i8 v[122:125], v[78:81], v[206:209], v[122:125]
	v_mfma_i32_16x16x64_i8 v[110:113], v[62:65], v[214:217], v[110:113]
	v_mfma_i32_16x16x64_i8 v[106:109], v[78:81], v[214:217], v[106:109]
	v_mfma_i32_16x16x64_i8 v[94:97], v[62:65], v[222:225], v[94:97]
	v_mfma_i32_16x16x64_i8 v[90:93], v[78:81], v[222:225], v[90:93]
	v_mfma_i32_16x16x64_i8 v[134:137], v[162:165], v[194:197], v[134:137]
	v_mfma_i32_16x16x64_i8 v[130:133], v[170:173], v[194:197], v[130:133]
	v_mfma_i32_16x16x64_i8 v[118:121], v[162:165], v[202:205], v[118:121]
	v_mfma_i32_16x16x64_i8 v[114:117], v[170:173], v[202:205], v[114:117]
	v_mfma_i32_16x16x64_i8 v[102:105], v[162:165], v[210:213], v[102:105]
	v_mfma_i32_16x16x64_i8 v[98:101], v[170:173], v[210:213], v[98:101]
	v_mfma_i32_16x16x64_i8 v[86:89], v[162:165], v[218:221], v[86:89]
	v_mfma_i32_16x16x64_i8 v[82:85], v[170:173], v[218:221], v[82:85]
	v_mfma_i32_16x16x64_i8 v[134:137], v[166:169], v[198:201], v[134:137]
	v_mfma_i32_16x16x64_i8 v[130:133], v[190:193], v[198:201], v[130:133]
	v_mfma_i32_16x16x64_i8 v[118:121], v[166:169], v[206:209], v[118:121]
	v_mfma_i32_16x16x64_i8 v[114:117], v[190:193], v[206:209], v[114:117]
	v_mfma_i32_16x16x64_i8 v[102:105], v[166:169], v[214:217], v[102:105]
	v_mfma_i32_16x16x64_i8 v[98:101], v[190:193], v[214:217], v[98:101]
	v_mfma_i32_16x16x64_i8 v[86:89], v[166:169], v[222:225], v[86:89]
	v_mfma_i32_16x16x64_i8 v[82:85], v[190:193], v[222:225], v[82:85]
	s_barrier
	s_add_i32 s41, s8, s68
	v_lshl_add_u64 v[174:175], s[34:35], 0, v[148:149]
	s_mov_b32 m0, s41
	ds_read_b128 v[194:197], v189 offset:16384
	ds_read_b128 v[198:201], v189 offset:17408
	ds_read_b128 v[202:205], v189 offset:18432
	ds_read_b128 v[206:209], v189 offset:19456
	ds_read_b128 v[210:213], v189 offset:20480
	ds_read_b128 v[214:217], v189 offset:21504
	ds_read_b128 v[218:221], v189 offset:22528
	ds_read_b128 v[222:225], v189 offset:23552
	global_load_lds_dwordx4 v[174:175], off
	s_add_i32 m0, s41, 0x2000
	s_add_u32 vcc_lo, s34, 0x80000
	v_lshl_add_u64 v[226:227], s[34:35], 0, v[152:153]
	s_addc_u32 vcc_hi, s35, 0
	s_add_i32 s41, s9, s68
	global_load_lds_dwordx4 v[226:227], off
	v_lshl_add_u64 v[228:229], vcc, 0, v[148:149]
	s_mov_b32 m0, s41
	v_lshl_add_u64 v[230:231], s[36:37], 0, v[150:151]
	global_load_lds_dwordx4 v[228:229], off
	v_lshl_add_u64 v[228:229], vcc, 0, v[152:153]
	s_add_i32 m0, s41, 0x2000
	s_nop 0
	global_load_lds_dwordx4 v[228:229], off
	v_lshl_add_u64 v[228:229], s[36:37], 0, v[146:147]
	s_mov_b32 m0, s31
	s_nop 0
	global_load_lds_dwordx4 v[228:229], off
	s_mov_b32 m0, s69
	s_nop 0
	global_load_lds_dwordx4 v[230:231], off
	s_waitcnt vmcnt(8)
	s_waitcnt lgkmcnt(0)
	s_barrier
; #define PG8_STAGE(bufoff, gbase, voff) do { _Pragma("unroll") for (int _i = 0; _i < 2; ++_i) \
;         __builtin_amdgcn_global_load_lds((const unsigned*)((const char*)(gbase) + (voff)[_i]), (PG8_LAS unsigned*)(lds + (bufoff) + ldsw + _i * 8192), 16, 0, 0); } while (0)
; #define PG8_LDA(dst, b, h) do { _Pragma("unroll") for (int m = 0; m < 4; ++m) _Pragma("unroll") for (int k = 0; k < 2; ++k) dst[m][k] = *(const PG8_LAS bf16x8*)(lds + PG8_SA(b, h) + aoff + m * 2048 + k * 1024); } while (0)
; #define PG8_LDB(dst, b, h) do { _Pragma("unroll") for (int n = 0; n < 2; ++n) _Pragma("unroll") for (int k = 0; k < 2; ++k) dst[n][k] = *(const PG8_LAS bf16x8*)(lds + PG8_SB(b, h) + boff + n * 2048 + k * 1024); } while (0)
; #define PG8_MMA(ai, bj, At, Bt) do { __builtin_amdgcn_s_setprio(1); _Pragma("unroll") for (int m = 0; m < 4; ++m) _Pragma("unroll") for (int n = 0; n < 2; ++n) _Pragma("unroll") for (int k = 0; k < 2; ++k) \
;         acc[ai][bj][m][n] = mma_<I8>(Bt[n][k], At[m][k], acc[ai][bj][m][n]); __builtin_amdgcn_s_setprio(0); } while (0)
; #define PG8_WAIT_V(n) asm volatile("s_waitcnt vmcnt(" #n ")" ::: "memory")
; #define PG8_WAIT_L(n) asm volatile("s_waitcnt lgkmcnt(" #n ")" ::: "memory")
; #define PG8_BAR __builtin_amdgcn_s_barrier()
; #define PG8_SCHED __builtin_amdgcn_sched_barrier(0)
; template <class Epi, class Sched, bool ALIGN_EPI = false, bool SP2 = false, bool I8 = false>
; __device__ __forceinline__ void gemm_phase(PG8_LAS unsigned char* lds, const Gemm g, const Sched& S, const Epi& E) {
;     ...
;             if constexpr (SP2) {
;             PG8_LDB(B0, 0, 0); PG8_LDB(B1, 0, 1); PG8_SCHED; PG8_LDA(At, 0, 0); PG8_STAGE(PG8_SA(1, 1), a1 + hstepA, voffA);
;             PG8_WAIT_V(8); PG8_WAIT_L(0); PG8_BAR; PG8_MMA(0, 0, At, B0); PG8_MMA(0, 1, At, B1); PG8_BAR; PG8_SCHED;
;             PG8_LDA(At, 0, 1); PG8_STAGE(PG8_SB(0, 0), b2, voffB); PG8_STAGE(PG8_SB(0, 1), b2 + hstepB, voffB); PG8_STAGE(PG8_SA(0, 0), a2, voffA);
;             PG8_WAIT_V(8); PG8_WAIT_L(0); PG8_BAR; PG8_MMA(1, 0, At, B0); PG8_MMA(1, 1, At, B1); PG8_BAR; PG8_SCHED;
;             PG8_LDB(B0, 1, 0); PG8_LDB(B1, 1, 1); PG8_SCHED; PG8_LDA(At, 1, 0); PG8_STAGE(PG8_SA(0, 1), a2 + hstepA, voffA);
;             PG8_WAIT_V(8); PG8_WAIT_L(0); PG8_BAR; PG8_MMA(0, 0, At, B0); PG8_MMA(0, 1, At, B1); PG8_BAR; PG8_SCHED;
	s_waitcnt lgkmcnt(0)
	v_mfma_i32_16x16x64_i8 v[70:73], v[58:61], v[194:197], v[70:73]
	v_mfma_i32_16x16x64_i8 v[66:69], v[74:77], v[194:197], v[66:69]
	v_mfma_i32_16x16x64_i8 v[46:49], v[58:61], v[202:205], v[46:49]
	v_mfma_i32_16x16x64_i8 v[42:45], v[74:77], v[202:205], v[42:45]
	v_mfma_i32_16x16x64_i8 v[30:33], v[58:61], v[210:213], v[30:33]
	v_mfma_i32_16x16x64_i8 v[26:29], v[74:77], v[210:213], v[26:29]
	v_mfma_i32_16x16x64_i8 v[14:17], v[58:61], v[218:221], v[14:17]
	v_mfma_i32_16x16x64_i8 v[10:13], v[74:77], v[218:221], v[10:13]
	v_mfma_i32_16x16x64_i8 v[70:73], v[62:65], v[198:201], v[70:73]
	v_mfma_i32_16x16x64_i8 v[66:69], v[78:81], v[198:201], v[66:69]
	v_mfma_i32_16x16x64_i8 v[46:49], v[62:65], v[206:209], v[46:49]
	v_mfma_i32_16x16x64_i8 v[42:45], v[78:81], v[206:209], v[42:45]
	v_mfma_i32_16x16x64_i8 v[30:33], v[62:65], v[214:217], v[30:33]
	v_mfma_i32_16x16x64_i8 v[26:29], v[78:81], v[214:217], v[26:29]
	v_mfma_i32_16x16x64_i8 v[14:17], v[62:65], v[222:225], v[14:17]
	v_mfma_i32_16x16x64_i8 v[10:13], v[78:81], v[222:225], v[10:13]
	v_mfma_i32_16x16x64_i8 v[54:57], v[162:165], v[194:197], v[54:57]
	v_mfma_i32_16x16x64_i8 v[50:53], v[170:173], v[194:197], v[50:53]
	v_mfma_i32_16x16x64_i8 v[38:41], v[162:165], v[202:205], v[38:41]
	v_mfma_i32_16x16x64_i8 v[34:37], v[170:173], v[202:205], v[34:37]
	v_mfma_i32_16x16x64_i8 v[22:25], v[162:165], v[210:213], v[22:25]
	v_mfma_i32_16x16x64_i8 v[18:21], v[170:173], v[210:213], v[18:21]
	v_mfma_i32_16x16x64_i8 v[6:9], v[162:165], v[218:221], v[6:9]
	v_mfma_i32_16x16x64_i8 v[2:5], v[170:173], v[218:221], v[2:5]
	v_mfma_i32_16x16x64_i8 v[54:57], v[166:169], v[198:201], v[54:57]
	v_mfma_i32_16x16x64_i8 v[50:53], v[190:193], v[198:201], v[50:53]
	v_mfma_i32_16x16x64_i8 v[38:41], v[166:169], v[206:209], v[38:41]
	v_mfma_i32_16x16x64_i8 v[34:37], v[190:193], v[206:209], v[34:37]
	v_mfma_i32_16x16x64_i8 v[22:25], v[166:169], v[214:217], v[22:25]
	v_mfma_i32_16x16x64_i8 v[18:21], v[190:193], v[214:217], v[18:21]
	v_mfma_i32_16x16x64_i8 v[6:9], v[166:169], v[222:225], v[6:9]
	v_mfma_i32_16x16x64_i8 v[2:5], v[190:193], v[222:225], v[2:5]
	s_barrier
	s_add_i32 s41, 0, 0x18000
	s_add_i32 s95, 0, 0x1c000
	v_add_u32_e32 v78, s41, v181
	v_add_u32_e32 v190, s95, v181
	ds_read_b128 v[58:61], v78
	ds_read_b128 v[62:65], v78 offset:1024
	ds_read_b128 v[74:77], v78 offset:2048
	ds_read_b128 v[78:81], v78 offset:3072
	ds_read_b128 v[162:165], v190
	ds_read_b128 v[166:169], v190 offset:1024
	ds_read_b128 v[170:173], v190 offset:2048
	ds_read_b128 v[190:193], v190 offset:3072
	s_add_u32 s36, s36, 0x80000
	s_addc_u32 s37, s37, 0
	s_mov_b32 m0, s70
	v_lshl_add_u64 v[234:235], s[36:37], 0, v[146:147]
	ds_read_b128 v[194:197], v189 offset:32768
	ds_read_b128 v[198:201], v189 offset:33792
	ds_read_b128 v[202:205], v189 offset:34816
	ds_read_b128 v[206:209], v189 offset:35840
	ds_read_b128 v[210:213], v189 offset:36864
	ds_read_b128 v[214:217], v189 offset:37888
	ds_read_b128 v[218:221], v189 offset:38912
	ds_read_b128 v[222:225], v189 offset:39936
	global_load_lds_dwordx4 v[234:235], off
	v_lshl_add_u64 v[234:235], s[36:37], 0, v[150:151]
	s_mov_b32 m0, s71
	s_nop 0
	global_load_lds_dwordx4 v[234:235], off
	s_waitcnt vmcnt(8)
	s_waitcnt lgkmcnt(0)
	s_barrier
	s_waitcnt lgkmcnt(0)
	v_mfma_i32_16x16x64_i8 v[142:145], v[58:61], v[194:197], v[142:145]
	v_mfma_i32_16x16x64_i8 v[138:141], v[74:77], v[194:197], v[138:141]
	v_mfma_i32_16x16x64_i8 v[126:129], v[58:61], v[202:205], v[126:129]
	v_mfma_i32_16x16x64_i8 v[122:125], v[74:77], v[202:205], v[122:125]
	v_mfma_i32_16x16x64_i8 v[110:113], v[58:61], v[210:213], v[110:113]
	v_mfma_i32_16x16x64_i8 v[106:109], v[74:77], v[210:213], v[106:109]
	v_mfma_i32_16x16x64_i8 v[94:97], v[58:61], v[218:221], v[94:97]
	v_mfma_i32_16x16x64_i8 v[90:93], v[74:77], v[218:221], v[90:93]
	v_mfma_i32_16x16x64_i8 v[142:145], v[62:65], v[198:201], v[142:145]
	v_mfma_i32_16x16x64_i8 v[138:141], v[78:81], v[198:201], v[138:141]
	v_mfma_i32_16x16x64_i8 v[126:129], v[62:65], v[206:209], v[126:129]
	v_mfma_i32_16x16x64_i8 v[122:125], v[78:81], v[206:209], v[122:125]
	v_mfma_i32_16x16x64_i8 v[110:113], v[62:65], v[214:217], v[110:113]
	v_mfma_i32_16x16x64_i8 v[106:109], v[78:81], v[214:217], v[106:109]
	v_mfma_i32_16x16x64_i8 v[94:97], v[62:65], v[222:225], v[94:97]
	v_mfma_i32_16x16x64_i8 v[90:93], v[78:81], v[222:225], v[90:93]
	v_mfma_i32_16x16x64_i8 v[134:137], v[162:165], v[194:197], v[134:137]
	v_mfma_i32_16x16x64_i8 v[130:133], v[170:173], v[194:197], v[130:133]
	v_mfma_i32_16x16x64_i8 v[118:121], v[162:165], v[202:205], v[118:121]
	v_mfma_i32_16x16x64_i8 v[114:117], v[170:173], v[202:205], v[114:117]
	v_mfma_i32_16x16x64_i8 v[102:105], v[162:165], v[210:213], v[102:105]
	v_mfma_i32_16x16x64_i8 v[98:101], v[170:173], v[210:213], v[98:101]
	v_mfma_i32_16x16x64_i8 v[86:89], v[162:165], v[218:221], v[86:89]
	v_mfma_i32_16x16x64_i8 v[82:85], v[170:173], v[218:221], v[82:85]
	v_mfma_i32_16x16x64_i8 v[134:137], v[166:169], v[198:201], v[134:137]
	v_mfma_i32_16x16x64_i8 v[130:133], v[190:193], v[198:201], v[130:133]
	v_mfma_i32_16x16x64_i8 v[118:121], v[166:169], v[206:209], v[118:121]
	v_mfma_i32_16x16x64_i8 v[114:117], v[190:193], v[206:209], v[114:117]
	v_mfma_i32_16x16x64_i8 v[102:105], v[166:169], v[214:217], v[102:105]
	v_mfma_i32_16x16x64_i8 v[98:101], v[190:193], v[214:217], v[98:101]
	v_mfma_i32_16x16x64_i8 v[86:89], v[166:169], v[222:225], v[86:89]
	v_mfma_i32_16x16x64_i8 v[82:85], v[190:193], v[222:225], v[82:85]
	s_barrier
; #define PG8_STAGE(bufoff, gbase, voff) do { _Pragma("unroll") for (int _i = 0; _i < 2; ++_i) \
;         __builtin_amdgcn_global_load_lds((const unsigned*)((const char*)(gbase) + (voff)[_i]), (PG8_LAS unsigned*)(lds + (bufoff) + ldsw + _i * 8192), 16, 0, 0); } while (0)
; #define PG8_LDA(dst, b, h) do { _Pragma("unroll") for (int m = 0; m < 4; ++m) _Pragma("unroll") for (int k = 0; k < 2; ++k) dst[m][k] = *(const PG8_LAS bf16x8*)(lds + PG8_SA(b, h) + aoff + m * 2048 + k * 1024); } while (0)
; #define PG8_MMA(ai, bj, At, Bt) do { __builtin_amdgcn_s_setprio(1); _Pragma("unroll") for (int m = 0; m < 4; ++m) _Pragma("unroll") for (int n = 0; n < 2; ++n) _Pragma("unroll") for (int k = 0; k < 2; ++k) \
;         acc[ai][bj][m][n] = mma_<I8>(Bt[n][k], At[m][k], acc[ai][bj][m][n]); __builtin_amdgcn_s_setprio(0); } while (0)
; #define PG8_WAIT_V(n) asm volatile("s_waitcnt vmcnt(" #n ")" ::: "memory")
; #define PG8_WAIT_L(n) asm volatile("s_waitcnt lgkmcnt(" #n ")" ::: "memory")
; #define PG8_BAR __builtin_amdgcn_s_barrier()
; #define PG8_SCHED __builtin_amdgcn_sched_barrier(0)
; template <class Epi, class Sched, bool ALIGN_EPI = false, bool SP2 = false, bool I8 = false>
; __device__ __forceinline__ void gemm_phase(PG8_LAS unsigned char* lds, const Gemm g, const Sched& S, const Epi& E) {
;     ...
;         for (int t = 0; t < nt; t += 2) {
;             const bool last = (t == nt - 2);
;             const char* a1 = cA + (size_t)(t + 1) * kstep;
;             const char* a2 = last ? nA : cA + (size_t)(t + 2) * kstep; const char* b2 = last ? nB : cB + (size_t)(t + 2) * kstep;
;     ...
;             PG8_LDA(At, 1, 1); PG8_STAGE(PG8_SB(1, 0), b3, voffB); PG8_STAGE(PG8_SB(1, 1), b3 + hstepB, voffB); PG8_STAGE(PG8_SA(1, 0), a3, voffA);
;             PG8_WAIT_V(8); PG8_WAIT_L(0); PG8_BAR; PG8_MMA(1, 0, At, B0); PG8_MMA(1, 1, At, B1); PG8_BAR; PG8_SCHED;
	s_add_i32 s36, s41, s68
	v_lshl_add_u64 v[174:175], v[174:175], 0, s[18:19]
	s_mov_b32 m0, s36
	ds_read_b128 v[194:197], v189 offset:49152
	ds_read_b128 v[198:201], v189 offset:50176
	ds_read_b128 v[202:205], v189 offset:51200
	ds_read_b128 v[206:209], v189 offset:52224
	ds_read_b128 v[210:213], v189 offset:53248
	ds_read_b128 v[214:217], v189 offset:54272
	ds_read_b128 v[218:221], v189 offset:55296
	ds_read_b128 v[222:225], v189 offset:56320
	global_load_lds_dwordx4 v[174:175], off
	s_add_i32 m0, s36, 0x2000
	s_add_u32 s34, s34, 0x80080
	v_lshl_add_u64 v[174:175], v[226:227], 0, s[18:19]
	s_addc_u32 s35, s35, 0
	s_add_i32 s36, s95, s68
	global_load_lds_dwordx4 v[174:175], off
	v_lshl_add_u64 v[174:175], s[34:35], 0, v[148:149]
	s_mov_b32 m0, s36
	s_nop 0
	global_load_lds_dwordx4 v[174:175], off
	v_lshl_add_u64 v[174:175], s[34:35], 0, v[152:153]
	s_add_i32 m0, s36, 0x2000
	s_nop 0
	global_load_lds_dwordx4 v[174:175], off
	v_lshl_add_u64 v[174:175], v[228:229], 0, s[18:19]
	s_mov_b32 m0, s89
	s_nop 0
	global_load_lds_dwordx4 v[174:175], off
	v_lshl_add_u64 v[174:175], v[230:231], 0, s[18:19]
	s_mov_b32 m0, s92
	s_nop 0
	global_load_lds_dwordx4 v[174:175], off
	s_waitcnt vmcnt(8)
	s_waitcnt lgkmcnt(0)
	s_barrier
	s_waitcnt lgkmcnt(0)
	v_mfma_i32_16x16x64_i8 v[70:73], v[58:61], v[194:197], v[70:73]
	v_mfma_i32_16x16x64_i8 v[66:69], v[74:77], v[194:197], v[66:69]
	v_mfma_i32_16x16x64_i8 v[46:49], v[58:61], v[202:205], v[46:49]
	v_mfma_i32_16x16x64_i8 v[42:45], v[74:77], v[202:205], v[42:45]
	v_mfma_i32_16x16x64_i8 v[30:33], v[58:61], v[210:213], v[30:33]
	v_mfma_i32_16x16x64_i8 v[26:29], v[74:77], v[210:213], v[26:29]
	v_mfma_i32_16x16x64_i8 v[14:17], v[58:61], v[218:221], v[14:17]
	v_mfma_i32_16x16x64_i8 v[10:13], v[74:77], v[218:221], v[10:13]
	v_mfma_i32_16x16x64_i8 v[70:73], v[62:65], v[198:201], v[70:73]
	v_mfma_i32_16x16x64_i8 v[66:69], v[78:81], v[198:201], v[66:69]
	v_mfma_i32_16x16x64_i8 v[46:49], v[62:65], v[206:209], v[46:49]
	v_mfma_i32_16x16x64_i8 v[42:45], v[78:81], v[206:209], v[42:45]
	v_mfma_i32_16x16x64_i8 v[30:33], v[62:65], v[214:217], v[30:33]
	v_mfma_i32_16x16x64_i8 v[26:29], v[78:81], v[214:217], v[26:29]
	v_mfma_i32_16x16x64_i8 v[14:17], v[62:65], v[222:225], v[14:17]
	v_mfma_i32_16x16x64_i8 v[10:13], v[78:81], v[222:225], v[10:13]
	v_mfma_i32_16x16x64_i8 v[54:57], v[162:165], v[194:197], v[54:57]
	v_mfma_i32_16x16x64_i8 v[50:53], v[170:173], v[194:197], v[50:53]
	v_mfma_i32_16x16x64_i8 v[38:41], v[162:165], v[202:205], v[38:41]
	v_mfma_i32_16x16x64_i8 v[34:37], v[170:173], v[202:205], v[34:37]
	v_mfma_i32_16x16x64_i8 v[22:25], v[162:165], v[210:213], v[22:25]
	v_mfma_i32_16x16x64_i8 v[18:21], v[170:173], v[210:213], v[18:21]
	v_mfma_i32_16x16x64_i8 v[6:9], v[162:165], v[218:221], v[6:9]
	v_mfma_i32_16x16x64_i8 v[2:5], v[170:173], v[218:221], v[2:5]
	v_mfma_i32_16x16x64_i8 v[54:57], v[166:169], v[198:201], v[54:57]
	v_mfma_i32_16x16x64_i8 v[50:53], v[190:193], v[198:201], v[50:53]
	v_mfma_i32_16x16x64_i8 v[38:41], v[166:169], v[206:209], v[38:41]
	v_mfma_i32_16x16x64_i8 v[34:37], v[190:193], v[206:209], v[34:37]
	v_mfma_i32_16x16x64_i8 v[22:25], v[166:169], v[214:217], v[22:25]
	v_mfma_i32_16x16x64_i8 v[18:21], v[190:193], v[214:217], v[18:21]
	v_mfma_i32_16x16x64_i8 v[6:9], v[166:169], v[222:225], v[6:9]
	v_mfma_i32_16x16x64_i8 v[2:5], v[190:193], v[222:225], v[2:5]
	s_barrier
	s_add_i32 s40, s40, 2
	s_add_u32 s2, s2, 0x100
	s_addc_u32 s3, s3, 0
	s_add_u32 s38, s38, 0x100
	s_addc_u32 s39, s39, 0
	s_cmp_gt_u32 s40, 29
	s_cbranch_scc0 .LBB0_483
	s_and_b64 vcc, exec, s[20:21]
	s_cbranch_vccz .LBB0_486
	s_barrier

; #define PG8_STAGE(bufoff, gbase, voff) do { _Pragma("unroll") for (int _i = 0; _i < 2; ++_i) \
;         __builtin_amdgcn_global_load_lds((const unsigned*)((const char*)(gbase) + (voff)[_i]), (PG8_LAS unsigned*)(lds + (bufoff) + ldsw + _i * 8192), 16, 0, 0); } while (0)
; #define PG8_LDA(dst, b, h) do { _Pragma("unroll") for (int m = 0; m < 4; ++m) _Pragma("unroll") for (int k = 0; k < 2; ++k) dst[m][k] = *(const PG8_LAS bf16x8*)(lds + PG8_SA(b, h) + aoff + m * 2048 + k * 1024); } while (0)
; #define PG8_LDB(dst, b, h) do { _Pragma("unroll") for (int n = 0; n < 2; ++n) _Pragma("unroll") for (int k = 0; k < 2; ++k) dst[n][k] = *(const PG8_LAS bf16x8*)(lds + PG8_SB(b, h) + boff + n * 2048 + k * 1024); } while (0)
; #define PG8_MMA(ai, bj, At, Bt) do { __builtin_amdgcn_s_setprio(1); _Pragma("unroll") for (int m = 0; m < 4; ++m) _Pragma("unroll") for (int n = 0; n < 2; ++n) _Pragma("unroll") for (int k = 0; k < 2; ++k) \
;         acc[ai][bj][m][n] = mma_<I8>(Bt[n][k], At[m][k], acc[ai][bj][m][n]); __builtin_amdgcn_s_setprio(0); } while (0)
; #define PG8_WAIT_V(n) asm volatile("s_waitcnt vmcnt(" #n ")" ::: "memory")
; #define PG8_WAIT_L(n) asm volatile("s_waitcnt lgkmcnt(" #n ")" ::: "memory")
; #define PG8_BAR __builtin_amdgcn_s_barrier()
; #define PG8_SCHED __builtin_amdgcn_sched_barrier(0)
; template <class Epi, class Sched, bool ALIGN_EPI = false, bool SP2 = false, bool I8 = false>
; __device__ __forceinline__ void gemm_phase(PG8_LAS unsigned char* lds, const Gemm g, const Sched& S, const Epi& E) {
;     ...
;         for (int t = 0; t < nt; t += 2) {
;             const bool last = (t == nt - 2);
;             const char* a1 = cA + (size_t)(t + 1) * kstep;
;             const char* a2 = last ? nA : cA + (size_t)(t + 2) * kstep; const char* b2 = last ? nB : cB + (size_t)(t + 2) * kstep;
;             const char* a3 = a2 + kstep; const char* b3 = b2 + kstep;
;             if (last && has_next) S.a_ready(nxt);
;             if constexpr (SP2) {
;             PG8_LDB(B0, 0, 0); PG8_LDB(B1, 0, 1); PG8_SCHED; PG8_LDA(At, 0, 0); PG8_STAGE(PG8_SA(1, 1), a1 + hstepA, voffA);
;             PG8_WAIT_V(8); PG8_WAIT_L(0); PG8_BAR; PG8_MMA(0, 0, At, B0); PG8_MMA(0, 1, At, B1); PG8_BAR; PG8_SCHED;
;             PG8_LDA(At, 0, 1); PG8_STAGE(PG8_SB(0, 0), b2, voffB); PG8_STAGE(PG8_SB(0, 1), b2 + hstepB, voffB); PG8_STAGE(PG8_SA(0, 0), a2, voffA);
.LBB0_541:
	ds_read_b128 v[154:157], v149
	ds_read_b128 v[158:161], v149 offset:1024
	ds_read_b128 v[162:165], v149 offset:2048
	ds_read_b128 v[166:169], v149 offset:3072
	ds_read_b128 v[170:173], v151
	ds_read_b128 v[174:177], v151 offset:1024
	ds_read_b128 v[178:181], v151 offset:2048
	ds_read_b128 v[188:191], v151 offset:3072
	s_add_u32 s34, s30, 0xfff00080
	s_addc_u32 s35, s31, -1
	s_cmp_eq_u32 s94, 60
	s_cselect_b32 s37, s7, s35
	s_cselect_b32 s36, s25, s34
	s_cselect_b32 s35, s23, s93
	s_cselect_b32 s34, s29, s92
	v_lshl_add_u64 v[224:225], s[30:31], 0, v[138:139]
	s_add_i32 m0, s39, 0xc000
	ds_read_b128 v[192:195], v153
	ds_read_b128 v[196:199], v153 offset:1024
	ds_read_b128 v[200:203], v153 offset:2048
	ds_read_b128 v[204:207], v153 offset:3072
	ds_read_b128 v[208:211], v153 offset:4096
	ds_read_b128 v[212:215], v153 offset:5120
	ds_read_b128 v[216:219], v153 offset:6144
	ds_read_b128 v[220:223], v153 offset:7168
	global_load_lds_dwordx4 v[224:225], off
	v_lshl_add_u64 v[224:225], s[30:31], 0, v[140:141]
	s_add_i32 m0, s39, 0xe000
	s_nop 0
	global_load_lds_dwordx4 v[224:225], off
	s_waitcnt vmcnt(8)
	s_waitcnt lgkmcnt(0)
	s_barrier
	s_waitcnt lgkmcnt(0)
	v_mfma_f32_16x16x32_bf16 v[126:129], v[154:157], v[192:195], v[126:129]
	v_mfma_f32_16x16x32_bf16 v[122:125], v[162:165], v[192:195], v[122:125]
	v_mfma_f32_16x16x32_bf16 v[110:113], v[154:157], v[200:203], v[110:113]
	v_mfma_f32_16x16x32_bf16 v[106:109], v[162:165], v[200:203], v[106:109]
	v_mfma_f32_16x16x32_bf16 v[94:97], v[154:157], v[208:211], v[94:97]
	v_mfma_f32_16x16x32_bf16 v[90:93], v[162:165], v[208:211], v[90:93]
	v_mfma_f32_16x16x32_bf16 v[78:81], v[154:157], v[216:219], v[78:81]
	v_mfma_f32_16x16x32_bf16 v[74:77], v[162:165], v[216:219], v[74:77]
	v_mfma_f32_16x16x32_bf16 v[126:129], v[158:161], v[196:199], v[126:129]
	v_mfma_f32_16x16x32_bf16 v[122:125], v[166:169], v[196:199], v[122:125]
	v_mfma_f32_16x16x32_bf16 v[110:113], v[158:161], v[204:207], v[110:113]
	v_mfma_f32_16x16x32_bf16 v[106:109], v[166:169], v[204:207], v[106:109]
	v_mfma_f32_16x16x32_bf16 v[94:97], v[158:161], v[212:215], v[94:97]
	v_mfma_f32_16x16x32_bf16 v[90:93], v[166:169], v[212:215], v[90:93]
	v_mfma_f32_16x16x32_bf16 v[78:81], v[158:161], v[220:223], v[78:81]
	v_mfma_f32_16x16x32_bf16 v[74:77], v[166:169], v[220:223], v[74:77]
	v_mfma_f32_16x16x32_bf16 v[118:121], v[170:173], v[192:195], v[118:121]
	v_mfma_f32_16x16x32_bf16 v[114:117], v[178:181], v[192:195], v[114:117]
	v_mfma_f32_16x16x32_bf16 v[102:105], v[170:173], v[200:203], v[102:105]
	v_mfma_f32_16x16x32_bf16 v[98:101], v[178:181], v[200:203], v[98:101]
	v_mfma_f32_16x16x32_bf16 v[86:89], v[170:173], v[208:211], v[86:89]
	v_mfma_f32_16x16x32_bf16 v[82:85], v[178:181], v[208:211], v[82:85]
	v_mfma_f32_16x16x32_bf16 v[70:73], v[170:173], v[216:219], v[70:73]
	v_mfma_f32_16x16x32_bf16 v[66:69], v[178:181], v[216:219], v[66:69]
	v_mfma_f32_16x16x32_bf16 v[118:121], v[174:177], v[196:199], v[118:121]
	v_mfma_f32_16x16x32_bf16 v[114:117], v[188:191], v[196:199], v[114:117]
	v_mfma_f32_16x16x32_bf16 v[102:105], v[174:177], v[204:207], v[102:105]
	v_mfma_f32_16x16x32_bf16 v[98:101], v[188:191], v[204:207], v[98:101]
	v_mfma_f32_16x16x32_bf16 v[86:89], v[174:177], v[212:215], v[86:89]
	v_mfma_f32_16x16x32_bf16 v[82:85], v[188:191], v[212:215], v[82:85]
	v_mfma_f32_16x16x32_bf16 v[70:73], v[174:177], v[220:223], v[70:73]
	v_mfma_f32_16x16x32_bf16 v[66:69], v[188:191], v[220:223], v[66:69]
	s_barrier
	s_add_i32 s95, s88, s38
	v_lshl_add_u64 v[224:225], s[34:35], 0, v[132:133]
	s_mov_b32 m0, s95
	ds_read_b128 v[192:195], v153 offset:16384
	ds_read_b128 v[196:199], v153 offset:17408
	ds_read_b128 v[200:203], v153 offset:18432
	ds_read_b128 v[204:207], v153 offset:19456
	ds_read_b128 v[208:211], v153 offset:20480
	ds_read_b128 v[212:215], v153 offset:21504
	ds_read_b128 v[216:219], v153 offset:22528
	ds_read_b128 v[220:223], v153 offset:23552
	global_load_lds_dwordx4 v[224:225], off
	s_add_i32 m0, s95, 0x2000
	s_add_u32 vcc_lo, s34, 0x100000
	v_lshl_add_u64 v[226:227], s[34:35], 0, v[136:137]
	s_addc_u32 vcc_hi, s35, 0
	s_add_i32 s95, s89, s38
	global_load_lds_dwordx4 v[226:227], off
	v_lshl_add_u64 v[228:229], vcc, 0, v[132:133]
	s_mov_b32 m0, s95
	v_lshl_add_u64 v[230:231], s[36:37], 0, v[134:135]
	global_load_lds_dwordx4 v[228:229], off
	v_lshl_add_u64 v[228:229], vcc, 0, v[136:137]
	s_add_i32 m0, s95, 0x2000
	s_nop 0
	global_load_lds_dwordx4 v[228:229], off
	v_lshl_add_u64 v[228:229], s[36:37], 0, v[130:131]
	s_mov_b32 m0, s39
	s_nop 0
	global_load_lds_dwordx4 v[228:229], off
	s_mov_b32 m0, s40
	s_nop 0
	global_load_lds_dwordx4 v[230:231], off
	s_waitcnt vmcnt(8)
	s_waitcnt lgkmcnt(0)
	s_barrier
; #define PG8_STAGE(bufoff, gbase, voff) do { _Pragma("unroll") for (int _i = 0; _i < 2; ++_i) \
;         __builtin_amdgcn_global_load_lds((const unsigned*)((const char*)(gbase) + (voff)[_i]), (PG8_LAS unsigned*)(lds + (bufoff) + ldsw + _i * 8192), 16, 0, 0); } while (0)
; #define PG8_LDA(dst, b, h) do { _Pragma("unroll") for (int m = 0; m < 4; ++m) _Pragma("unroll") for (int k = 0; k < 2; ++k) dst[m][k] = *(const PG8_LAS bf16x8*)(lds + PG8_SA(b, h) + aoff + m * 2048 + k * 1024); } while (0)
; #define PG8_LDB(dst, b, h) do { _Pragma("unroll") for (int n = 0; n < 2; ++n) _Pragma("unroll") for (int k = 0; k < 2; ++k) dst[n][k] = *(const PG8_LAS bf16x8*)(lds + PG8_SB(b, h) + boff + n * 2048 + k * 1024); } while (0)
; #define PG8_MMA(ai, bj, At, Bt) do { __builtin_amdgcn_s_setprio(1); _Pragma("unroll") for (int m = 0; m < 4; ++m) _Pragma("unroll") for (int n = 0; n < 2; ++n) _Pragma("unroll") for (int k = 0; k < 2; ++k) \
;         acc[ai][bj][m][n] = mma_<I8>(Bt[n][k], At[m][k], acc[ai][bj][m][n]); __builtin_amdgcn_s_setprio(0); } while (0)
; #define PG8_WAIT_V(n) asm volatile("s_waitcnt vmcnt(" #n ")" ::: "memory")
; #define PG8_WAIT_L(n) asm volatile("s_waitcnt lgkmcnt(" #n ")" ::: "memory")
; #define PG8_BAR __builtin_amdgcn_s_barrier()
; #define PG8_SCHED __builtin_amdgcn_sched_barrier(0)
; template <class Epi, class Sched, bool ALIGN_EPI = false, bool SP2 = false, bool I8 = false>
; __device__ __forceinline__ void gemm_phase(PG8_LAS unsigned char* lds, const Gemm g, const Sched& S, const Epi& E) {
;     ...
;             PG8_WAIT_V(8); PG8_WAIT_L(0); PG8_BAR; PG8_MMA(1, 0, At, B0); PG8_MMA(1, 1, At, B1); PG8_BAR; PG8_SCHED;
;             PG8_LDB(B0, 1, 0); PG8_LDB(B1, 1, 1); PG8_SCHED; PG8_LDA(At, 1, 0); PG8_STAGE(PG8_SA(0, 1), a2 + hstepA, voffA);
;             PG8_WAIT_V(8); PG8_WAIT_L(0); PG8_BAR; PG8_MMA(0, 0, At, B0); PG8_MMA(0, 1, At, B1); PG8_BAR; PG8_SCHED;
	s_waitcnt lgkmcnt(0)
	v_mfma_f32_16x16x32_bf16 v[62:65], v[154:157], v[192:195], v[62:65]
	v_mfma_f32_16x16x32_bf16 v[58:61], v[162:165], v[192:195], v[58:61]
	v_mfma_f32_16x16x32_bf16 v[46:49], v[154:157], v[200:203], v[46:49]
	v_mfma_f32_16x16x32_bf16 v[42:45], v[162:165], v[200:203], v[42:45]
	v_mfma_f32_16x16x32_bf16 v[30:33], v[154:157], v[208:211], v[30:33]
	v_mfma_f32_16x16x32_bf16 v[26:29], v[162:165], v[208:211], v[26:29]
	v_mfma_f32_16x16x32_bf16 v[14:17], v[154:157], v[216:219], v[14:17]
	v_mfma_f32_16x16x32_bf16 v[10:13], v[162:165], v[216:219], v[10:13]
	v_mfma_f32_16x16x32_bf16 v[62:65], v[158:161], v[196:199], v[62:65]
	v_mfma_f32_16x16x32_bf16 v[58:61], v[166:169], v[196:199], v[58:61]
	v_mfma_f32_16x16x32_bf16 v[46:49], v[158:161], v[204:207], v[46:49]
	v_mfma_f32_16x16x32_bf16 v[42:45], v[166:169], v[204:207], v[42:45]
	v_mfma_f32_16x16x32_bf16 v[30:33], v[158:161], v[212:215], v[30:33]
	v_mfma_f32_16x16x32_bf16 v[26:29], v[166:169], v[212:215], v[26:29]
	v_mfma_f32_16x16x32_bf16 v[14:17], v[158:161], v[220:223], v[14:17]
	v_mfma_f32_16x16x32_bf16 v[10:13], v[166:169], v[220:223], v[10:13]
	v_mfma_f32_16x16x32_bf16 v[54:57], v[170:173], v[192:195], v[54:57]
	v_mfma_f32_16x16x32_bf16 v[50:53], v[178:181], v[192:195], v[50:53]
	v_mfma_f32_16x16x32_bf16 v[38:41], v[170:173], v[200:203], v[38:41]
	v_mfma_f32_16x16x32_bf16 v[34:37], v[178:181], v[200:203], v[34:37]
	v_mfma_f32_16x16x32_bf16 v[22:25], v[170:173], v[208:211], v[22:25]
	v_mfma_f32_16x16x32_bf16 v[18:21], v[178:181], v[208:211], v[18:21]
	v_mfma_f32_16x16x32_bf16 v[6:9], v[170:173], v[216:219], v[6:9]
	v_mfma_f32_16x16x32_bf16 v[2:5], v[178:181], v[216:219], v[2:5]
	v_mfma_f32_16x16x32_bf16 v[54:57], v[174:177], v[196:199], v[54:57]
	v_mfma_f32_16x16x32_bf16 v[50:53], v[188:191], v[196:199], v[50:53]
	v_mfma_f32_16x16x32_bf16 v[38:41], v[174:177], v[204:207], v[38:41]
	v_mfma_f32_16x16x32_bf16 v[34:37], v[188:191], v[204:207], v[34:37]
	v_mfma_f32_16x16x32_bf16 v[22:25], v[174:177], v[212:215], v[22:25]
	v_mfma_f32_16x16x32_bf16 v[18:21], v[188:191], v[212:215], v[18:21]
	v_mfma_f32_16x16x32_bf16 v[6:9], v[174:177], v[220:223], v[6:9]
	v_mfma_f32_16x16x32_bf16 v[2:5], v[188:191], v[220:223], v[2:5]
	s_barrier
	s_add_i32 s95, 0, 0x18000
	s_add_i32 vcc_lo, 0, 0x1c000
	v_add_u32_e32 v166, s95, v147
	v_add_u32_e32 v187, vcc_lo, v147
	ds_read_b128 v[154:157], v166
	ds_read_b128 v[158:161], v166 offset:1024
	ds_read_b128 v[162:165], v166 offset:2048
	ds_read_b128 v[166:169], v166 offset:3072
	ds_read_b128 v[170:173], v187
	ds_read_b128 v[174:177], v187 offset:1024
	ds_read_b128 v[178:181], v187 offset:2048
	ds_read_b128 v[188:191], v187 offset:3072
	s_add_u32 s36, s36, 0x100000
	s_addc_u32 s37, s37, 0
	s_mov_b32 m0, s41
	v_lshl_add_u64 v[234:235], s[36:37], 0, v[130:131]
	ds_read_b128 v[192:195], v153 offset:32768
	ds_read_b128 v[196:199], v153 offset:33792
	ds_read_b128 v[200:203], v153 offset:34816
	ds_read_b128 v[204:207], v153 offset:35840
	ds_read_b128 v[208:211], v153 offset:36864
	ds_read_b128 v[212:215], v153 offset:37888
	ds_read_b128 v[216:219], v153 offset:38912
	ds_read_b128 v[220:223], v153 offset:39936
	global_load_lds_dwordx4 v[234:235], off
	v_lshl_add_u64 v[234:235], s[36:37], 0, v[134:135]
	s_mov_b32 m0, s46
	s_nop 0
	global_load_lds_dwordx4 v[234:235], off
	s_waitcnt vmcnt(8)
	s_waitcnt lgkmcnt(0)
	s_barrier
	s_waitcnt lgkmcnt(0)
	v_mfma_f32_16x16x32_bf16 v[126:129], v[154:157], v[192:195], v[126:129]
	v_mfma_f32_16x16x32_bf16 v[122:125], v[162:165], v[192:195], v[122:125]
	v_mfma_f32_16x16x32_bf16 v[110:113], v[154:157], v[200:203], v[110:113]
	v_mfma_f32_16x16x32_bf16 v[106:109], v[162:165], v[200:203], v[106:109]
	v_mfma_f32_16x16x32_bf16 v[94:97], v[154:157], v[208:211], v[94:97]
	v_mfma_f32_16x16x32_bf16 v[90:93], v[162:165], v[208:211], v[90:93]
	v_mfma_f32_16x16x32_bf16 v[78:81], v[154:157], v[216:219], v[78:81]
	v_mfma_f32_16x16x32_bf16 v[74:77], v[162:165], v[216:219], v[74:77]
	v_mfma_f32_16x16x32_bf16 v[126:129], v[158:161], v[196:199], v[126:129]
	v_mfma_f32_16x16x32_bf16 v[122:125], v[166:169], v[196:199], v[122:125]
	v_mfma_f32_16x16x32_bf16 v[110:113], v[158:161], v[204:207], v[110:113]
	v_mfma_f32_16x16x32_bf16 v[106:109], v[166:169], v[204:207], v[106:109]
	v_mfma_f32_16x16x32_bf16 v[94:97], v[158:161], v[212:215], v[94:97]
	v_mfma_f32_16x16x32_bf16 v[90:93], v[166:169], v[212:215], v[90:93]
	v_mfma_f32_16x16x32_bf16 v[78:81], v[158:161], v[220:223], v[78:81]
	v_mfma_f32_16x16x32_bf16 v[74:77], v[166:169], v[220:223], v[74:77]
	v_mfma_f32_16x16x32_bf16 v[118:121], v[170:173], v[192:195], v[118:121]
	v_mfma_f32_16x16x32_bf16 v[114:117], v[178:181], v[192:195], v[114:117]
	v_mfma_f32_16x16x32_bf16 v[102:105], v[170:173], v[200:203], v[102:105]
	v_mfma_f32_16x16x32_bf16 v[98:101], v[178:181], v[200:203], v[98:101]
	v_mfma_f32_16x16x32_bf16 v[86:89], v[170:173], v[208:211], v[86:89]
	v_mfma_f32_16x16x32_bf16 v[82:85], v[178:181], v[208:211], v[82:85]
	v_mfma_f32_16x16x32_bf16 v[70:73], v[170:173], v[216:219], v[70:73]
	v_mfma_f32_16x16x32_bf16 v[66:69], v[178:181], v[216:219], v[66:69]
	v_mfma_f32_16x16x32_bf16 v[118:121], v[174:177], v[196:199], v[118:121]
	v_mfma_f32_16x16x32_bf16 v[114:117], v[188:191], v[196:199], v[114:117]
	v_mfma_f32_16x16x32_bf16 v[102:105], v[174:177], v[204:207], v[102:105]
	v_mfma_f32_16x16x32_bf16 v[98:101], v[188:191], v[204:207], v[98:101]
	v_mfma_f32_16x16x32_bf16 v[86:89], v[174:177], v[212:215], v[86:89]
	v_mfma_f32_16x16x32_bf16 v[82:85], v[188:191], v[212:215], v[82:85]
	v_mfma_f32_16x16x32_bf16 v[70:73], v[174:177], v[220:223], v[70:73]
	v_mfma_f32_16x16x32_bf16 v[66:69], v[188:191], v[220:223], v[66:69]
	s_barrier
; #define PG8_STAGE(bufoff, gbase, voff) do { _Pragma("unroll") for (int _i = 0; _i < 2; ++_i) \
;         __builtin_amdgcn_global_load_lds((const unsigned*)((const char*)(gbase) + (voff)[_i]), (PG8_LAS unsigned*)(lds + (bufoff) + ldsw + _i * 8192), 16, 0, 0); } while (0)
; #define PG8_LDA(dst, b, h) do { _Pragma("unroll") for (int m = 0; m < 4; ++m) _Pragma("unroll") for (int k = 0; k < 2; ++k) dst[m][k] = *(const PG8_LAS bf16x8*)(lds + PG8_SA(b, h) + aoff + m * 2048 + k * 1024); } while (0)
; #define PG8_MMA(ai, bj, At, Bt) do { __builtin_amdgcn_s_setprio(1); _Pragma("unroll") for (int m = 0; m < 4; ++m) _Pragma("unroll") for (int n = 0; n < 2; ++n) _Pragma("unroll") for (int k = 0; k < 2; ++k) \
;         acc[ai][bj][m][n] = mma_<I8>(Bt[n][k], At[m][k], acc[ai][bj][m][n]); __builtin_amdgcn_s_setprio(0); } while (0)
; #define PG8_WAIT_V(n) asm volatile("s_waitcnt vmcnt(" #n ")" ::: "memory")
; #define PG8_WAIT_L(n) asm volatile("s_waitcnt lgkmcnt(" #n ")" ::: "memory")
; #define PG8_BAR __builtin_amdgcn_s_barrier()
; #define PG8_SCHED __builtin_amdgcn_sched_barrier(0)
; template <class Epi, class Sched, bool ALIGN_EPI = false, bool SP2 = false, bool I8 = false>
; __device__ __forceinline__ void gemm_phase(PG8_LAS unsigned char* lds, const Gemm g, const Sched& S, const Epi& E) {
;     ...
;         for (int t = 0; t < nt; t += 2) {
;             const bool last = (t == nt - 2);
;             const char* a1 = cA + (size_t)(t + 1) * kstep;
;             const char* a2 = last ? nA : cA + (size_t)(t + 2) * kstep; const char* b2 = last ? nB : cB + (size_t)(t + 2) * kstep;
;     ...
;             PG8_LDA(At, 1, 1); PG8_STAGE(PG8_SB(1, 0), b3, voffB); PG8_STAGE(PG8_SB(1, 1), b3 + hstepB, voffB); PG8_STAGE(PG8_SA(1, 0), a3, voffA);
;             PG8_WAIT_V(8); PG8_WAIT_L(0); PG8_BAR; PG8_MMA(1, 0, At, B0); PG8_MMA(1, 1, At, B1); PG8_BAR; PG8_SCHED;
	s_add_i32 s36, s95, s38
	v_lshl_add_u64 v[224:225], v[224:225], 0, s[18:19]
	s_mov_b32 m0, s36
	ds_read_b128 v[192:195], v153 offset:49152
	ds_read_b128 v[196:199], v153 offset:50176
	ds_read_b128 v[200:203], v153 offset:51200
	ds_read_b128 v[204:207], v153 offset:52224
	ds_read_b128 v[208:211], v153 offset:53248
	ds_read_b128 v[212:215], v153 offset:54272
	ds_read_b128 v[216:219], v153 offset:55296
	ds_read_b128 v[220:223], v153 offset:56320
	global_load_lds_dwordx4 v[224:225], off
	s_add_i32 m0, s36, 0x2000
	s_add_u32 s34, s34, 0x100080
	v_lshl_add_u64 v[224:225], v[226:227], 0, s[18:19]
	s_addc_u32 s35, s35, 0
	s_add_i32 s36, vcc_lo, s38
	global_load_lds_dwordx4 v[224:225], off
	v_lshl_add_u64 v[224:225], s[34:35], 0, v[132:133]
	s_mov_b32 m0, s36
	s_nop 0
	global_load_lds_dwordx4 v[224:225], off
	v_lshl_add_u64 v[224:225], s[34:35], 0, v[136:137]
	s_add_i32 m0, s36, 0x2000
	s_nop 0
	global_load_lds_dwordx4 v[224:225], off
	v_lshl_add_u64 v[224:225], v[228:229], 0, s[18:19]
	s_mov_b32 m0, s68
	s_nop 0
	global_load_lds_dwordx4 v[224:225], off
	v_lshl_add_u64 v[224:225], v[230:231], 0, s[18:19]
	s_mov_b32 m0, s69
	s_nop 0
	global_load_lds_dwordx4 v[224:225], off
	s_waitcnt vmcnt(8)
	s_waitcnt lgkmcnt(0)
	s_barrier
	s_waitcnt lgkmcnt(0)
	v_mfma_f32_16x16x32_bf16 v[62:65], v[154:157], v[192:195], v[62:65]
	v_mfma_f32_16x16x32_bf16 v[58:61], v[162:165], v[192:195], v[58:61]
	v_mfma_f32_16x16x32_bf16 v[46:49], v[154:157], v[200:203], v[46:49]
	v_mfma_f32_16x16x32_bf16 v[42:45], v[162:165], v[200:203], v[42:45]
	v_mfma_f32_16x16x32_bf16 v[30:33], v[154:157], v[208:211], v[30:33]
	v_mfma_f32_16x16x32_bf16 v[26:29], v[162:165], v[208:211], v[26:29]
	v_mfma_f32_16x16x32_bf16 v[14:17], v[154:157], v[216:219], v[14:17]
	v_mfma_f32_16x16x32_bf16 v[10:13], v[162:165], v[216:219], v[10:13]
	v_mfma_f32_16x16x32_bf16 v[62:65], v[158:161], v[196:199], v[62:65]
	v_mfma_f32_16x16x32_bf16 v[58:61], v[166:169], v[196:199], v[58:61]
	v_mfma_f32_16x16x32_bf16 v[46:49], v[158:161], v[204:207], v[46:49]
	v_mfma_f32_16x16x32_bf16 v[42:45], v[166:169], v[204:207], v[42:45]
	v_mfma_f32_16x16x32_bf16 v[30:33], v[158:161], v[212:215], v[30:33]
	v_mfma_f32_16x16x32_bf16 v[26:29], v[166:169], v[212:215], v[26:29]
	v_mfma_f32_16x16x32_bf16 v[14:17], v[158:161], v[220:223], v[14:17]
	v_mfma_f32_16x16x32_bf16 v[10:13], v[166:169], v[220:223], v[10:13]
	v_mfma_f32_16x16x32_bf16 v[54:57], v[170:173], v[192:195], v[54:57]
	v_mfma_f32_16x16x32_bf16 v[50:53], v[178:181], v[192:195], v[50:53]
	v_mfma_f32_16x16x32_bf16 v[38:41], v[170:173], v[200:203], v[38:41]
	v_mfma_f32_16x16x32_bf16 v[34:37], v[178:181], v[200:203], v[34:37]
	v_mfma_f32_16x16x32_bf16 v[22:25], v[170:173], v[208:211], v[22:25]
	v_mfma_f32_16x16x32_bf16 v[18:21], v[178:181], v[208:211], v[18:21]
	v_mfma_f32_16x16x32_bf16 v[6:9], v[170:173], v[216:219], v[6:9]
	v_mfma_f32_16x16x32_bf16 v[2:5], v[178:181], v[216:219], v[2:5]
	v_mfma_f32_16x16x32_bf16 v[54:57], v[174:177], v[196:199], v[54:57]
	v_mfma_f32_16x16x32_bf16 v[50:53], v[188:191], v[196:199], v[50:53]
	v_mfma_f32_16x16x32_bf16 v[38:41], v[174:177], v[204:207], v[38:41]
	v_mfma_f32_16x16x32_bf16 v[34:37], v[188:191], v[204:207], v[34:37]
	v_mfma_f32_16x16x32_bf16 v[22:25], v[174:177], v[212:215], v[22:25]
	v_mfma_f32_16x16x32_bf16 v[18:21], v[188:191], v[212:215], v[18:21]
	v_mfma_f32_16x16x32_bf16 v[6:9], v[174:177], v[220:223], v[6:9]
	v_mfma_f32_16x16x32_bf16 v[2:5], v[188:191], v[220:223], v[2:5]
	s_barrier
	s_add_i32 s94, s94, 2
	s_add_u32 s30, s30, 0x100
	s_addc_u32 s31, s31, 0
	s_add_u32 s92, s92, 0x100
	s_addc_u32 s93, s93, 0
	s_cmp_gt_u32 s94, 61
	s_cbranch_scc0 .LBB0_541
	s_and_b64 vcc, exec, s[20:21]
	s_cbranch_vccz .LBB0_544
	s_barrier

; #define PG8_STAGE(bufoff, gbase, voff) do { _Pragma("unroll") for (int _i = 0; _i < 2; ++_i) \
;         __builtin_amdgcn_global_load_lds((const unsigned*)((const char*)(gbase) + (voff)[_i]), (PG8_LAS unsigned*)(lds + (bufoff) + ldsw + _i * 8192), 16, 0, 0); } while (0)
; #define PG8_LDA(dst, b, h) do { _Pragma("unroll") for (int m = 0; m < 4; ++m) _Pragma("unroll") for (int k = 0; k < 2; ++k) dst[m][k] = *(const PG8_LAS bf16x8*)(lds + PG8_SA(b, h) + aoff + m * 2048 + k * 1024); } while (0)
; #define PG8_LDB(dst, b, h) do { _Pragma("unroll") for (int n = 0; n < 2; ++n) _Pragma("unroll") for (int k = 0; k < 2; ++k) dst[n][k] = *(const PG8_LAS bf16x8*)(lds + PG8_SB(b, h) + boff + n * 2048 + k * 1024); } while (0)
; #define PG8_MMA(ai, bj, At, Bt) do { __builtin_amdgcn_s_setprio(1); _Pragma("unroll") for (int m = 0; m < 4; ++m) _Pragma("unroll") for (int n = 0; n < 2; ++n) _Pragma("unroll") for (int k = 0; k < 2; ++k) \
;         acc[ai][bj][m][n] = mma_<I8>(Bt[n][k], At[m][k], acc[ai][bj][m][n]); __builtin_amdgcn_s_setprio(0); } while (0)
; #define PG8_WAIT_V(n) asm volatile("s_waitcnt vmcnt(" #n ")" ::: "memory")
; #define PG8_WAIT_L(n) asm volatile("s_waitcnt lgkmcnt(" #n ")" ::: "memory")
; #define PG8_BAR __builtin_amdgcn_s_barrier()
; #define PG8_SCHED __builtin_amdgcn_sched_barrier(0)
; template <class Epi, class Sched, bool ALIGN_EPI = false, bool SP2 = false, bool I8 = false>
; __device__ __forceinline__ void gemm_phase(PG8_LAS unsigned char* lds, const Gemm g, const Sched& S, const Epi& E) {
;     ...
;         for (int t = 0; t < nt; t += 2) {
;             const bool last = (t == nt - 2);
;             const char* a1 = cA + (size_t)(t + 1) * kstep;
;             const char* a2 = last ? nA : cA + (size_t)(t + 2) * kstep; const char* b2 = last ? nB : cB + (size_t)(t + 2) * kstep;
;             const char* a3 = a2 + kstep; const char* b3 = b2 + kstep;
;             if (last && has_next) S.a_ready(nxt);
;             if constexpr (SP2) {
;             PG8_LDB(B0, 0, 0); PG8_LDB(B1, 0, 1); PG8_SCHED; PG8_LDA(At, 0, 0); PG8_STAGE(PG8_SA(1, 1), a1 + hstepA, voffA);
;             PG8_WAIT_V(8); PG8_WAIT_L(0); PG8_BAR; PG8_MMA(0, 0, At, B0); PG8_MMA(0, 1, At, B1); PG8_BAR; PG8_SCHED;
;             PG8_LDA(At, 0, 1); PG8_STAGE(PG8_SB(0, 0), b2, voffB); PG8_STAGE(PG8_SB(0, 1), b2 + hstepB, voffB); PG8_STAGE(PG8_SA(0, 0), a2, voffA);
.LBB0_607:
	ds_read_b128 v[58:61], v177
	ds_read_b128 v[62:65], v177 offset:1024
	ds_read_b128 v[74:77], v177 offset:2048
	ds_read_b128 v[78:81], v177 offset:3072
	ds_read_b128 v[162:165], v178
	ds_read_b128 v[166:169], v178 offset:1024
	ds_read_b128 v[170:173], v178 offset:2048
	ds_read_b128 v[180:183], v178 offset:3072
	s_add_u32 s34, s2, 0xfff80080
	s_addc_u32 s35, s3, -1
	s_cmp_eq_u32 s39, 28
	s_cselect_b32 s37, s7, s35
	s_cselect_b32 s36, s9, s34
	s_cselect_b32 s35, s23, s38
	s_cselect_b32 s34, s25, s31
	v_lshl_add_u64 v[174:175], s[2:3], 0, v[154:155]
	s_add_i32 m0, s69, 0xc000
	ds_read_b128 v[184:187], v179
	ds_read_b128 v[188:191], v179 offset:1024
	ds_read_b128 v[192:195], v179 offset:2048
	ds_read_b128 v[196:199], v179 offset:3072
	ds_read_b128 v[200:203], v179 offset:4096
	ds_read_b128 v[204:207], v179 offset:5120
	ds_read_b128 v[208:211], v179 offset:6144
	ds_read_b128 v[212:215], v179 offset:7168
	global_load_lds_dwordx4 v[174:175], off
	v_lshl_add_u64 v[174:175], s[2:3], 0, v[156:157]
	s_add_i32 m0, s69, 0xe000
	s_nop 0
	global_load_lds_dwordx4 v[174:175], off
	s_waitcnt vmcnt(8)
	s_waitcnt lgkmcnt(0)
	s_barrier
	s_waitcnt lgkmcnt(0)
	v_mfma_i32_16x16x64_i8 v[142:145], v[58:61], v[184:187], v[142:145]
	v_mfma_i32_16x16x64_i8 v[138:141], v[74:77], v[184:187], v[138:141]
	v_mfma_i32_16x16x64_i8 v[126:129], v[58:61], v[192:195], v[126:129]
	v_mfma_i32_16x16x64_i8 v[122:125], v[74:77], v[192:195], v[122:125]
	v_mfma_i32_16x16x64_i8 v[110:113], v[58:61], v[200:203], v[110:113]
	v_mfma_i32_16x16x64_i8 v[106:109], v[74:77], v[200:203], v[106:109]
	v_mfma_i32_16x16x64_i8 v[94:97], v[58:61], v[208:211], v[94:97]
	v_mfma_i32_16x16x64_i8 v[90:93], v[74:77], v[208:211], v[90:93]
	v_mfma_i32_16x16x64_i8 v[142:145], v[62:65], v[188:191], v[142:145]
	v_mfma_i32_16x16x64_i8 v[138:141], v[78:81], v[188:191], v[138:141]
	v_mfma_i32_16x16x64_i8 v[126:129], v[62:65], v[196:199], v[126:129]
	v_mfma_i32_16x16x64_i8 v[122:125], v[78:81], v[196:199], v[122:125]
	v_mfma_i32_16x16x64_i8 v[110:113], v[62:65], v[204:207], v[110:113]
	v_mfma_i32_16x16x64_i8 v[106:109], v[78:81], v[204:207], v[106:109]
	v_mfma_i32_16x16x64_i8 v[94:97], v[62:65], v[212:215], v[94:97]
	v_mfma_i32_16x16x64_i8 v[90:93], v[78:81], v[212:215], v[90:93]
	v_mfma_i32_16x16x64_i8 v[134:137], v[162:165], v[184:187], v[134:137]
	v_mfma_i32_16x16x64_i8 v[130:133], v[170:173], v[184:187], v[130:133]
	v_mfma_i32_16x16x64_i8 v[118:121], v[162:165], v[192:195], v[118:121]
	v_mfma_i32_16x16x64_i8 v[114:117], v[170:173], v[192:195], v[114:117]
	v_mfma_i32_16x16x64_i8 v[102:105], v[162:165], v[200:203], v[102:105]
	v_mfma_i32_16x16x64_i8 v[98:101], v[170:173], v[200:203], v[98:101]
	v_mfma_i32_16x16x64_i8 v[86:89], v[162:165], v[208:211], v[86:89]
	v_mfma_i32_16x16x64_i8 v[82:85], v[170:173], v[208:211], v[82:85]
	v_mfma_i32_16x16x64_i8 v[134:137], v[166:169], v[188:191], v[134:137]
	v_mfma_i32_16x16x64_i8 v[130:133], v[180:183], v[188:191], v[130:133]
	v_mfma_i32_16x16x64_i8 v[118:121], v[166:169], v[196:199], v[118:121]
	v_mfma_i32_16x16x64_i8 v[114:117], v[180:183], v[196:199], v[114:117]
	v_mfma_i32_16x16x64_i8 v[102:105], v[166:169], v[204:207], v[102:105]
	v_mfma_i32_16x16x64_i8 v[98:101], v[180:183], v[204:207], v[98:101]
	v_mfma_i32_16x16x64_i8 v[86:89], v[166:169], v[212:215], v[86:89]
	v_mfma_i32_16x16x64_i8 v[82:85], v[180:183], v[212:215], v[82:85]
	s_barrier
	s_add_i32 s40, s33, s68
	v_lshl_add_u64 v[174:175], s[34:35], 0, v[148:149]
	s_mov_b32 m0, s40
	ds_read_b128 v[184:187], v179 offset:16384
	ds_read_b128 v[188:191], v179 offset:17408
	ds_read_b128 v[192:195], v179 offset:18432
	ds_read_b128 v[196:199], v179 offset:19456
	ds_read_b128 v[200:203], v179 offset:20480
	ds_read_b128 v[204:207], v179 offset:21504
	ds_read_b128 v[208:211], v179 offset:22528
	ds_read_b128 v[212:215], v179 offset:23552
	global_load_lds_dwordx4 v[174:175], off
	s_add_i32 m0, s40, 0x2000
	s_add_u32 s40, s34, 0x80000
	v_lshl_add_u64 v[216:217], s[34:35], 0, v[152:153]
	s_addc_u32 s41, s35, 0
	s_add_i32 vcc_lo, s8, s68
	global_load_lds_dwordx4 v[216:217], off
	v_lshl_add_u64 v[218:219], s[40:41], 0, v[148:149]
	s_mov_b32 m0, vcc_lo
	v_lshl_add_u64 v[220:221], s[36:37], 0, v[150:151]
	global_load_lds_dwordx4 v[218:219], off
	v_lshl_add_u64 v[218:219], s[40:41], 0, v[152:153]
	s_add_i32 m0, vcc_lo, 0x2000
	s_nop 0
	global_load_lds_dwordx4 v[218:219], off
	v_lshl_add_u64 v[218:219], s[36:37], 0, v[146:147]
	s_mov_b32 m0, s69
	s_nop 0
	global_load_lds_dwordx4 v[218:219], off
	s_mov_b32 m0, s70
	s_nop 0
	global_load_lds_dwordx4 v[220:221], off
	s_waitcnt vmcnt(8)
	s_waitcnt lgkmcnt(0)
	s_barrier
; #define PG8_STAGE(bufoff, gbase, voff) do { _Pragma("unroll") for (int _i = 0; _i < 2; ++_i) \
;         __builtin_amdgcn_global_load_lds((const unsigned*)((const char*)(gbase) + (voff)[_i]), (PG8_LAS unsigned*)(lds + (bufoff) + ldsw + _i * 8192), 16, 0, 0); } while (0)
; #define PG8_LDA(dst, b, h) do { _Pragma("unroll") for (int m = 0; m < 4; ++m) _Pragma("unroll") for (int k = 0; k < 2; ++k) dst[m][k] = *(const PG8_LAS bf16x8*)(lds + PG8_SA(b, h) + aoff + m * 2048 + k * 1024); } while (0)
; #define PG8_LDB(dst, b, h) do { _Pragma("unroll") for (int n = 0; n < 2; ++n) _Pragma("unroll") for (int k = 0; k < 2; ++k) dst[n][k] = *(const PG8_LAS bf16x8*)(lds + PG8_SB(b, h) + boff + n * 2048 + k * 1024); } while (0)
; #define PG8_MMA(ai, bj, At, Bt) do { __builtin_amdgcn_s_setprio(1); _Pragma("unroll") for (int m = 0; m < 4; ++m) _Pragma("unroll") for (int n = 0; n < 2; ++n) _Pragma("unroll") for (int k = 0; k < 2; ++k) \
;         acc[ai][bj][m][n] = mma_<I8>(Bt[n][k], At[m][k], acc[ai][bj][m][n]); __builtin_amdgcn_s_setprio(0); } while (0)
; #define PG8_WAIT_V(n) asm volatile("s_waitcnt vmcnt(" #n ")" ::: "memory")
; #define PG8_WAIT_L(n) asm volatile("s_waitcnt lgkmcnt(" #n ")" ::: "memory")
; #define PG8_BAR __builtin_amdgcn_s_barrier()
; #define PG8_SCHED __builtin_amdgcn_sched_barrier(0)
; template <class Epi, class Sched, bool ALIGN_EPI = false, bool SP2 = false, bool I8 = false>
; __device__ __forceinline__ void gemm_phase(PG8_LAS unsigned char* lds, const Gemm g, const Sched& S, const Epi& E) {
;     ...
;             PG8_WAIT_V(8); PG8_WAIT_L(0); PG8_BAR; PG8_MMA(1, 0, At, B0); PG8_MMA(1, 1, At, B1); PG8_BAR; PG8_SCHED;
;             PG8_LDB(B0, 1, 0); PG8_LDB(B1, 1, 1); PG8_SCHED; PG8_LDA(At, 1, 0); PG8_STAGE(PG8_SA(0, 1), a2 + hstepA, voffA);
;             PG8_WAIT_V(8); PG8_WAIT_L(0); PG8_BAR; PG8_MMA(0, 0, At, B0); PG8_MMA(0, 1, At, B1); PG8_BAR; PG8_SCHED;
	s_waitcnt lgkmcnt(0)
	v_mfma_i32_16x16x64_i8 v[70:73], v[58:61], v[184:187], v[70:73]
	v_mfma_i32_16x16x64_i8 v[66:69], v[74:77], v[184:187], v[66:69]
	v_mfma_i32_16x16x64_i8 v[46:49], v[58:61], v[192:195], v[46:49]
	v_mfma_i32_16x16x64_i8 v[42:45], v[74:77], v[192:195], v[42:45]
	v_mfma_i32_16x16x64_i8 v[30:33], v[58:61], v[200:203], v[30:33]
	v_mfma_i32_16x16x64_i8 v[26:29], v[74:77], v[200:203], v[26:29]
	v_mfma_i32_16x16x64_i8 v[14:17], v[58:61], v[208:211], v[14:17]
	v_mfma_i32_16x16x64_i8 v[10:13], v[74:77], v[208:211], v[10:13]
	v_mfma_i32_16x16x64_i8 v[70:73], v[62:65], v[188:191], v[70:73]
	v_mfma_i32_16x16x64_i8 v[66:69], v[78:81], v[188:191], v[66:69]
	v_mfma_i32_16x16x64_i8 v[46:49], v[62:65], v[196:199], v[46:49]
	v_mfma_i32_16x16x64_i8 v[42:45], v[78:81], v[196:199], v[42:45]
	v_mfma_i32_16x16x64_i8 v[30:33], v[62:65], v[204:207], v[30:33]
	v_mfma_i32_16x16x64_i8 v[26:29], v[78:81], v[204:207], v[26:29]
	v_mfma_i32_16x16x64_i8 v[14:17], v[62:65], v[212:215], v[14:17]
	v_mfma_i32_16x16x64_i8 v[10:13], v[78:81], v[212:215], v[10:13]
	v_mfma_i32_16x16x64_i8 v[54:57], v[162:165], v[184:187], v[54:57]
	v_mfma_i32_16x16x64_i8 v[50:53], v[170:173], v[184:187], v[50:53]
	v_mfma_i32_16x16x64_i8 v[38:41], v[162:165], v[192:195], v[38:41]
	v_mfma_i32_16x16x64_i8 v[34:37], v[170:173], v[192:195], v[34:37]
	v_mfma_i32_16x16x64_i8 v[22:25], v[162:165], v[200:203], v[22:25]
	v_mfma_i32_16x16x64_i8 v[18:21], v[170:173], v[200:203], v[18:21]
	v_mfma_i32_16x16x64_i8 v[6:9], v[162:165], v[208:211], v[6:9]
	v_mfma_i32_16x16x64_i8 v[2:5], v[170:173], v[208:211], v[2:5]
	v_mfma_i32_16x16x64_i8 v[54:57], v[166:169], v[188:191], v[54:57]
	v_mfma_i32_16x16x64_i8 v[50:53], v[180:183], v[188:191], v[50:53]
	v_mfma_i32_16x16x64_i8 v[38:41], v[166:169], v[196:199], v[38:41]
	v_mfma_i32_16x16x64_i8 v[34:37], v[180:183], v[196:199], v[34:37]
	v_mfma_i32_16x16x64_i8 v[22:25], v[166:169], v[204:207], v[22:25]
	v_mfma_i32_16x16x64_i8 v[18:21], v[180:183], v[204:207], v[18:21]
	v_mfma_i32_16x16x64_i8 v[6:9], v[166:169], v[212:215], v[6:9]
	v_mfma_i32_16x16x64_i8 v[2:5], v[180:183], v[212:215], v[2:5]
	s_barrier
	s_add_i32 s40, 0, 0x18000
	s_add_i32 s41, 0, 0x1c000
	v_add_u32_e32 v78, s40, v176
	v_add_u32_e32 v180, s41, v176
	ds_read_b128 v[58:61], v78
	ds_read_b128 v[62:65], v78 offset:1024
	ds_read_b128 v[74:77], v78 offset:2048
	ds_read_b128 v[78:81], v78 offset:3072
	ds_read_b128 v[162:165], v180
	ds_read_b128 v[166:169], v180 offset:1024
	ds_read_b128 v[170:173], v180 offset:2048
	ds_read_b128 v[180:183], v180 offset:3072
	s_add_u32 s36, s36, 0x80000
	s_addc_u32 s37, s37, 0
	s_mov_b32 m0, s71
	v_lshl_add_u64 v[222:223], s[36:37], 0, v[146:147]
	ds_read_b128 v[184:187], v179 offset:32768
	ds_read_b128 v[188:191], v179 offset:33792
	ds_read_b128 v[192:195], v179 offset:34816
	ds_read_b128 v[196:199], v179 offset:35840
	ds_read_b128 v[200:203], v179 offset:36864
	ds_read_b128 v[204:207], v179 offset:37888
	ds_read_b128 v[208:211], v179 offset:38912
	ds_read_b128 v[212:215], v179 offset:39936
	global_load_lds_dwordx4 v[222:223], off
	v_lshl_add_u64 v[222:223], s[36:37], 0, v[150:151]
	s_mov_b32 m0, s88
	s_nop 0
	global_load_lds_dwordx4 v[222:223], off
	s_waitcnt vmcnt(8)
	s_waitcnt lgkmcnt(0)
	s_barrier
	s_waitcnt lgkmcnt(0)
	v_mfma_i32_16x16x64_i8 v[142:145], v[58:61], v[184:187], v[142:145]
	v_mfma_i32_16x16x64_i8 v[138:141], v[74:77], v[184:187], v[138:141]
	v_mfma_i32_16x16x64_i8 v[126:129], v[58:61], v[192:195], v[126:129]
	v_mfma_i32_16x16x64_i8 v[122:125], v[74:77], v[192:195], v[122:125]
	v_mfma_i32_16x16x64_i8 v[110:113], v[58:61], v[200:203], v[110:113]
	v_mfma_i32_16x16x64_i8 v[106:109], v[74:77], v[200:203], v[106:109]
	v_mfma_i32_16x16x64_i8 v[94:97], v[58:61], v[208:211], v[94:97]
	v_mfma_i32_16x16x64_i8 v[90:93], v[74:77], v[208:211], v[90:93]
	v_mfma_i32_16x16x64_i8 v[142:145], v[62:65], v[188:191], v[142:145]
	v_mfma_i32_16x16x64_i8 v[138:141], v[78:81], v[188:191], v[138:141]
	v_mfma_i32_16x16x64_i8 v[126:129], v[62:65], v[196:199], v[126:129]
	v_mfma_i32_16x16x64_i8 v[122:125], v[78:81], v[196:199], v[122:125]
	v_mfma_i32_16x16x64_i8 v[110:113], v[62:65], v[204:207], v[110:113]
	v_mfma_i32_16x16x64_i8 v[106:109], v[78:81], v[204:207], v[106:109]
	v_mfma_i32_16x16x64_i8 v[94:97], v[62:65], v[212:215], v[94:97]
	v_mfma_i32_16x16x64_i8 v[90:93], v[78:81], v[212:215], v[90:93]
	v_mfma_i32_16x16x64_i8 v[134:137], v[162:165], v[184:187], v[134:137]
	v_mfma_i32_16x16x64_i8 v[130:133], v[170:173], v[184:187], v[130:133]
	v_mfma_i32_16x16x64_i8 v[118:121], v[162:165], v[192:195], v[118:121]
	v_mfma_i32_16x16x64_i8 v[114:117], v[170:173], v[192:195], v[114:117]
	v_mfma_i32_16x16x64_i8 v[102:105], v[162:165], v[200:203], v[102:105]
	v_mfma_i32_16x16x64_i8 v[98:101], v[170:173], v[200:203], v[98:101]
	v_mfma_i32_16x16x64_i8 v[86:89], v[162:165], v[208:211], v[86:89]
	v_mfma_i32_16x16x64_i8 v[82:85], v[170:173], v[208:211], v[82:85]
	v_mfma_i32_16x16x64_i8 v[134:137], v[166:169], v[188:191], v[134:137]
	v_mfma_i32_16x16x64_i8 v[130:133], v[180:183], v[188:191], v[130:133]
	v_mfma_i32_16x16x64_i8 v[118:121], v[166:169], v[196:199], v[118:121]
	v_mfma_i32_16x16x64_i8 v[114:117], v[180:183], v[196:199], v[114:117]
	v_mfma_i32_16x16x64_i8 v[102:105], v[166:169], v[204:207], v[102:105]
	v_mfma_i32_16x16x64_i8 v[98:101], v[180:183], v[204:207], v[98:101]
	v_mfma_i32_16x16x64_i8 v[86:89], v[166:169], v[212:215], v[86:89]
	v_mfma_i32_16x16x64_i8 v[82:85], v[180:183], v[212:215], v[82:85]
	s_barrier
; #define PG8_STAGE(bufoff, gbase, voff) do { _Pragma("unroll") for (int _i = 0; _i < 2; ++_i) \
;         __builtin_amdgcn_global_load_lds((const unsigned*)((const char*)(gbase) + (voff)[_i]), (PG8_LAS unsigned*)(lds + (bufoff) + ldsw + _i * 8192), 16, 0, 0); } while (0)
; #define PG8_LDA(dst, b, h) do { _Pragma("unroll") for (int m = 0; m < 4; ++m) _Pragma("unroll") for (int k = 0; k < 2; ++k) dst[m][k] = *(const PG8_LAS bf16x8*)(lds + PG8_SA(b, h) + aoff + m * 2048 + k * 1024); } while (0)
; #define PG8_MMA(ai, bj, At, Bt) do { __builtin_amdgcn_s_setprio(1); _Pragma("unroll") for (int m = 0; m < 4; ++m) _Pragma("unroll") for (int n = 0; n < 2; ++n) _Pragma("unroll") for (int k = 0; k < 2; ++k) \
;         acc[ai][bj][m][n] = mma_<I8>(Bt[n][k], At[m][k], acc[ai][bj][m][n]); __builtin_amdgcn_s_setprio(0); } while (0)
; #define PG8_WAIT_V(n) asm volatile("s_waitcnt vmcnt(" #n ")" ::: "memory")
; #define PG8_WAIT_L(n) asm volatile("s_waitcnt lgkmcnt(" #n ")" ::: "memory")
; #define PG8_BAR __builtin_amdgcn_s_barrier()
; #define PG8_SCHED __builtin_amdgcn_sched_barrier(0)
; template <class Epi, class Sched, bool ALIGN_EPI = false, bool SP2 = false, bool I8 = false>
; __device__ __forceinline__ void gemm_phase(PG8_LAS unsigned char* lds, const Gemm g, const Sched& S, const Epi& E) {
;     ...
;         for (int t = 0; t < nt; t += 2) {
;             const bool last = (t == nt - 2);
;             const char* a1 = cA + (size_t)(t + 1) * kstep;
;             const char* a2 = last ? nA : cA + (size_t)(t + 2) * kstep; const char* b2 = last ? nB : cB + (size_t)(t + 2) * kstep;
;     ...
;             PG8_LDA(At, 1, 1); PG8_STAGE(PG8_SB(1, 0), b3, voffB); PG8_STAGE(PG8_SB(1, 1), b3 + hstepB, voffB); PG8_STAGE(PG8_SA(1, 0), a3, voffA);
;             PG8_WAIT_V(8); PG8_WAIT_L(0); PG8_BAR; PG8_MMA(1, 0, At, B0); PG8_MMA(1, 1, At, B1); PG8_BAR; PG8_SCHED;
	s_add_i32 s36, s40, s68
	v_lshl_add_u64 v[174:175], v[174:175], 0, s[18:19]
	s_mov_b32 m0, s36
	ds_read_b128 v[184:187], v179 offset:49152
	ds_read_b128 v[188:191], v179 offset:50176
	ds_read_b128 v[192:195], v179 offset:51200
	ds_read_b128 v[196:199], v179 offset:52224
	ds_read_b128 v[200:203], v179 offset:53248
	ds_read_b128 v[204:207], v179 offset:54272
	ds_read_b128 v[208:211], v179 offset:55296
	ds_read_b128 v[212:215], v179 offset:56320
	global_load_lds_dwordx4 v[174:175], off
	s_add_i32 m0, s36, 0x2000
	s_add_u32 s34, s34, 0x80080
	v_lshl_add_u64 v[174:175], v[216:217], 0, s[18:19]
	s_addc_u32 s35, s35, 0
	s_add_i32 s36, s41, s68
	global_load_lds_dwordx4 v[174:175], off
	v_lshl_add_u64 v[174:175], s[34:35], 0, v[148:149]
	s_mov_b32 m0, s36
	s_nop 0
	global_load_lds_dwordx4 v[174:175], off
	v_lshl_add_u64 v[174:175], s[34:35], 0, v[152:153]
	s_add_i32 m0, s36, 0x2000
	s_nop 0
	global_load_lds_dwordx4 v[174:175], off
	v_lshl_add_u64 v[174:175], v[218:219], 0, s[18:19]
	s_mov_b32 m0, s92
	s_nop 0
	global_load_lds_dwordx4 v[174:175], off
	v_lshl_add_u64 v[174:175], v[220:221], 0, s[18:19]
	s_mov_b32 m0, s93
	s_nop 0
	global_load_lds_dwordx4 v[174:175], off
	s_waitcnt vmcnt(8)
	s_waitcnt lgkmcnt(0)
	s_barrier
	s_waitcnt lgkmcnt(0)
	v_mfma_i32_16x16x64_i8 v[70:73], v[58:61], v[184:187], v[70:73]
	v_mfma_i32_16x16x64_i8 v[66:69], v[74:77], v[184:187], v[66:69]
	v_mfma_i32_16x16x64_i8 v[46:49], v[58:61], v[192:195], v[46:49]
	v_mfma_i32_16x16x64_i8 v[42:45], v[74:77], v[192:195], v[42:45]
	v_mfma_i32_16x16x64_i8 v[30:33], v[58:61], v[200:203], v[30:33]
	v_mfma_i32_16x16x64_i8 v[26:29], v[74:77], v[200:203], v[26:29]
	v_mfma_i32_16x16x64_i8 v[14:17], v[58:61], v[208:211], v[14:17]
	v_mfma_i32_16x16x64_i8 v[10:13], v[74:77], v[208:211], v[10:13]
	v_mfma_i32_16x16x64_i8 v[70:73], v[62:65], v[188:191], v[70:73]
	v_mfma_i32_16x16x64_i8 v[66:69], v[78:81], v[188:191], v[66:69]
	v_mfma_i32_16x16x64_i8 v[46:49], v[62:65], v[196:199], v[46:49]
	v_mfma_i32_16x16x64_i8 v[42:45], v[78:81], v[196:199], v[42:45]
	v_mfma_i32_16x16x64_i8 v[30:33], v[62:65], v[204:207], v[30:33]
	v_mfma_i32_16x16x64_i8 v[26:29], v[78:81], v[204:207], v[26:29]
	v_mfma_i32_16x16x64_i8 v[14:17], v[62:65], v[212:215], v[14:17]
	v_mfma_i32_16x16x64_i8 v[10:13], v[78:81], v[212:215], v[10:13]
	v_mfma_i32_16x16x64_i8 v[54:57], v[162:165], v[184:187], v[54:57]
	v_mfma_i32_16x16x64_i8 v[50:53], v[170:173], v[184:187], v[50:53]
	v_mfma_i32_16x16x64_i8 v[38:41], v[162:165], v[192:195], v[38:41]
	v_mfma_i32_16x16x64_i8 v[34:37], v[170:173], v[192:195], v[34:37]
	v_mfma_i32_16x16x64_i8 v[22:25], v[162:165], v[200:203], v[22:25]
	v_mfma_i32_16x16x64_i8 v[18:21], v[170:173], v[200:203], v[18:21]
	v_mfma_i32_16x16x64_i8 v[6:9], v[162:165], v[208:211], v[6:9]
	v_mfma_i32_16x16x64_i8 v[2:5], v[170:173], v[208:211], v[2:5]
	v_mfma_i32_16x16x64_i8 v[54:57], v[166:169], v[188:191], v[54:57]
	v_mfma_i32_16x16x64_i8 v[50:53], v[180:183], v[188:191], v[50:53]
	v_mfma_i32_16x16x64_i8 v[38:41], v[166:169], v[196:199], v[38:41]
	v_mfma_i32_16x16x64_i8 v[34:37], v[180:183], v[196:199], v[34:37]
	v_mfma_i32_16x16x64_i8 v[22:25], v[166:169], v[204:207], v[22:25]
	v_mfma_i32_16x16x64_i8 v[18:21], v[180:183], v[204:207], v[18:21]
	v_mfma_i32_16x16x64_i8 v[6:9], v[166:169], v[212:215], v[6:9]
	v_mfma_i32_16x16x64_i8 v[2:5], v[180:183], v[212:215], v[2:5]
	s_barrier
	s_add_i32 s39, s39, 2
	s_add_u32 s2, s2, 0x100
	s_addc_u32 s3, s3, 0
	s_add_u32 s31, s31, 0x100
	s_addc_u32 s38, s38, 0
	s_cmp_gt_u32 s39, 29
	s_cbranch_scc0 .LBB0_607
	s_and_b64 vcc, exec, s[20:21]
	s_cbranch_vccz .LBB0_610
	s_barrier

; #define LAS __attribute__((address_space(3)))
; #define GRID_BAR() xcd_barrier(bar)
; #define GRID_BAR() do {} while (0)
; #define BOTH(k) (IN(k) && IN((k) + 1))
; __device__ __forceinline__ float t5_bias_bucket(int dist) {
;     if (dist < 16) return (float)dist;
;     int l = 16 + (int)(logf((float)dist / 16.0f) / 4.852030263919617f * 16.0f); return (float)(l < 31 ? l : 31);
; }
; __device__ __forceinline__ void t_attn(Frame& F) {
;     typedef short bf16x8 __attribute__((ext_vector_type(8)));
;     unsigned char* ws = F.ws;
;     const bf16* QKV = (const bf16*)(ws + WS_QKV); bf16* OG = (bf16*)(ws + WS_OG); float* LSE = (float*)(ws + WS_LSE); const float* relb = F.in[6];
;     LAS unsigned char* KL = F.lds + RING_OFF; LAS unsigned char* VT = KL + KL_BYTES; LAS float* btab = (LAS float*)(KL + BT_OFF);
;     for (int i = F.tid; i < 12 * 132; i += 512) { const int hh = i / 132, j = i % 132, gi = hh >> 2; float bb = 0.f;
;         if (j <= 128) { const int bk = (int)t5_bias_bucket(j << (2 * gi)); bb = relb[bk * 12 + hh]; }
;         btab[i] = bb; }
; __global__ void __launch_bounds__(NWAVES * 64, 2) mk_fwd(Args args) {
;     ...
;     if (IN(T_ATTN)) { t_attn(F); __syncthreads(); t_lora_in(F); if (BOTH(T_ATTN)) GRID_BAR(); }
.LBB0_708:
	s_setprio 0
	s_cmp_lt_i32 s4, 3
	s_cselect_b64 s[0:1], -1, 0
	s_cmp_gt_i32 s5, 2
	s_cselect_b64 s[2:3], -1, 0
	s_and_b64 s[0:1], s[0:1], s[2:3]
	s_andn2_b64 vcc, exec, s[0:1]
	s_cbranch_vccnz .LBB0_1076
	v_add_u32_e32 v1, 0x21400, v1
	s_mov_b64 s[0:1], 0
	s_mov_b32 s6, 0x3e0f83e1
	s_movk_i32 s7, 0xff7c
	s_movk_i32 s8, 0x81
	s_mov_b32 s9, 0x800000
	s_mov_b32 s10, 0x3f317217
	s_mov_b32 s11, 0x7f800000
	s_mov_b32 s12, 0x409b43d5
	s_movk_i32 s13, 0x42f
	s_waitcnt vmcnt(15)
	v_mov_b32_e32 v3, 0x41b17218
	v_mov_b32_e32 v2, v0
	s_branch .LBB0_712

;     __host__ __device__ bool next(int i, Unit& u) const {
;         const long L = (long)i * G + c; if (L >= nwg) return false;
;         int wgid = (int)L; { const int q = nwg / NXCD, r = nwg % NXCD, xcd = wgid % NXCD, off = wgid / NXCD; wgid = (xcd < r ? xcd * (q + 1) : r * (q + 1) + (xcd - r) * q) + off; }
;         const int nig = WGM * nN, gid = wgid / nig, fm = gid * WGM, gsz = (nM - fm) < WGM ? (nM - fm) : WGM;
;         u.pm = fm + ((wgid % nig) % gsz); u.pn = (wgid % nig) / gsz; return true;
; __global__ void __launch_bounds__(NWAVES * 64, 2) mk_fwd(Args args) {
;     ...
;     if (IN(G_LORA)) {
;         pg8::Gemm g{(const bf16*)(ws + WS_ALORA), (const bf16*)(ws + WS_WLORA), M, LORAN, LORAK, LORAK, LORAK, 1}; pg8::StaticOrder S; S.init(M, LORAN, F.G, bx);
.LBB0_1076:
	s_cmp_lt_i32 s4, 4
	s_cselect_b64 s[0:1], -1, 0
	s_cmp_gt_i32 s5, 3
	s_cselect_b64 s[2:3], -1, 0
	s_and_b64 s[0:1], s[0:1], s[2:3]
	s_andn2_b64 vcc, exec, s[0:1]
	s_cbranch_vccnz .LBB0_1193
	v_readfirstlane_b32 s98, v0
	s_nop 3
	s_and_b32 s98, s98, 0x3ff
	s_lshr_b32 s98, s98, 6
	s_cmp_ge_u32 s98, 4
	s_cbranch_scc0 .Lprio_lora
	s_setprio 1
.Lprio_lora:
	v_readlane_b32 s0, v254, 3
	v_readlane_b32 s1, v254, 4
	s_mov_b32 s2, s0
	s_cmpk_lt_i32 s0, 0x600
	s_cselect_b64 s[0:1], -1, 0
	s_cmpk_gt_i32 s2, 0x5ff
	v_readfirstlane_b32 s4, v0
	s_cbranch_scc1 .LBB0_1079
	v_readlane_b32 s2, v254, 3
	s_mov_b32 s6, s2
	s_ashr_i32 s2, s2, 31
	s_lshr_b32 s2, s2, 29
	v_readlane_b32 s3, v254, 4
	s_add_i32 s2, s6, s2
	s_ashr_i32 s3, s2, 3
	s_and_b32 s2, s2, -8
	s_sub_i32 s2, s6, s2
	s_cmp_lt_i32 s2, 0
	s_movk_i32 s5, 0xc1
	s_cselect_b32 s5, s5, 0xc0
	s_mul_i32 s2, s2, s5
	s_add_i32 s2, s2, s3
	s_mul_hi_i32 s3, s2, 0x2aaaaaab
	s_lshr_b32 s5, s3, 31
	s_ashr_i32 s3, s3, 5
	s_add_i32 s3, s3, s5
	s_lshl_b32 s5, s3, 3
	s_mulk_i32 s3, 0xc0
	s_sub_i32 s2, s2, s3
	s_sext_i32_i16 s3, s2
	s_bfe_u32 s3, s3, 0x3001c
	s_add_i32 s3, s2, s3
	s_sext_i32_i16 s6, s3
	s_and_b32 s3, s3, 0xfff8
	s_sub_i32 s2, s2, s3
	s_sext_i32_i16 s2, s2
	s_add_i32 s2, s5, s2
	s_ashr_i32 s6, s6, 3

; #define PG8_STAGE(bufoff, gbase, voff) do { _Pragma("unroll") for (int _i = 0; _i < 2; ++_i) \
;         __builtin_amdgcn_global_load_lds((const unsigned*)((const char*)(gbase) + (voff)[_i]), (PG8_LAS unsigned*)(lds + (bufoff) + ldsw + _i * 8192), 16, 0, 0); } while (0)
; #define PG8_LDA(dst, b, h) do { _Pragma("unroll") for (int m = 0; m < 4; ++m) _Pragma("unroll") for (int k = 0; k < 2; ++k) dst[m][k] = *(const PG8_LAS bf16x8*)(lds + PG8_SA(b, h) + aoff + m * 2048 + k * 1024); } while (0)
; #define PG8_LDB(dst, b, h) do { _Pragma("unroll") for (int n = 0; n < 2; ++n) _Pragma("unroll") for (int k = 0; k < 2; ++k) dst[n][k] = *(const PG8_LAS bf16x8*)(lds + PG8_SB(b, h) + boff + n * 2048 + k * 1024); } while (0)
; #define PG8_MMA(ai, bj, At, Bt) do { __builtin_amdgcn_s_setprio(1); _Pragma("unroll") for (int m = 0; m < 4; ++m) _Pragma("unroll") for (int n = 0; n < 2; ++n) _Pragma("unroll") for (int k = 0; k < 2; ++k) \
;         acc[ai][bj][m][n] = mma_<I8>(Bt[n][k], At[m][k], acc[ai][bj][m][n]); __builtin_amdgcn_s_setprio(0); } while (0)
; #define PG8_WAIT_V(n) asm volatile("s_waitcnt vmcnt(" #n ")" ::: "memory")
; #define PG8_WAIT_L(n) asm volatile("s_waitcnt lgkmcnt(" #n ")" ::: "memory")
; #define PG8_BAR __builtin_amdgcn_s_barrier()
; #define PG8_SCHED __builtin_amdgcn_sched_barrier(0)
; template <class Epi, class Sched, bool ALIGN_EPI = false, bool SP2 = false, bool I8 = false>
; __device__ __forceinline__ void gemm_phase(PG8_LAS unsigned char* lds, const Gemm g, const Sched& S, const Epi& E) {
;     ...
;         for (int t = 0; t < nt; t += 2) {
;             const bool last = (t == nt - 2);
;             const char* a1 = cA + (size_t)(t + 1) * kstep;
;             const char* a2 = last ? nA : cA + (size_t)(t + 2) * kstep; const char* b2 = last ? nB : cB + (size_t)(t + 2) * kstep;
;             const char* a3 = a2 + kstep; const char* b3 = b2 + kstep;
;             if (last && has_next) S.a_ready(nxt);
;             if constexpr (SP2) {
;             PG8_LDB(B0, 0, 0); PG8_LDB(B1, 0, 1); PG8_SCHED; PG8_LDA(At, 0, 0); PG8_STAGE(PG8_SA(1, 1), a1 + hstepA, voffA);
;             PG8_WAIT_V(8); PG8_WAIT_L(0); PG8_BAR; PG8_MMA(0, 0, At, B0); PG8_MMA(0, 1, At, B1); PG8_BAR; PG8_SCHED;
;             PG8_LDA(At, 0, 1); PG8_STAGE(PG8_SB(0, 0), b2, voffB); PG8_STAGE(PG8_SB(0, 1), b2 + hstepB, voffB); PG8_STAGE(PG8_SA(0, 0), a2, voffA);
.LBB0_1092:
	ds_read_b128 v[58:61], v172
	ds_read_b128 v[62:65], v172 offset:1024
	ds_read_b128 v[74:77], v172 offset:2048
	ds_read_b128 v[78:81], v172 offset:3072
	ds_read_b128 v[164:167], v173
	ds_read_b128 v[168:171], v173 offset:1024
	ds_read_b128 v[176:179], v173 offset:2048
	ds_read_b128 v[180:183], v173 offset:3072
	s_add_i32 s47, s22, 2
	s_add_u32 s23, s8, 0xfffe0080
	s_addc_u32 s24, s9, -1
	s_cmp_eq_u32 s3, s22
	s_cselect_b32 s22, s20, s17
	s_cselect_b32 s25, s1, s24
	s_cselect_b32 s24, s0, s23
	s_cselect_b32 s23, s21, s19
	v_lshl_add_u64 v[216:217], s[8:9], 0, v[156:157]
	s_add_i32 m0, s33, 0xc000
	ds_read_b128 v[184:187], v174
	ds_read_b128 v[188:191], v174 offset:1024
	ds_read_b128 v[192:195], v174 offset:2048
	ds_read_b128 v[196:199], v174 offset:3072
	ds_read_b128 v[200:203], v174 offset:4096
	ds_read_b128 v[204:207], v174 offset:5120
	ds_read_b128 v[208:211], v174 offset:6144
	ds_read_b128 v[212:215], v174 offset:7168
	global_load_lds_dwordx4 v[216:217], off
	v_lshl_add_u64 v[216:217], s[8:9], 0, v[158:159]
	s_add_i32 m0, s33, 0xe000
	s_nop 0
	global_load_lds_dwordx4 v[216:217], off
	s_waitcnt vmcnt(8)
	s_waitcnt lgkmcnt(0)
	s_barrier
	s_waitcnt lgkmcnt(0)
	v_mfma_f32_16x16x32_bf16 v[142:145], v[58:61], v[184:187], v[142:145]
	v_mfma_f32_16x16x32_bf16 v[138:141], v[74:77], v[184:187], v[138:141]
	v_mfma_f32_16x16x32_bf16 v[126:129], v[58:61], v[192:195], v[126:129]
	v_mfma_f32_16x16x32_bf16 v[122:125], v[74:77], v[192:195], v[122:125]
	v_mfma_f32_16x16x32_bf16 v[110:113], v[58:61], v[200:203], v[110:113]
	v_mfma_f32_16x16x32_bf16 v[106:109], v[74:77], v[200:203], v[106:109]
	v_mfma_f32_16x16x32_bf16 v[94:97], v[58:61], v[208:211], v[94:97]
	v_mfma_f32_16x16x32_bf16 v[90:93], v[74:77], v[208:211], v[90:93]
	v_mfma_f32_16x16x32_bf16 v[142:145], v[62:65], v[188:191], v[142:145]
	v_mfma_f32_16x16x32_bf16 v[138:141], v[78:81], v[188:191], v[138:141]
	v_mfma_f32_16x16x32_bf16 v[126:129], v[62:65], v[196:199], v[126:129]
	v_mfma_f32_16x16x32_bf16 v[122:125], v[78:81], v[196:199], v[122:125]
	v_mfma_f32_16x16x32_bf16 v[110:113], v[62:65], v[204:207], v[110:113]
	v_mfma_f32_16x16x32_bf16 v[106:109], v[78:81], v[204:207], v[106:109]
	v_mfma_f32_16x16x32_bf16 v[94:97], v[62:65], v[212:215], v[94:97]
	v_mfma_f32_16x16x32_bf16 v[90:93], v[78:81], v[212:215], v[90:93]
	v_mfma_f32_16x16x32_bf16 v[134:137], v[164:167], v[184:187], v[134:137]
	v_mfma_f32_16x16x32_bf16 v[130:133], v[176:179], v[184:187], v[130:133]
	v_mfma_f32_16x16x32_bf16 v[118:121], v[164:167], v[192:195], v[118:121]
	v_mfma_f32_16x16x32_bf16 v[114:117], v[176:179], v[192:195], v[114:117]
	v_mfma_f32_16x16x32_bf16 v[102:105], v[164:167], v[200:203], v[102:105]
	v_mfma_f32_16x16x32_bf16 v[98:101], v[176:179], v[200:203], v[98:101]
	v_mfma_f32_16x16x32_bf16 v[86:89], v[164:167], v[208:211], v[86:89]
	v_mfma_f32_16x16x32_bf16 v[82:85], v[176:179], v[208:211], v[82:85]
	v_mfma_f32_16x16x32_bf16 v[134:137], v[168:171], v[188:191], v[134:137]
	v_mfma_f32_16x16x32_bf16 v[130:133], v[180:183], v[188:191], v[130:133]
	v_mfma_f32_16x16x32_bf16 v[118:121], v[168:171], v[196:199], v[118:121]
	v_mfma_f32_16x16x32_bf16 v[114:117], v[180:183], v[196:199], v[114:117]
	v_mfma_f32_16x16x32_bf16 v[102:105], v[168:171], v[204:207], v[102:105]
	v_mfma_f32_16x16x32_bf16 v[98:101], v[180:183], v[204:207], v[98:101]
	v_mfma_f32_16x16x32_bf16 v[86:89], v[168:171], v[212:215], v[86:89]
	v_mfma_f32_16x16x32_bf16 v[82:85], v[180:183], v[212:215], v[82:85]
	s_barrier
	s_add_i32 s56, s44, s30
	v_lshl_add_u64 v[216:217], s[22:23], 0, v[148:149]
	s_mov_b32 m0, s56
	ds_read_b128 v[184:187], v174 offset:16384
	ds_read_b128 v[188:191], v174 offset:17408
	ds_read_b128 v[192:195], v174 offset:18432
	ds_read_b128 v[196:199], v174 offset:19456
	ds_read_b128 v[200:203], v174 offset:20480
	ds_read_b128 v[204:207], v174 offset:21504
	ds_read_b128 v[208:211], v174 offset:22528
	ds_read_b128 v[212:215], v174 offset:23552
	global_load_lds_dwordx4 v[216:217], off
	s_add_i32 m0, s56, 0x2000
	s_add_u32 s56, s22, 0x20000
	v_lshl_add_u64 v[218:219], s[22:23], 0, v[152:153]
	s_addc_u32 s57, s23, 0
	s_add_i32 s58, s45, s30
	global_load_lds_dwordx4 v[218:219], off
	v_lshl_add_u64 v[220:221], s[56:57], 0, v[148:149]
	s_mov_b32 m0, s58
	v_lshl_add_u64 v[222:223], s[24:25], 0, v[150:151]
	global_load_lds_dwordx4 v[220:221], off
	v_lshl_add_u64 v[220:221], s[56:57], 0, v[152:153]
	s_add_i32 m0, s58, 0x2000
	s_nop 0
	global_load_lds_dwordx4 v[220:221], off
	v_lshl_add_u64 v[220:221], s[24:25], 0, v[146:147]
	s_mov_b32 m0, s33
	s_nop 0
	global_load_lds_dwordx4 v[220:221], off
	s_mov_b32 m0, s34
	s_nop 0
	global_load_lds_dwordx4 v[222:223], off
	s_waitcnt vmcnt(8)
	s_waitcnt lgkmcnt(0)
	s_barrier
; #define PG8_STAGE(bufoff, gbase, voff) do { _Pragma("unroll") for (int _i = 0; _i < 2; ++_i) \
;         __builtin_amdgcn_global_load_lds((const unsigned*)((const char*)(gbase) + (voff)[_i]), (PG8_LAS unsigned*)(lds + (bufoff) + ldsw + _i * 8192), 16, 0, 0); } while (0)
; #define PG8_LDA(dst, b, h) do { _Pragma("unroll") for (int m = 0; m < 4; ++m) _Pragma("unroll") for (int k = 0; k < 2; ++k) dst[m][k] = *(const PG8_LAS bf16x8*)(lds + PG8_SA(b, h) + aoff + m * 2048 + k * 1024); } while (0)
; #define PG8_LDB(dst, b, h) do { _Pragma("unroll") for (int n = 0; n < 2; ++n) _Pragma("unroll") for (int k = 0; k < 2; ++k) dst[n][k] = *(const PG8_LAS bf16x8*)(lds + PG8_SB(b, h) + boff + n * 2048 + k * 1024); } while (0)
; #define PG8_MMA(ai, bj, At, Bt) do { __builtin_amdgcn_s_setprio(1); _Pragma("unroll") for (int m = 0; m < 4; ++m) _Pragma("unroll") for (int n = 0; n < 2; ++n) _Pragma("unroll") for (int k = 0; k < 2; ++k) \
;         acc[ai][bj][m][n] = mma_<I8>(Bt[n][k], At[m][k], acc[ai][bj][m][n]); __builtin_amdgcn_s_setprio(0); } while (0)
; #define PG8_WAIT_V(n) asm volatile("s_waitcnt vmcnt(" #n ")" ::: "memory")
; #define PG8_WAIT_L(n) asm volatile("s_waitcnt lgkmcnt(" #n ")" ::: "memory")
; #define PG8_BAR __builtin_amdgcn_s_barrier()
; #define PG8_SCHED __builtin_amdgcn_sched_barrier(0)
; template <class Epi, class Sched, bool ALIGN_EPI = false, bool SP2 = false, bool I8 = false>
; __device__ __forceinline__ void gemm_phase(PG8_LAS unsigned char* lds, const Gemm g, const Sched& S, const Epi& E) {
;     ...
;             PG8_WAIT_V(8); PG8_WAIT_L(0); PG8_BAR; PG8_MMA(1, 0, At, B0); PG8_MMA(1, 1, At, B1); PG8_BAR; PG8_SCHED;
;             PG8_LDB(B0, 1, 0); PG8_LDB(B1, 1, 1); PG8_SCHED; PG8_LDA(At, 1, 0); PG8_STAGE(PG8_SA(0, 1), a2 + hstepA, voffA);
;             PG8_WAIT_V(8); PG8_WAIT_L(0); PG8_BAR; PG8_MMA(0, 0, At, B0); PG8_MMA(0, 1, At, B1); PG8_BAR; PG8_SCHED;
	s_waitcnt lgkmcnt(0)
	v_mfma_f32_16x16x32_bf16 v[70:73], v[58:61], v[184:187], v[70:73]
	v_mfma_f32_16x16x32_bf16 v[66:69], v[74:77], v[184:187], v[66:69]
	v_mfma_f32_16x16x32_bf16 v[46:49], v[58:61], v[192:195], v[46:49]
	v_mfma_f32_16x16x32_bf16 v[42:45], v[74:77], v[192:195], v[42:45]
	v_mfma_f32_16x16x32_bf16 v[30:33], v[58:61], v[200:203], v[30:33]
	v_mfma_f32_16x16x32_bf16 v[26:29], v[74:77], v[200:203], v[26:29]
	v_mfma_f32_16x16x32_bf16 v[14:17], v[58:61], v[208:211], v[14:17]
	v_mfma_f32_16x16x32_bf16 v[10:13], v[74:77], v[208:211], v[10:13]
	v_mfma_f32_16x16x32_bf16 v[70:73], v[62:65], v[188:191], v[70:73]
	v_mfma_f32_16x16x32_bf16 v[66:69], v[78:81], v[188:191], v[66:69]
	v_mfma_f32_16x16x32_bf16 v[46:49], v[62:65], v[196:199], v[46:49]
	v_mfma_f32_16x16x32_bf16 v[42:45], v[78:81], v[196:199], v[42:45]
	v_mfma_f32_16x16x32_bf16 v[30:33], v[62:65], v[204:207], v[30:33]
	v_mfma_f32_16x16x32_bf16 v[26:29], v[78:81], v[204:207], v[26:29]
	v_mfma_f32_16x16x32_bf16 v[14:17], v[62:65], v[212:215], v[14:17]
	v_mfma_f32_16x16x32_bf16 v[10:13], v[78:81], v[212:215], v[10:13]
	v_mfma_f32_16x16x32_bf16 v[54:57], v[164:167], v[184:187], v[54:57]
	v_mfma_f32_16x16x32_bf16 v[50:53], v[176:179], v[184:187], v[50:53]
	v_mfma_f32_16x16x32_bf16 v[38:41], v[164:167], v[192:195], v[38:41]
	v_mfma_f32_16x16x32_bf16 v[34:37], v[176:179], v[192:195], v[34:37]
	v_mfma_f32_16x16x32_bf16 v[22:25], v[164:167], v[200:203], v[22:25]
	v_mfma_f32_16x16x32_bf16 v[18:21], v[176:179], v[200:203], v[18:21]
	v_mfma_f32_16x16x32_bf16 v[6:9], v[164:167], v[208:211], v[6:9]
	v_mfma_f32_16x16x32_bf16 v[2:5], v[176:179], v[208:211], v[2:5]
	v_mfma_f32_16x16x32_bf16 v[54:57], v[168:171], v[188:191], v[54:57]
	v_mfma_f32_16x16x32_bf16 v[50:53], v[180:183], v[188:191], v[50:53]
	v_mfma_f32_16x16x32_bf16 v[38:41], v[168:171], v[196:199], v[38:41]
	v_mfma_f32_16x16x32_bf16 v[34:37], v[180:183], v[196:199], v[34:37]
	v_mfma_f32_16x16x32_bf16 v[22:25], v[168:171], v[204:207], v[22:25]
	v_mfma_f32_16x16x32_bf16 v[18:21], v[180:183], v[204:207], v[18:21]
	v_mfma_f32_16x16x32_bf16 v[6:9], v[168:171], v[212:215], v[6:9]
	v_mfma_f32_16x16x32_bf16 v[2:5], v[180:183], v[212:215], v[2:5]
	s_barrier
	s_add_i32 s56, 0, 0x18000
	s_add_i32 s57, 0, 0x1c000
	v_add_u32_e32 v78, s56, v1
	v_add_u32_e32 v154, s57, v1
	ds_read_b128 v[58:61], v78
	ds_read_b128 v[62:65], v78 offset:1024
	ds_read_b128 v[74:77], v78 offset:2048
	ds_read_b128 v[78:81], v78 offset:3072
	ds_read_b128 v[164:167], v154
	ds_read_b128 v[168:171], v154 offset:1024
	ds_read_b128 v[176:179], v154 offset:2048
	ds_read_b128 v[180:183], v154 offset:3072
	s_add_u32 s24, s24, 0x20000
	s_addc_u32 s25, s25, 0
	s_mov_b32 m0, s35
	v_lshl_add_u64 v[224:225], s[24:25], 0, v[146:147]
	ds_read_b128 v[184:187], v174 offset:32768
	ds_read_b128 v[188:191], v174 offset:33792
	ds_read_b128 v[192:195], v174 offset:34816
	ds_read_b128 v[196:199], v174 offset:35840
	ds_read_b128 v[200:203], v174 offset:36864
	ds_read_b128 v[204:207], v174 offset:37888
	ds_read_b128 v[208:211], v174 offset:38912
	ds_read_b128 v[212:215], v174 offset:39936
	global_load_lds_dwordx4 v[224:225], off
	v_lshl_add_u64 v[224:225], s[24:25], 0, v[150:151]
	s_mov_b32 m0, s36
	s_nop 0
	global_load_lds_dwordx4 v[224:225], off
	s_waitcnt vmcnt(8)
	s_waitcnt lgkmcnt(0)
	s_barrier
	s_waitcnt lgkmcnt(0)
	v_mfma_f32_16x16x32_bf16 v[142:145], v[58:61], v[184:187], v[142:145]
	v_mfma_f32_16x16x32_bf16 v[138:141], v[74:77], v[184:187], v[138:141]
	v_mfma_f32_16x16x32_bf16 v[126:129], v[58:61], v[192:195], v[126:129]
	v_mfma_f32_16x16x32_bf16 v[122:125], v[74:77], v[192:195], v[122:125]
	v_mfma_f32_16x16x32_bf16 v[110:113], v[58:61], v[200:203], v[110:113]
	v_mfma_f32_16x16x32_bf16 v[106:109], v[74:77], v[200:203], v[106:109]
	v_mfma_f32_16x16x32_bf16 v[94:97], v[58:61], v[208:211], v[94:97]
	v_mfma_f32_16x16x32_bf16 v[90:93], v[74:77], v[208:211], v[90:93]
	v_mfma_f32_16x16x32_bf16 v[142:145], v[62:65], v[188:191], v[142:145]
	v_mfma_f32_16x16x32_bf16 v[138:141], v[78:81], v[188:191], v[138:141]
	v_mfma_f32_16x16x32_bf16 v[126:129], v[62:65], v[196:199], v[126:129]
	v_mfma_f32_16x16x32_bf16 v[122:125], v[78:81], v[196:199], v[122:125]
	v_mfma_f32_16x16x32_bf16 v[110:113], v[62:65], v[204:207], v[110:113]
	v_mfma_f32_16x16x32_bf16 v[106:109], v[78:81], v[204:207], v[106:109]
	v_mfma_f32_16x16x32_bf16 v[94:97], v[62:65], v[212:215], v[94:97]
	v_mfma_f32_16x16x32_bf16 v[90:93], v[78:81], v[212:215], v[90:93]
	v_mfma_f32_16x16x32_bf16 v[134:137], v[164:167], v[184:187], v[134:137]
	v_mfma_f32_16x16x32_bf16 v[130:133], v[176:179], v[184:187], v[130:133]
	v_mfma_f32_16x16x32_bf16 v[118:121], v[164:167], v[192:195], v[118:121]
	v_mfma_f32_16x16x32_bf16 v[114:117], v[176:179], v[192:195], v[114:117]
	v_mfma_f32_16x16x32_bf16 v[102:105], v[164:167], v[200:203], v[102:105]
	v_mfma_f32_16x16x32_bf16 v[98:101], v[176:179], v[200:203], v[98:101]
	v_mfma_f32_16x16x32_bf16 v[86:89], v[164:167], v[208:211], v[86:89]
	v_mfma_f32_16x16x32_bf16 v[82:85], v[176:179], v[208:211], v[82:85]
	v_mfma_f32_16x16x32_bf16 v[134:137], v[168:171], v[188:191], v[134:137]
	v_mfma_f32_16x16x32_bf16 v[130:133], v[180:183], v[188:191], v[130:133]
	v_mfma_f32_16x16x32_bf16 v[118:121], v[168:171], v[196:199], v[118:121]
	v_mfma_f32_16x16x32_bf16 v[114:117], v[180:183], v[196:199], v[114:117]
	v_mfma_f32_16x16x32_bf16 v[102:105], v[168:171], v[204:207], v[102:105]
	v_mfma_f32_16x16x32_bf16 v[98:101], v[180:183], v[204:207], v[98:101]
	v_mfma_f32_16x16x32_bf16 v[86:89], v[168:171], v[212:215], v[86:89]
	v_mfma_f32_16x16x32_bf16 v[82:85], v[180:183], v[212:215], v[82:85]
	s_barrier
; #define PG8_STAGE(bufoff, gbase, voff) do { _Pragma("unroll") for (int _i = 0; _i < 2; ++_i) \
;         __builtin_amdgcn_global_load_lds((const unsigned*)((const char*)(gbase) + (voff)[_i]), (PG8_LAS unsigned*)(lds + (bufoff) + ldsw + _i * 8192), 16, 0, 0); } while (0)
; #define PG8_LDA(dst, b, h) do { _Pragma("unroll") for (int m = 0; m < 4; ++m) _Pragma("unroll") for (int k = 0; k < 2; ++k) dst[m][k] = *(const PG8_LAS bf16x8*)(lds + PG8_SA(b, h) + aoff + m * 2048 + k * 1024); } while (0)
; #define PG8_MMA(ai, bj, At, Bt) do { __builtin_amdgcn_s_setprio(1); _Pragma("unroll") for (int m = 0; m < 4; ++m) _Pragma("unroll") for (int n = 0; n < 2; ++n) _Pragma("unroll") for (int k = 0; k < 2; ++k) \
;         acc[ai][bj][m][n] = mma_<I8>(Bt[n][k], At[m][k], acc[ai][bj][m][n]); __builtin_amdgcn_s_setprio(0); } while (0)
; #define PG8_WAIT_V(n) asm volatile("s_waitcnt vmcnt(" #n ")" ::: "memory")
; #define PG8_WAIT_L(n) asm volatile("s_waitcnt lgkmcnt(" #n ")" ::: "memory")
; #define PG8_BAR __builtin_amdgcn_s_barrier()
; #define PG8_SCHED __builtin_amdgcn_sched_barrier(0)
; template <class Epi, class Sched, bool ALIGN_EPI = false, bool SP2 = false, bool I8 = false>
; __device__ __forceinline__ void gemm_phase(PG8_LAS unsigned char* lds, const Gemm g, const Sched& S, const Epi& E) {
;     ...
;         for (int t = 0; t < nt; t += 2) {
;             const bool last = (t == nt - 2);
;             const char* a1 = cA + (size_t)(t + 1) * kstep;
;             const char* a2 = last ? nA : cA + (size_t)(t + 2) * kstep; const char* b2 = last ? nB : cB + (size_t)(t + 2) * kstep;
;     ...
;             PG8_LDA(At, 1, 1); PG8_STAGE(PG8_SB(1, 0), b3, voffB); PG8_STAGE(PG8_SB(1, 1), b3 + hstepB, voffB); PG8_STAGE(PG8_SA(1, 0), a3, voffA);
;             PG8_WAIT_V(8); PG8_WAIT_L(0); PG8_BAR; PG8_MMA(1, 0, At, B0); PG8_MMA(1, 1, At, B1); PG8_BAR; PG8_SCHED;
	s_add_i32 s24, s56, s30
	v_lshl_add_u64 v[216:217], v[216:217], 0, s[12:13]
	s_mov_b32 m0, s24
	ds_read_b128 v[184:187], v174 offset:49152
	ds_read_b128 v[188:191], v174 offset:50176
	ds_read_b128 v[192:195], v174 offset:51200
	ds_read_b128 v[196:199], v174 offset:52224
	ds_read_b128 v[200:203], v174 offset:53248
	ds_read_b128 v[204:207], v174 offset:54272
	ds_read_b128 v[208:211], v174 offset:55296
	ds_read_b128 v[212:215], v174 offset:56320
	global_load_lds_dwordx4 v[216:217], off
	s_add_i32 m0, s24, 0x2000
	s_add_u32 s22, s22, 0x20080
	v_lshl_add_u64 v[216:217], v[218:219], 0, s[12:13]
	s_addc_u32 s23, s23, 0
	s_add_i32 s24, s57, s30
	global_load_lds_dwordx4 v[216:217], off
	v_lshl_add_u64 v[216:217], s[22:23], 0, v[148:149]
	s_mov_b32 m0, s24
	s_nop 0
	global_load_lds_dwordx4 v[216:217], off
	v_lshl_add_u64 v[216:217], s[22:23], 0, v[152:153]
	s_add_i32 m0, s24, 0x2000
	s_nop 0
	global_load_lds_dwordx4 v[216:217], off
	v_lshl_add_u64 v[216:217], v[220:221], 0, s[12:13]
	s_mov_b32 m0, s40
	s_nop 0
	global_load_lds_dwordx4 v[216:217], off
	v_lshl_add_u64 v[216:217], v[222:223], 0, s[12:13]
	s_mov_b32 m0, s41
	s_nop 0
	global_load_lds_dwordx4 v[216:217], off
	s_waitcnt vmcnt(8)
	s_waitcnt lgkmcnt(0)
	s_barrier
	s_waitcnt lgkmcnt(0)
	v_mfma_f32_16x16x32_bf16 v[70:73], v[58:61], v[184:187], v[70:73]
	v_mfma_f32_16x16x32_bf16 v[66:69], v[74:77], v[184:187], v[66:69]
	v_mfma_f32_16x16x32_bf16 v[46:49], v[58:61], v[192:195], v[46:49]
	v_mfma_f32_16x16x32_bf16 v[42:45], v[74:77], v[192:195], v[42:45]
	v_mfma_f32_16x16x32_bf16 v[30:33], v[58:61], v[200:203], v[30:33]
	v_mfma_f32_16x16x32_bf16 v[26:29], v[74:77], v[200:203], v[26:29]
	v_mfma_f32_16x16x32_bf16 v[14:17], v[58:61], v[208:211], v[14:17]
	v_mfma_f32_16x16x32_bf16 v[10:13], v[74:77], v[208:211], v[10:13]
	v_mfma_f32_16x16x32_bf16 v[70:73], v[62:65], v[188:191], v[70:73]
	v_mfma_f32_16x16x32_bf16 v[66:69], v[78:81], v[188:191], v[66:69]
	v_mfma_f32_16x16x32_bf16 v[46:49], v[62:65], v[196:199], v[46:49]
	v_mfma_f32_16x16x32_bf16 v[42:45], v[78:81], v[196:199], v[42:45]
	v_mfma_f32_16x16x32_bf16 v[30:33], v[62:65], v[204:207], v[30:33]
	v_mfma_f32_16x16x32_bf16 v[26:29], v[78:81], v[204:207], v[26:29]
	v_mfma_f32_16x16x32_bf16 v[14:17], v[62:65], v[212:215], v[14:17]
	v_mfma_f32_16x16x32_bf16 v[10:13], v[78:81], v[212:215], v[10:13]
	v_mfma_f32_16x16x32_bf16 v[54:57], v[164:167], v[184:187], v[54:57]
	v_mfma_f32_16x16x32_bf16 v[50:53], v[176:179], v[184:187], v[50:53]
	v_mfma_f32_16x16x32_bf16 v[38:41], v[164:167], v[192:195], v[38:41]
	v_mfma_f32_16x16x32_bf16 v[34:37], v[176:179], v[192:195], v[34:37]
	v_mfma_f32_16x16x32_bf16 v[22:25], v[164:167], v[200:203], v[22:25]
	v_mfma_f32_16x16x32_bf16 v[18:21], v[176:179], v[200:203], v[18:21]
	v_mfma_f32_16x16x32_bf16 v[6:9], v[164:167], v[208:211], v[6:9]
	v_mfma_f32_16x16x32_bf16 v[2:5], v[176:179], v[208:211], v[2:5]
	v_mfma_f32_16x16x32_bf16 v[54:57], v[168:171], v[188:191], v[54:57]
	v_mfma_f32_16x16x32_bf16 v[50:53], v[180:183], v[188:191], v[50:53]
	v_mfma_f32_16x16x32_bf16 v[38:41], v[168:171], v[196:199], v[38:41]
	v_mfma_f32_16x16x32_bf16 v[34:37], v[180:183], v[196:199], v[34:37]
	v_mfma_f32_16x16x32_bf16 v[22:25], v[168:171], v[204:207], v[22:25]
	v_mfma_f32_16x16x32_bf16 v[18:21], v[180:183], v[204:207], v[18:21]
	v_mfma_f32_16x16x32_bf16 v[6:9], v[168:171], v[212:215], v[6:9]
	v_mfma_f32_16x16x32_bf16 v[2:5], v[180:183], v[212:215], v[2:5]
	s_barrier
	s_add_u32 s8, s8, 0x100
	s_addc_u32 s9, s9, 0
	s_add_u32 s17, s17, 0x100
	s_addc_u32 s19, s19, 0
	s_cmp_ge_u32 s47, s7
	s_mov_b32 s22, s47
	s_cbranch_scc0 .LBB0_1092
	s_and_b64 vcc, exec, s[14:15]
	s_cbranch_vccz .LBB0_1095
	s_barrier

; #define LAS __attribute__((address_space(3)))
; __device__ __forceinline__ void t_scan1(Frame& F) {
;     unsigned char* ws = F.ws;
;     const bf16* Z = (const bf16*)(ws + WS_Z); const bf16* EAG = (const bf16*)(ws + WS_EAG);
;     bf16* YLOC = (bf16*)(ws + WS_YLOC); bf16* GBUF = (bf16*)(ws + WS_GBUF); float* LST = (float*)(ws + WS_LST); float* TST = (float*)(ws + WS_TST); float* RKB = (float*)(ws + WS_RKB);
;     const float* mix = F.in[8]; const float* k_k = F.in[14]; const float* k_a = F.in[15]; const float* r_k = F.in[16];
;     const int lane = F.lane, wave = F.wave, pr = wave & 3, n = lane & 15, q = lane >> 4;
;     const bool isT = wave >= 4;
;     LAS unsigned char* WB = F.lds + RING_OFF + pr * SC_WAVE;
;     const v2u z2 = (v2u){0u, 0u};
;     for (int wi = blockIdx.x; wi < 128 * NCH / 4; wi += F.G) {
;         const int pair = wi * 4 + pr, unit = pair / NCH, ch = pair % NCH, b = unit >> 5, h = unit & 31, c = h * 64 + lane;
;         const size_t rowc = (size_t)b * SEQ + (size_t)ch * CHL;
;         const int tc = ch * CHL;
;         const bool phi_on = ch > 0;
;         f32x4 acc[4][4];
; #pragma unroll
;         for (int jt = 0; jt < 4; ++jt)
; #pragma unroll
;             for (int it = 0; it < 4; ++it)
; #pragma unroll
;                 for (int r = 0; r < 4; ++r) acc[jt][it][r] = (isT && jt == it && 4 * q + r == n) ? 1.f : 0.f;
;         const float mr = mix[c], mk = mix[2048 + c], mv = mix[4096 + c], kkc = k_k[c], kac = k_a[c], rkc = r_k[c];
;         v4u raw[5];
;         const int hf = isT ? 1 : 0;
;         const unsigned lo_z = (unsigned)(lane >> 3) * (NZP * 2) + (unsigned)(lane & 7) * 16, lo_e = (unsigned)(lane >> 3) * 4096 + (unsigned)(lane & 7) * 16, lo_l = (unsigned)(lane >> 3) * 640 + (unsigned)(lane & 7) * 16;
;         { const char* zb = (const char*)(Z + (rowc + 8 * hf) * NZP + h * 64); const char* eb = (const char*)(EAG + (rowc + 8 * hf) * 2048 + h * 64);
; #pragma unroll
;             for (int i = 0; i < 5; ++i) raw[i] = i < 3 ? *(const v4u*)(zb + i * 4096 + lo_z) : *(const v4u*)(eb + (size_t)(i - 3) * M * 4096 + lo_e); }
;         bf16 pz0 = 0, pz1 = 0, pz2 = 0;
;         if (!isT && tc > 0) { const bf16* zp = Z + (rowc - 1) * NZP; pz0 = zp[c]; pz1 = zp[2048 + c]; pz2 = zp[4096 + c]; }
; __global__ void __launch_bounds__(NWAVES * 64, 2) mk_fwd(Args args) {
;     ...
;     if (IN(T_SCAN)) { t_scan1(F); if (BOTH(T_SCAN)) GRID_BAR(); }
.LBB0_1193:
	s_setprio 0
	s_cmp_lt_i32 s4, 5
	s_cselect_b64 s[0:1], -1, 0
	s_cmp_gt_i32 s5, 4
	s_cselect_b64 s[2:3], -1, 0
	s_and_b64 s[0:1], s[0:1], s[2:3]
	s_andn2_b64 vcc, exec, s[0:1]
	s_cbranch_vccnz .LBB0_1335
	v_readlane_b32 s0, v254, 3
	s_cmpk_gt_i32 s0, 0xff
	v_readlane_b32 s1, v254, 4
	s_cbranch_scc1 .LBB0_1281
	s_add_u32 s0, s96, 0x1e400000
	s_addc_u32 s1, s97, 0
	s_add_u32 s24, s96, 0x40400000
	s_addc_u32 s25, s97, 0
	s_add_u32 s60, s96, 0x15400000
	s_addc_u32 s61, s97, 0
	s_add_u32 s68, s96, 0x9200000
	v_readlane_b32 s3, v254, 0
	s_addc_u32 s69, s97, 0
	s_bfe_u32 s70, s3, 0x20006
	s_cmpk_lt_u32 s3, 0x100
	s_mul_i32 s2, s70, 0x8a00
	s_cselect_b64 s[26:27], -1, 0
	s_add_i32 s71, s2, 0
	s_cmpk_gt_u32 s3, 0xff
	s_cselect_b64 s[30:31], -1, 0
	s_and_b64 s[2:3], s[30:31], exec
	s_cselect_b32 s34, 8, 0
	s_mul_i32 s3, s34, 0x280
	s_mov_b32 s4, 0x4c400000
	s_waitcnt vmcnt(0)
	v_lshlrev_b32_e32 v5, 4, v0
	s_cselect_b32 s72, 2, 0
	s_cselect_b32 s8, s4, 0x8200000
	s_add_i32 s3, s71, s3
	v_lshrrev_b32_e32 v170, 4, v232
	v_lshrrev_b32_e32 v3, 3, v232
	v_and_b32_e32 v5, 0x70, v5
	s_movk_i32 s2, 0x280
	v_mov_b32_e32 v6, s3
	v_and_b32_e32 v1, 15, v0
	v_lshlrev_b32_e32 v2, 2, v170
	v_mul_u32_u24_e32 v4, 0x3400, v3
	v_lshl_or_b32 v156, v3, 12, v5
	v_mad_u32_u24 v3, v3, s2, v6
	s_or_b32 s73, s34, 16
	v_mad_u32_u24 v172, v232, 40, s71
	s_movk_i32 s2, 0xffdc
	v_mov_b32_e32 v7, s71
	v_mad_i32_i24 v173, v232, s2, v172
	s_movk_i32 s2, 0x90
	s_add_u32 s74, s96, s8
	v_cmp_eq_u32_e32 vcc, v2, v1
	v_or_b32_e32 v11, 1, v2
	v_lshlrev_b32_e32 v6, 1, v232
	v_mad_u32_u24 v175, v1, s2, v7
	s_addc_u32 s75, s97, 0
	s_and_b64 s[2:3], s[30:31], vcc
	v_cmp_eq_u32_e32 vcc, v11, v1
	v_or_b32_e32 v12, 2, v2
	v_add_u32_e32 v171, s71, v6
	v_sub_u32_e32 v10, 0, v6
	v_cndmask_b32_e64 v6, 0, 1.0, s[2:3]
	s_and_b64 s[2:3], s[30:31], vcc
	v_cmp_eq_u32_e32 vcc, v12, v1
	v_or_b32_e32 v13, 3, v2
	v_cndmask_b32_e64 v7, 0, 1.0, s[2:3]
	s_and_b64 s[2:3], s[30:31], vcc
	v_cmp_eq_u32_e32 vcc, v13, v1
	v_cndmask_b32_e64 v8, 0, 1.0, s[2:3]
	s_and_b64 s[2:3], s[30:31], vcc
	v_cmp_eq_u32_e32 vcc, 0, v1
	v_cmp_lt_u32_e64 s[8:9], v1, v2
	v_cmp_gt_u32_e64 s[10:11], v1, v2
	v_cndmask_b32_e64 v183, 0, 1.0, vcc
	v_cmp_eq_u32_e32 vcc, 1, v1
	v_lshl_or_b32 v2, v170, 6, v1
	v_lshl_or_b32 v14, v11, 4, v1
	v_cndmask_b32_e64 v184, 0, 1.0, vcc
	v_cmp_eq_u32_e32 vcc, 2, v1
	v_cmp_lt_u32_e64 s[14:15], v1, v12
	v_cmp_gt_u32_e64 s[16:17], v1, v12
	v_cndmask_b32_e64 v185, 0, 1.0, vcc
	v_cmp_eq_u32_e32 vcc, 3, v1
	v_lshl_or_b32 v12, v12, 4, v1
	v_cmp_lt_u32_e64 s[18:19], v1, v13
	v_cndmask_b32_e64 v186, 0, 1.0, vcc
	v_cmp_eq_u32_e32 vcc, 4, v1
	v_cmp_gt_u32_e64 s[20:21], v1, v13
	v_lshl_or_b32 v13, v13, 4, v1
	v_cndmask_b32_e64 v187, 0, 1.0, vcc
	v_cmp_eq_u32_e32 vcc, 5, v1
	v_or_b32_e32 v154, v4, v5
	v_mov_b32_e32 v4, 0
	v_cndmask_b32_e64 v188, 0, 1.0, vcc
	v_cmp_eq_u32_e32 vcc, 6, v1
	v_lshl_add_u32 v179, v2, 2, s71
	v_lshlrev_b32_e32 v2, 1, v2
	v_cndmask_b32_e64 v189, 0, 1.0, vcc
	v_cmp_eq_u32_e32 vcc, 7, v1
	v_lshl_add_u32 v180, v14, 2, s71
	v_lshlrev_b32_e32 v14, 1, v14
	v_cndmask_b32_e64 v190, 0, 1.0, vcc
	v_cmp_eq_u32_e32 vcc, 8, v1
	v_lshl_add_u32 v181, v12, 2, s71
	v_lshlrev_b32_e32 v12, 1, v12
	v_cndmask_b32_e64 v191, 0, 1.0, vcc
	v_cmp_eq_u32_e32 vcc, 9, v1
	v_lshl_add_u32 v182, v13, 2, s71
	v_lshlrev_b32_e32 v13, 1, v13
	v_cndmask_b32_e64 v192, 0, 1.0, vcc
	v_cmp_eq_u32_e32 vcc, 10, v1
	s_mov_b32 s29, 0
	v_mov_b32_e32 v157, v4
	v_cndmask_b32_e64 v193, 0, 1.0, vcc
	v_cmp_eq_u32_e32 vcc, 11, v1
	v_mov_b32_e32 v155, v4
	v_lshlrev_b32_e32 v177, 3, v170
	v_cndmask_b32_e64 v194, 0, 1.0, vcc
	v_cmp_eq_u32_e32 vcc, 12, v1
	v_cndmask_b32_e64 v9, 0, 1.0, s[2:3]
	v_sub_u32_e32 v2, 0, v2
	v_cndmask_b32_e64 v195, 0, 1.0, vcc
	v_cmp_eq_u32_e32 vcc, 13, v1
	v_cmp_gt_u32_e64 s[12:13], v1, v11
	v_sub_u32_e32 v14, 0, v14
	v_cndmask_b32_e64 v196, 0, 1.0, vcc
	v_cmp_eq_u32_e32 vcc, 14, v1
	v_sub_u32_e32 v12, 0, v12
	v_sub_u32_e32 v13, 0, v13
	v_cndmask_b32_e64 v197, 0, 1.0, vcc
	v_cmp_eq_u32_e32 vcc, 15, v1
	v_lshl_add_u32 v15, v1, 1, s71
	v_mul_u32_u24_e32 v16, 0x240, v170
	v_mul_u32_u24_e32 v11, 0x90, v11
	v_readlane_b32 s2, v254, 3
	s_mov_b32 s35, s29
	v_lshl_add_u64 v[158:159], s[24:25], 0, v[156:157]
	v_lshl_add_u64 v[160:161], s[0:1], 0, v[154:155]
	v_cmp_eq_u32_e64 s[4:5], 0, v232
	v_and_b32_e32 v174, 48, v0
	v_cmp_gt_u32_e64 s[6:7], 16, v232
	v_lshl_add_u32 v176, v1, 5, s71
	v_add_u32_e32 v178, s71, v177
	v_cndmask_b32_e64 v198, 0, 1.0, vcc
	v_cvt_pk_bf16_f32 v199, v183, s0
	v_mul_u32_u24_e32 v200, 40, v1
	s_movk_i32 s76, 0x1000
	v_add_u32_e32 v201, v3, v5
	v_add_u32_e32 v202, v179, v2
	v_add_u32_e32 v203, v180, v14
	v_add_u32_e32 v204, v181, v12
	v_add_u32_e32 v205, v182, v13
	v_add_u32_e32 v206, v15, v16
	v_add_u32_e32 v207, v15, v11
	v_mov_b32_e32 v208, 0x3400
	v_add_u32_e32 v209, v173, v10
	s_mov_b32 s77, s2
	v_readlane_b32 s3, v254, 4
	s_branch .LBB0_1197

; __global__ void __launch_bounds__(NWAVES * 64, 2) mk_fwd(Args args) {
;     ...
;     if (IN(G_ATTUP)) {
;         pg8::Gemm g{(const bf16*)(ws + WS_ATT), (const bf16*)(ws + WS_WATT), M, D, AOW, AOW, AOW, 0}; pg8::StaticOrder S; S.init(M, D, F.G, bx);
.LBB0_1520:
	s_cmp_lt_i32 s4, 8
	s_cselect_b64 s[0:1], -1, 0
	s_cmp_gt_i32 s5, 7
	s_cselect_b64 s[2:3], -1, 0
	s_and_b64 s[0:1], s[0:1], s[2:3]
	s_andn2_b64 vcc, exec, s[0:1]
	s_cbranch_vccnz .LBB0_1545
	v_readfirstlane_b32 s98, v0
	s_nop 3
	s_and_b32 s98, s98, 0x3ff
	s_lshr_b32 s98, s98, 6
	s_cmp_ge_u32 s98, 4
	s_cbranch_scc0 .Lprio_attup
	s_setprio 1

; #define PG8_STAGE(bufoff, gbase, voff) do { _Pragma("unroll") for (int _i = 0; _i < 2; ++_i) \
;         __builtin_amdgcn_global_load_lds((const unsigned*)((const char*)(gbase) + (voff)[_i]), (PG8_LAS unsigned*)(lds + (bufoff) + ldsw + _i * 8192), 16, 0, 0); } while (0)
; #define PG8_LDA(dst, b, h) do { _Pragma("unroll") for (int m = 0; m < 4; ++m) _Pragma("unroll") for (int k = 0; k < 2; ++k) dst[m][k] = *(const PG8_LAS bf16x8*)(lds + PG8_SA(b, h) + aoff + m * 2048 + k * 1024); } while (0)
; #define PG8_LDB(dst, b, h) do { _Pragma("unroll") for (int n = 0; n < 2; ++n) _Pragma("unroll") for (int k = 0; k < 2; ++k) dst[n][k] = *(const PG8_LAS bf16x8*)(lds + PG8_SB(b, h) + boff + n * 2048 + k * 1024); } while (0)
; #define PG8_MMA(ai, bj, At, Bt) do { __builtin_amdgcn_s_setprio(1); _Pragma("unroll") for (int m = 0; m < 4; ++m) _Pragma("unroll") for (int n = 0; n < 2; ++n) _Pragma("unroll") for (int k = 0; k < 2; ++k) \
;         acc[ai][bj][m][n] = mma_<I8>(Bt[n][k], At[m][k], acc[ai][bj][m][n]); __builtin_amdgcn_s_setprio(0); } while (0)
; #define PG8_WAIT_V(n) asm volatile("s_waitcnt vmcnt(" #n ")" ::: "memory")
; #define PG8_WAIT_L(n) asm volatile("s_waitcnt lgkmcnt(" #n ")" ::: "memory")
; #define PG8_BAR __builtin_amdgcn_s_barrier()
; #define PG8_SCHED __builtin_amdgcn_sched_barrier(0)
; template <class Epi, class Sched, bool ALIGN_EPI = false, bool SP2 = false, bool I8 = false>
; __device__ __forceinline__ void gemm_phase(PG8_LAS unsigned char* lds, const Gemm g, const Sched& S, const Epi& E) {
;     ...
;         for (int t = 0; t < nt; t += 2) {
;             const bool last = (t == nt - 2);
;             const char* a1 = cA + (size_t)(t + 1) * kstep;
;             const char* a2 = last ? nA : cA + (size_t)(t + 2) * kstep; const char* b2 = last ? nB : cB + (size_t)(t + 2) * kstep;
;             const char* a3 = a2 + kstep; const char* b3 = b2 + kstep;
;             if (last && has_next) S.a_ready(nxt);
;             if constexpr (SP2) {
;             PG8_LDB(B0, 0, 0); PG8_LDB(B1, 0, 1); PG8_SCHED; PG8_LDA(At, 0, 0); PG8_STAGE(PG8_SA(1, 1), a1 + hstepA, voffA);
;             PG8_WAIT_V(8); PG8_WAIT_L(0); PG8_BAR; PG8_MMA(0, 0, At, B0); PG8_MMA(0, 1, At, B1); PG8_BAR; PG8_SCHED;
;             PG8_LDA(At, 0, 1); PG8_STAGE(PG8_SB(0, 0), b2, voffB); PG8_STAGE(PG8_SB(0, 1), b2 + hstepB, voffB); PG8_STAGE(PG8_SA(0, 0), a2, voffA);
.LBB0_1538:
	ds_read_b128 v[146:149], v154
	ds_read_b128 v[150:153], v154 offset:1024
	ds_read_b128 v[158:161], v154 offset:2048
	ds_read_b128 v[162:165], v154 offset:3072
	ds_read_b128 v[166:169], v155
	ds_read_b128 v[170:173], v155 offset:1024
	ds_read_b128 v[174:177], v155 offset:2048
	ds_read_b128 v[178:181], v155 offset:3072
	s_add_u32 s24, s22, 0xfffe0080
	s_addc_u32 s25, s23, -1
	s_cmp_eq_u32 s49, 4
	s_cselect_b32 s27, s15, s25
	s_cselect_b32 s26, s45, s24
	s_cselect_b32 s25, s13, s48
	s_cselect_b32 s24, s46, s47
	v_lshl_add_u64 v[214:215], s[22:23], 0, v[138:139]
	s_add_i32 m0, s21, 0xc000
	ds_read_b128 v[182:185], v156
	ds_read_b128 v[186:189], v156 offset:1024
	ds_read_b128 v[190:193], v156 offset:2048
	ds_read_b128 v[194:197], v156 offset:3072
	ds_read_b128 v[198:201], v156 offset:4096
	ds_read_b128 v[202:205], v156 offset:5120
	ds_read_b128 v[206:209], v156 offset:6144
	ds_read_b128 v[210:213], v156 offset:7168
	global_load_lds_dwordx4 v[214:215], off
	v_lshl_add_u64 v[214:215], s[22:23], 0, v[140:141]
	s_add_i32 m0, s21, 0xe000
	s_nop 0
	global_load_lds_dwordx4 v[214:215], off
	s_waitcnt vmcnt(8)
	s_waitcnt lgkmcnt(0)
	s_barrier
	s_waitcnt lgkmcnt(0)
	v_mfma_f32_16x16x32_bf16 v[126:129], v[146:149], v[182:185], v[126:129]
	v_mfma_f32_16x16x32_bf16 v[122:125], v[158:161], v[182:185], v[122:125]
	v_mfma_f32_16x16x32_bf16 v[114:117], v[146:149], v[190:193], v[114:117]
	v_mfma_f32_16x16x32_bf16 v[106:109], v[158:161], v[190:193], v[106:109]
	v_mfma_f32_16x16x32_bf16 v[94:97], v[146:149], v[198:201], v[94:97]
	v_mfma_f32_16x16x32_bf16 v[90:93], v[158:161], v[198:201], v[90:93]
	v_mfma_f32_16x16x32_bf16 v[86:89], v[146:149], v[206:209], v[86:89]
	v_mfma_f32_16x16x32_bf16 v[82:85], v[158:161], v[206:209], v[82:85]
	v_mfma_f32_16x16x32_bf16 v[126:129], v[150:153], v[186:189], v[126:129]
	v_mfma_f32_16x16x32_bf16 v[122:125], v[162:165], v[186:189], v[122:125]
	v_mfma_f32_16x16x32_bf16 v[114:117], v[150:153], v[194:197], v[114:117]
	v_mfma_f32_16x16x32_bf16 v[106:109], v[162:165], v[194:197], v[106:109]
	v_mfma_f32_16x16x32_bf16 v[94:97], v[150:153], v[202:205], v[94:97]
	v_mfma_f32_16x16x32_bf16 v[90:93], v[162:165], v[202:205], v[90:93]
	v_mfma_f32_16x16x32_bf16 v[86:89], v[150:153], v[210:213], v[86:89]
	v_mfma_f32_16x16x32_bf16 v[82:85], v[162:165], v[210:213], v[82:85]
	v_mfma_f32_16x16x32_bf16 v[118:121], v[166:169], v[182:185], v[118:121]
	v_mfma_f32_16x16x32_bf16 v[110:113], v[174:177], v[182:185], v[110:113]
	v_mfma_f32_16x16x32_bf16 v[102:105], v[166:169], v[190:193], v[102:105]
	v_mfma_f32_16x16x32_bf16 v[98:101], v[174:177], v[190:193], v[98:101]
	v_mfma_f32_16x16x32_bf16 v[78:81], v[166:169], v[198:201], v[78:81]
	v_mfma_f32_16x16x32_bf16 v[74:77], v[174:177], v[198:201], v[74:77]
	v_mfma_f32_16x16x32_bf16 v[70:73], v[166:169], v[206:209], v[70:73]
	v_mfma_f32_16x16x32_bf16 v[66:69], v[174:177], v[206:209], v[66:69]
	v_mfma_f32_16x16x32_bf16 v[118:121], v[170:173], v[186:189], v[118:121]
	v_mfma_f32_16x16x32_bf16 v[110:113], v[178:181], v[186:189], v[110:113]
	v_mfma_f32_16x16x32_bf16 v[102:105], v[170:173], v[194:197], v[102:105]
	v_mfma_f32_16x16x32_bf16 v[98:101], v[178:181], v[194:197], v[98:101]
	v_mfma_f32_16x16x32_bf16 v[78:81], v[170:173], v[202:205], v[78:81]
	v_mfma_f32_16x16x32_bf16 v[74:77], v[178:181], v[202:205], v[74:77]
	v_mfma_f32_16x16x32_bf16 v[70:73], v[170:173], v[210:213], v[70:73]
	v_mfma_f32_16x16x32_bf16 v[66:69], v[178:181], v[210:213], v[66:69]
	s_barrier
	s_add_i32 s50, s42, s34
	v_lshl_add_u64 v[214:215], s[24:25], 0, v[132:133]
	s_mov_b32 m0, s50
	ds_read_b128 v[182:185], v156 offset:16384
	ds_read_b128 v[186:189], v156 offset:17408
	ds_read_b128 v[190:193], v156 offset:18432
	ds_read_b128 v[194:197], v156 offset:19456
	ds_read_b128 v[198:201], v156 offset:20480
	ds_read_b128 v[202:205], v156 offset:21504
	ds_read_b128 v[206:209], v156 offset:22528
	ds_read_b128 v[210:213], v156 offset:23552
	global_load_lds_dwordx4 v[214:215], off
	s_add_i32 m0, s50, 0x2000
	s_add_u32 s50, s24, 0x20000
	v_lshl_add_u64 v[216:217], s[24:25], 0, v[136:137]
	s_addc_u32 s51, s25, 0
	s_add_i32 s52, s43, s34
	global_load_lds_dwordx4 v[216:217], off
	v_lshl_add_u64 v[218:219], s[50:51], 0, v[132:133]
	s_mov_b32 m0, s52
	v_lshl_add_u64 v[220:221], s[26:27], 0, v[134:135]
	global_load_lds_dwordx4 v[218:219], off
	v_lshl_add_u64 v[218:219], s[50:51], 0, v[136:137]
	s_add_i32 m0, s52, 0x2000
	s_nop 0
	global_load_lds_dwordx4 v[218:219], off
	v_lshl_add_u64 v[218:219], s[26:27], 0, v[130:131]
	s_mov_b32 m0, s21
	s_nop 0
	global_load_lds_dwordx4 v[218:219], off
	s_mov_b32 m0, s35
	s_nop 0
	global_load_lds_dwordx4 v[220:221], off
	s_waitcnt vmcnt(8)
	s_waitcnt lgkmcnt(0)
	s_barrier
; #define PG8_STAGE(bufoff, gbase, voff) do { _Pragma("unroll") for (int _i = 0; _i < 2; ++_i) \
;         __builtin_amdgcn_global_load_lds((const unsigned*)((const char*)(gbase) + (voff)[_i]), (PG8_LAS unsigned*)(lds + (bufoff) + ldsw + _i * 8192), 16, 0, 0); } while (0)
; #define PG8_LDA(dst, b, h) do { _Pragma("unroll") for (int m = 0; m < 4; ++m) _Pragma("unroll") for (int k = 0; k < 2; ++k) dst[m][k] = *(const PG8_LAS bf16x8*)(lds + PG8_SA(b, h) + aoff + m * 2048 + k * 1024); } while (0)
; #define PG8_LDB(dst, b, h) do { _Pragma("unroll") for (int n = 0; n < 2; ++n) _Pragma("unroll") for (int k = 0; k < 2; ++k) dst[n][k] = *(const PG8_LAS bf16x8*)(lds + PG8_SB(b, h) + boff + n * 2048 + k * 1024); } while (0)
; #define PG8_MMA(ai, bj, At, Bt) do { __builtin_amdgcn_s_setprio(1); _Pragma("unroll") for (int m = 0; m < 4; ++m) _Pragma("unroll") for (int n = 0; n < 2; ++n) _Pragma("unroll") for (int k = 0; k < 2; ++k) \
;         acc[ai][bj][m][n] = mma_<I8>(Bt[n][k], At[m][k], acc[ai][bj][m][n]); __builtin_amdgcn_s_setprio(0); } while (0)
; #define PG8_WAIT_V(n) asm volatile("s_waitcnt vmcnt(" #n ")" ::: "memory")
; #define PG8_WAIT_L(n) asm volatile("s_waitcnt lgkmcnt(" #n ")" ::: "memory")
; #define PG8_BAR __builtin_amdgcn_s_barrier()
; #define PG8_SCHED __builtin_amdgcn_sched_barrier(0)
; template <class Epi, class Sched, bool ALIGN_EPI = false, bool SP2 = false, bool I8 = false>
; __device__ __forceinline__ void gemm_phase(PG8_LAS unsigned char* lds, const Gemm g, const Sched& S, const Epi& E) {
;     ...
;             PG8_WAIT_V(8); PG8_WAIT_L(0); PG8_BAR; PG8_MMA(1, 0, At, B0); PG8_MMA(1, 1, At, B1); PG8_BAR; PG8_SCHED;
;             PG8_LDB(B0, 1, 0); PG8_LDB(B1, 1, 1); PG8_SCHED; PG8_LDA(At, 1, 0); PG8_STAGE(PG8_SA(0, 1), a2 + hstepA, voffA);
;             PG8_WAIT_V(8); PG8_WAIT_L(0); PG8_BAR; PG8_MMA(0, 0, At, B0); PG8_MMA(0, 1, At, B1); PG8_BAR; PG8_SCHED;
	s_waitcnt lgkmcnt(0)
	v_mfma_f32_16x16x32_bf16 v[62:65], v[146:149], v[182:185], v[62:65]
	v_mfma_f32_16x16x32_bf16 v[58:61], v[158:161], v[182:185], v[58:61]
	v_mfma_f32_16x16x32_bf16 v[54:57], v[146:149], v[190:193], v[54:57]
	v_mfma_f32_16x16x32_bf16 v[50:53], v[158:161], v[190:193], v[50:53]
	v_mfma_f32_16x16x32_bf16 v[30:33], v[146:149], v[198:201], v[30:33]
	v_mfma_f32_16x16x32_bf16 v[26:29], v[158:161], v[198:201], v[26:29]
	v_mfma_f32_16x16x32_bf16 v[22:25], v[146:149], v[206:209], v[22:25]
	v_mfma_f32_16x16x32_bf16 v[10:13], v[158:161], v[206:209], v[10:13]
	v_mfma_f32_16x16x32_bf16 v[62:65], v[150:153], v[186:189], v[62:65]
	v_mfma_f32_16x16x32_bf16 v[58:61], v[162:165], v[186:189], v[58:61]
	v_mfma_f32_16x16x32_bf16 v[54:57], v[150:153], v[194:197], v[54:57]
	v_mfma_f32_16x16x32_bf16 v[50:53], v[162:165], v[194:197], v[50:53]
	v_mfma_f32_16x16x32_bf16 v[30:33], v[150:153], v[202:205], v[30:33]
	v_mfma_f32_16x16x32_bf16 v[26:29], v[162:165], v[202:205], v[26:29]
	v_mfma_f32_16x16x32_bf16 v[22:25], v[150:153], v[210:213], v[22:25]
	v_mfma_f32_16x16x32_bf16 v[10:13], v[162:165], v[210:213], v[10:13]
	v_mfma_f32_16x16x32_bf16 v[46:49], v[166:169], v[182:185], v[46:49]
	v_mfma_f32_16x16x32_bf16 v[42:45], v[174:177], v[182:185], v[42:45]
	v_mfma_f32_16x16x32_bf16 v[38:41], v[166:169], v[190:193], v[38:41]
	v_mfma_f32_16x16x32_bf16 v[34:37], v[174:177], v[190:193], v[34:37]
	v_mfma_f32_16x16x32_bf16 v[18:21], v[166:169], v[198:201], v[18:21]
	v_mfma_f32_16x16x32_bf16 v[14:17], v[174:177], v[198:201], v[14:17]
	v_mfma_f32_16x16x32_bf16 v[6:9], v[166:169], v[206:209], v[6:9]
	v_mfma_f32_16x16x32_bf16 v[2:5], v[174:177], v[206:209], v[2:5]
	v_mfma_f32_16x16x32_bf16 v[46:49], v[170:173], v[186:189], v[46:49]
	v_mfma_f32_16x16x32_bf16 v[42:45], v[178:181], v[186:189], v[42:45]
	v_mfma_f32_16x16x32_bf16 v[38:41], v[170:173], v[194:197], v[38:41]
	v_mfma_f32_16x16x32_bf16 v[34:37], v[178:181], v[194:197], v[34:37]
	v_mfma_f32_16x16x32_bf16 v[18:21], v[170:173], v[202:205], v[18:21]
	v_mfma_f32_16x16x32_bf16 v[14:17], v[178:181], v[202:205], v[14:17]
	v_mfma_f32_16x16x32_bf16 v[6:9], v[170:173], v[210:213], v[6:9]
	v_mfma_f32_16x16x32_bf16 v[2:5], v[178:181], v[210:213], v[2:5]
	s_barrier
	s_add_i32 s50, 0, 0x18000
	v_add_u32_e32 v157, s50, v1
	s_add_i32 s51, 0, 0x1c000
	ds_read_b128 v[146:149], v157
	ds_read_b128 v[150:153], v157 offset:1024
	ds_read_b128 v[158:161], v157 offset:2048
	ds_read_b128 v[162:165], v157 offset:3072
	v_add_u32_e32 v157, s51, v1
	ds_read_b128 v[166:169], v157
	ds_read_b128 v[170:173], v157 offset:1024
	ds_read_b128 v[174:177], v157 offset:2048
	ds_read_b128 v[178:181], v157 offset:3072
	s_add_u32 s26, s26, 0x20000
	s_addc_u32 s27, s27, 0
	s_mov_b32 m0, s36
	v_lshl_add_u64 v[222:223], s[26:27], 0, v[130:131]
	ds_read_b128 v[182:185], v156 offset:32768
	ds_read_b128 v[186:189], v156 offset:33792
	ds_read_b128 v[190:193], v156 offset:34816
	ds_read_b128 v[194:197], v156 offset:35840
	ds_read_b128 v[198:201], v156 offset:36864
	ds_read_b128 v[202:205], v156 offset:37888
	ds_read_b128 v[206:209], v156 offset:38912
	ds_read_b128 v[210:213], v156 offset:39936
	global_load_lds_dwordx4 v[222:223], off
	v_lshl_add_u64 v[222:223], s[26:27], 0, v[134:135]
	s_mov_b32 m0, s37
	s_nop 0
	global_load_lds_dwordx4 v[222:223], off
	s_waitcnt vmcnt(8)
	s_waitcnt lgkmcnt(0)
	s_barrier
	s_waitcnt lgkmcnt(0)
	v_mfma_f32_16x16x32_bf16 v[126:129], v[146:149], v[182:185], v[126:129]
	v_mfma_f32_16x16x32_bf16 v[122:125], v[158:161], v[182:185], v[122:125]
	v_mfma_f32_16x16x32_bf16 v[114:117], v[146:149], v[190:193], v[114:117]
	v_mfma_f32_16x16x32_bf16 v[106:109], v[158:161], v[190:193], v[106:109]
	v_mfma_f32_16x16x32_bf16 v[94:97], v[146:149], v[198:201], v[94:97]
	v_mfma_f32_16x16x32_bf16 v[90:93], v[158:161], v[198:201], v[90:93]
	v_mfma_f32_16x16x32_bf16 v[86:89], v[146:149], v[206:209], v[86:89]
	v_mfma_f32_16x16x32_bf16 v[82:85], v[158:161], v[206:209], v[82:85]
	v_mfma_f32_16x16x32_bf16 v[126:129], v[150:153], v[186:189], v[126:129]
	v_mfma_f32_16x16x32_bf16 v[122:125], v[162:165], v[186:189], v[122:125]
	v_mfma_f32_16x16x32_bf16 v[114:117], v[150:153], v[194:197], v[114:117]
	v_mfma_f32_16x16x32_bf16 v[106:109], v[162:165], v[194:197], v[106:109]
	v_mfma_f32_16x16x32_bf16 v[94:97], v[150:153], v[202:205], v[94:97]
	v_mfma_f32_16x16x32_bf16 v[90:93], v[162:165], v[202:205], v[90:93]
	v_mfma_f32_16x16x32_bf16 v[86:89], v[150:153], v[210:213], v[86:89]
	v_mfma_f32_16x16x32_bf16 v[82:85], v[162:165], v[210:213], v[82:85]
	v_mfma_f32_16x16x32_bf16 v[118:121], v[166:169], v[182:185], v[118:121]
	v_mfma_f32_16x16x32_bf16 v[110:113], v[174:177], v[182:185], v[110:113]
	v_mfma_f32_16x16x32_bf16 v[102:105], v[166:169], v[190:193], v[102:105]
	v_mfma_f32_16x16x32_bf16 v[98:101], v[174:177], v[190:193], v[98:101]
	v_mfma_f32_16x16x32_bf16 v[78:81], v[166:169], v[198:201], v[78:81]
	v_mfma_f32_16x16x32_bf16 v[74:77], v[174:177], v[198:201], v[74:77]
	v_mfma_f32_16x16x32_bf16 v[70:73], v[166:169], v[206:209], v[70:73]
	v_mfma_f32_16x16x32_bf16 v[66:69], v[174:177], v[206:209], v[66:69]
	v_mfma_f32_16x16x32_bf16 v[118:121], v[170:173], v[186:189], v[118:121]
	v_mfma_f32_16x16x32_bf16 v[110:113], v[178:181], v[186:189], v[110:113]
	v_mfma_f32_16x16x32_bf16 v[102:105], v[170:173], v[194:197], v[102:105]
	v_mfma_f32_16x16x32_bf16 v[98:101], v[178:181], v[194:197], v[98:101]
	v_mfma_f32_16x16x32_bf16 v[78:81], v[170:173], v[202:205], v[78:81]
	v_mfma_f32_16x16x32_bf16 v[74:77], v[178:181], v[202:205], v[74:77]
	v_mfma_f32_16x16x32_bf16 v[70:73], v[170:173], v[210:213], v[70:73]
	v_mfma_f32_16x16x32_bf16 v[66:69], v[178:181], v[210:213], v[66:69]
	s_barrier
; #define PG8_STAGE(bufoff, gbase, voff) do { _Pragma("unroll") for (int _i = 0; _i < 2; ++_i) \
;         __builtin_amdgcn_global_load_lds((const unsigned*)((const char*)(gbase) + (voff)[_i]), (PG8_LAS unsigned*)(lds + (bufoff) + ldsw + _i * 8192), 16, 0, 0); } while (0)
; #define PG8_LDA(dst, b, h) do { _Pragma("unroll") for (int m = 0; m < 4; ++m) _Pragma("unroll") for (int k = 0; k < 2; ++k) dst[m][k] = *(const PG8_LAS bf16x8*)(lds + PG8_SA(b, h) + aoff + m * 2048 + k * 1024); } while (0)
; #define PG8_MMA(ai, bj, At, Bt) do { __builtin_amdgcn_s_setprio(1); _Pragma("unroll") for (int m = 0; m < 4; ++m) _Pragma("unroll") for (int n = 0; n < 2; ++n) _Pragma("unroll") for (int k = 0; k < 2; ++k) \
;         acc[ai][bj][m][n] = mma_<I8>(Bt[n][k], At[m][k], acc[ai][bj][m][n]); __builtin_amdgcn_s_setprio(0); } while (0)
; #define PG8_WAIT_V(n) asm volatile("s_waitcnt vmcnt(" #n ")" ::: "memory")
; #define PG8_WAIT_L(n) asm volatile("s_waitcnt lgkmcnt(" #n ")" ::: "memory")
; #define PG8_BAR __builtin_amdgcn_s_barrier()
; #define PG8_SCHED __builtin_amdgcn_sched_barrier(0)
; template <class Epi, class Sched, bool ALIGN_EPI = false, bool SP2 = false, bool I8 = false>
; __device__ __forceinline__ void gemm_phase(PG8_LAS unsigned char* lds, const Gemm g, const Sched& S, const Epi& E) {
;     ...
;         for (int t = 0; t < nt; t += 2) {
;             const bool last = (t == nt - 2);
;             const char* a1 = cA + (size_t)(t + 1) * kstep;
;             const char* a2 = last ? nA : cA + (size_t)(t + 2) * kstep; const char* b2 = last ? nB : cB + (size_t)(t + 2) * kstep;
;     ...
;             PG8_LDA(At, 1, 1); PG8_STAGE(PG8_SB(1, 0), b3, voffB); PG8_STAGE(PG8_SB(1, 1), b3 + hstepB, voffB); PG8_STAGE(PG8_SA(1, 0), a3, voffA);
;             PG8_WAIT_V(8); PG8_WAIT_L(0); PG8_BAR; PG8_MMA(1, 0, At, B0); PG8_MMA(1, 1, At, B1); PG8_BAR; PG8_SCHED;
	s_add_i32 s26, s50, s34
	v_lshl_add_u64 v[214:215], v[214:215], 0, s[8:9]
	s_mov_b32 m0, s26
	ds_read_b128 v[182:185], v156 offset:49152
	ds_read_b128 v[186:189], v156 offset:50176
	ds_read_b128 v[190:193], v156 offset:51200
	ds_read_b128 v[194:197], v156 offset:52224
	ds_read_b128 v[198:201], v156 offset:53248
	ds_read_b128 v[202:205], v156 offset:54272
	ds_read_b128 v[206:209], v156 offset:55296
	ds_read_b128 v[210:213], v156 offset:56320
	global_load_lds_dwordx4 v[214:215], off
	s_add_i32 m0, s26, 0x2000
	s_add_u32 s24, s24, 0x20080
	v_lshl_add_u64 v[214:215], v[216:217], 0, s[8:9]
	s_addc_u32 s25, s25, 0
	s_add_i32 s26, s51, s34
	global_load_lds_dwordx4 v[214:215], off
	v_lshl_add_u64 v[214:215], s[24:25], 0, v[132:133]
	s_mov_b32 m0, s26
	s_nop 0
	global_load_lds_dwordx4 v[214:215], off
	v_lshl_add_u64 v[214:215], s[24:25], 0, v[136:137]
	s_add_i32 m0, s26, 0x2000
	s_nop 0
	global_load_lds_dwordx4 v[214:215], off
	v_lshl_add_u64 v[214:215], v[218:219], 0, s[8:9]
	s_mov_b32 m0, s39
	s_nop 0
	global_load_lds_dwordx4 v[214:215], off
	v_lshl_add_u64 v[214:215], v[220:221], 0, s[8:9]
	s_mov_b32 m0, s40
	s_nop 0
	global_load_lds_dwordx4 v[214:215], off
	s_waitcnt vmcnt(8)
	s_waitcnt lgkmcnt(0)
	s_barrier
	s_waitcnt lgkmcnt(0)
	v_mfma_f32_16x16x32_bf16 v[62:65], v[146:149], v[182:185], v[62:65]
	v_mfma_f32_16x16x32_bf16 v[58:61], v[158:161], v[182:185], v[58:61]
	v_mfma_f32_16x16x32_bf16 v[54:57], v[146:149], v[190:193], v[54:57]
	v_mfma_f32_16x16x32_bf16 v[50:53], v[158:161], v[190:193], v[50:53]
	v_mfma_f32_16x16x32_bf16 v[30:33], v[146:149], v[198:201], v[30:33]
	v_mfma_f32_16x16x32_bf16 v[26:29], v[158:161], v[198:201], v[26:29]
	v_mfma_f32_16x16x32_bf16 v[22:25], v[146:149], v[206:209], v[22:25]
	v_mfma_f32_16x16x32_bf16 v[10:13], v[158:161], v[206:209], v[10:13]
	v_mfma_f32_16x16x32_bf16 v[62:65], v[150:153], v[186:189], v[62:65]
	v_mfma_f32_16x16x32_bf16 v[58:61], v[162:165], v[186:189], v[58:61]
	v_mfma_f32_16x16x32_bf16 v[54:57], v[150:153], v[194:197], v[54:57]
	v_mfma_f32_16x16x32_bf16 v[50:53], v[162:165], v[194:197], v[50:53]
	v_mfma_f32_16x16x32_bf16 v[30:33], v[150:153], v[202:205], v[30:33]
	v_mfma_f32_16x16x32_bf16 v[26:29], v[162:165], v[202:205], v[26:29]
	v_mfma_f32_16x16x32_bf16 v[22:25], v[150:153], v[210:213], v[22:25]
	v_mfma_f32_16x16x32_bf16 v[10:13], v[162:165], v[210:213], v[10:13]
	v_mfma_f32_16x16x32_bf16 v[46:49], v[166:169], v[182:185], v[46:49]
	v_mfma_f32_16x16x32_bf16 v[42:45], v[174:177], v[182:185], v[42:45]
	v_mfma_f32_16x16x32_bf16 v[38:41], v[166:169], v[190:193], v[38:41]
	v_mfma_f32_16x16x32_bf16 v[34:37], v[174:177], v[190:193], v[34:37]
	v_mfma_f32_16x16x32_bf16 v[18:21], v[166:169], v[198:201], v[18:21]
	v_mfma_f32_16x16x32_bf16 v[14:17], v[174:177], v[198:201], v[14:17]
	v_mfma_f32_16x16x32_bf16 v[6:9], v[166:169], v[206:209], v[6:9]
	v_mfma_f32_16x16x32_bf16 v[2:5], v[174:177], v[206:209], v[2:5]
	v_mfma_f32_16x16x32_bf16 v[46:49], v[170:173], v[186:189], v[46:49]
	v_mfma_f32_16x16x32_bf16 v[42:45], v[178:181], v[186:189], v[42:45]
	v_mfma_f32_16x16x32_bf16 v[38:41], v[170:173], v[194:197], v[38:41]
	v_mfma_f32_16x16x32_bf16 v[34:37], v[178:181], v[194:197], v[34:37]
	v_mfma_f32_16x16x32_bf16 v[18:21], v[170:173], v[202:205], v[18:21]
	v_mfma_f32_16x16x32_bf16 v[14:17], v[178:181], v[202:205], v[14:17]
	v_mfma_f32_16x16x32_bf16 v[6:9], v[170:173], v[210:213], v[6:9]
	v_mfma_f32_16x16x32_bf16 v[2:5], v[178:181], v[210:213], v[2:5]
	s_barrier
	s_add_i32 s49, s49, 2
	s_add_u32 s22, s22, 0x100
	s_addc_u32 s23, s23, 0
	s_add_u32 s47, s47, 0x100
	s_addc_u32 s48, s48, 0
	s_cmp_gt_u32 s49, 5
	s_cbranch_scc0 .LBB0_1538
	s_and_b64 vcc, exec, s[10:11]
	s_cbranch_vccz .LBB0_1541
	s_barrier

; #define PG8_STAGE(bufoff, gbase, voff) do { _Pragma("unroll") for (int _i = 0; _i < 2; ++_i) \
;         __builtin_amdgcn_global_load_lds((const unsigned*)((const char*)(gbase) + (voff)[_i]), (PG8_LAS unsigned*)(lds + (bufoff) + ldsw + _i * 8192), 16, 0, 0); } while (0)
; #define PG8_LDA(dst, b, h) do { _Pragma("unroll") for (int m = 0; m < 4; ++m) _Pragma("unroll") for (int k = 0; k < 2; ++k) dst[m][k] = *(const PG8_LAS bf16x8*)(lds + PG8_SA(b, h) + aoff + m * 2048 + k * 1024); } while (0)
; #define PG8_LDB(dst, b, h) do { _Pragma("unroll") for (int n = 0; n < 2; ++n) _Pragma("unroll") for (int k = 0; k < 2; ++k) dst[n][k] = *(const PG8_LAS bf16x8*)(lds + PG8_SB(b, h) + boff + n * 2048 + k * 1024); } while (0)
; #define PG8_MMA(ai, bj, At, Bt) do { __builtin_amdgcn_s_setprio(1); _Pragma("unroll") for (int m = 0; m < 4; ++m) _Pragma("unroll") for (int n = 0; n < 2; ++n) _Pragma("unroll") for (int k = 0; k < 2; ++k) \
;         acc[ai][bj][m][n] = mma_<I8>(Bt[n][k], At[m][k], acc[ai][bj][m][n]); __builtin_amdgcn_s_setprio(0); } while (0)
; #define PG8_WAIT_V(n) asm volatile("s_waitcnt vmcnt(" #n ")" ::: "memory")
; #define PG8_WAIT_L(n) asm volatile("s_waitcnt lgkmcnt(" #n ")" ::: "memory")
; #define PG8_BAR __builtin_amdgcn_s_barrier()
; #define PG8_SCHED __builtin_amdgcn_sched_barrier(0)
; template <class Epi, class Sched, bool ALIGN_EPI = false, bool SP2 = false, bool I8 = false>
; __device__ __forceinline__ void gemm_phase(PG8_LAS unsigned char* lds, const Gemm g, const Sched& S, const Epi& E) {
;     ...
;         for (int t = 0; t < nt; t += 2) {
;             const bool last = (t == nt - 2);
;             const char* a1 = cA + (size_t)(t + 1) * kstep;
;             const char* a2 = last ? nA : cA + (size_t)(t + 2) * kstep; const char* b2 = last ? nB : cB + (size_t)(t + 2) * kstep;
;             const char* a3 = a2 + kstep; const char* b3 = b2 + kstep;
;             if (last && has_next) S.a_ready(nxt);
;             if constexpr (SP2) {
;             PG8_LDB(B0, 0, 0); PG8_LDB(B1, 0, 1); PG8_SCHED; PG8_LDA(At, 0, 0); PG8_STAGE(PG8_SA(1, 1), a1 + hstepA, voffA);
;             PG8_WAIT_V(8); PG8_WAIT_L(0); PG8_BAR; PG8_MMA(0, 0, At, B0); PG8_MMA(0, 1, At, B1); PG8_BAR; PG8_SCHED;
;             PG8_LDA(At, 0, 1); PG8_STAGE(PG8_SB(0, 0), b2, voffB); PG8_STAGE(PG8_SB(0, 1), b2 + hstepB, voffB); PG8_STAGE(PG8_SA(0, 0), a2, voffA);
.LBB0_1565:
	ds_read_b128 v[130:133], v176
	ds_read_b128 v[134:137], v176 offset:1024
	ds_read_b128 v[138:141], v176 offset:2048
	ds_read_b128 v[142:145], v176 offset:3072
	ds_read_b128 v[162:165], v177
	ds_read_b128 v[166:169], v177 offset:1024
	ds_read_b128 v[170:173], v177 offset:2048
	ds_read_b128 v[180:183], v177 offset:3072
	s_add_u32 s30, s28, 0xfff80080
	s_addc_u32 s31, s29, -1
	s_cmp_eq_u32 s54, 28
	s_cselect_b32 s35, s7, s31
	s_cselect_b32 s34, s21, s30
	s_cselect_b32 s31, s19, s53
	s_cselect_b32 s30, s27, s52
	v_lshl_add_u64 v[174:175], s[28:29], 0, v[154:155]
	s_add_i32 m0, s40, 0xc000
	ds_read_b128 v[184:187], v178
	ds_read_b128 v[188:191], v178 offset:1024
	ds_read_b128 v[192:195], v178 offset:2048
	ds_read_b128 v[196:199], v178 offset:3072
	ds_read_b128 v[200:203], v178 offset:4096
	ds_read_b128 v[204:207], v178 offset:5120
	ds_read_b128 v[208:211], v178 offset:6144
	ds_read_b128 v[212:215], v178 offset:7168
	global_load_lds_dwordx4 v[174:175], off
	v_lshl_add_u64 v[174:175], s[28:29], 0, v[156:157]
	s_add_i32 m0, s40, 0xe000
	s_nop 0
	global_load_lds_dwordx4 v[174:175], off
	s_waitcnt vmcnt(8)
	s_waitcnt lgkmcnt(0)
	s_barrier
	s_waitcnt lgkmcnt(0)
	v_mfma_f32_16x16x32_bf16 v[126:129], v[130:133], v[184:187], v[126:129]
	v_mfma_f32_16x16x32_bf16 v[122:125], v[138:141], v[184:187], v[122:125]
	v_mfma_f32_16x16x32_bf16 v[110:113], v[130:133], v[192:195], v[110:113]
	v_mfma_f32_16x16x32_bf16 v[106:109], v[138:141], v[192:195], v[106:109]
	v_mfma_f32_16x16x32_bf16 v[94:97], v[130:133], v[200:203], v[94:97]
	v_mfma_f32_16x16x32_bf16 v[90:93], v[138:141], v[200:203], v[90:93]
	v_mfma_f32_16x16x32_bf16 v[78:81], v[130:133], v[208:211], v[78:81]
	v_mfma_f32_16x16x32_bf16 v[74:77], v[138:141], v[208:211], v[74:77]
	v_mfma_f32_16x16x32_bf16 v[126:129], v[134:137], v[188:191], v[126:129]
	v_mfma_f32_16x16x32_bf16 v[122:125], v[142:145], v[188:191], v[122:125]
	v_mfma_f32_16x16x32_bf16 v[110:113], v[134:137], v[196:199], v[110:113]
	v_mfma_f32_16x16x32_bf16 v[106:109], v[142:145], v[196:199], v[106:109]
	v_mfma_f32_16x16x32_bf16 v[94:97], v[134:137], v[204:207], v[94:97]
	v_mfma_f32_16x16x32_bf16 v[90:93], v[142:145], v[204:207], v[90:93]
	v_mfma_f32_16x16x32_bf16 v[78:81], v[134:137], v[212:215], v[78:81]
	v_mfma_f32_16x16x32_bf16 v[74:77], v[142:145], v[212:215], v[74:77]
	v_mfma_f32_16x16x32_bf16 v[118:121], v[162:165], v[184:187], v[118:121]
	v_mfma_f32_16x16x32_bf16 v[114:117], v[170:173], v[184:187], v[114:117]
	v_mfma_f32_16x16x32_bf16 v[102:105], v[162:165], v[192:195], v[102:105]
	v_mfma_f32_16x16x32_bf16 v[98:101], v[170:173], v[192:195], v[98:101]
	v_mfma_f32_16x16x32_bf16 v[86:89], v[162:165], v[200:203], v[86:89]
	v_mfma_f32_16x16x32_bf16 v[82:85], v[170:173], v[200:203], v[82:85]
	v_mfma_f32_16x16x32_bf16 v[70:73], v[162:165], v[208:211], v[70:73]
	v_mfma_f32_16x16x32_bf16 v[66:69], v[170:173], v[208:211], v[66:69]
	v_mfma_f32_16x16x32_bf16 v[118:121], v[166:169], v[188:191], v[118:121]
	v_mfma_f32_16x16x32_bf16 v[114:117], v[180:183], v[188:191], v[114:117]
	v_mfma_f32_16x16x32_bf16 v[102:105], v[166:169], v[196:199], v[102:105]
	v_mfma_f32_16x16x32_bf16 v[98:101], v[180:183], v[196:199], v[98:101]
	v_mfma_f32_16x16x32_bf16 v[86:89], v[166:169], v[204:207], v[86:89]
	v_mfma_f32_16x16x32_bf16 v[82:85], v[180:183], v[204:207], v[82:85]
	v_mfma_f32_16x16x32_bf16 v[70:73], v[166:169], v[212:215], v[70:73]
	v_mfma_f32_16x16x32_bf16 v[66:69], v[180:183], v[212:215], v[66:69]
	s_barrier
	s_add_i32 s55, s50, s39
	v_lshl_add_u64 v[174:175], s[30:31], 0, v[148:149]
	s_mov_b32 m0, s55
	ds_read_b128 v[184:187], v178 offset:16384
	ds_read_b128 v[188:191], v178 offset:17408
	ds_read_b128 v[192:195], v178 offset:18432
	ds_read_b128 v[196:199], v178 offset:19456
	ds_read_b128 v[200:203], v178 offset:20480
	ds_read_b128 v[204:207], v178 offset:21504
	ds_read_b128 v[208:211], v178 offset:22528
	ds_read_b128 v[212:215], v178 offset:23552
	global_load_lds_dwordx4 v[174:175], off
	s_add_i32 m0, s55, 0x2000
	s_add_u32 s56, s30, 0x80000
	v_lshl_add_u64 v[216:217], s[30:31], 0, v[152:153]
	s_addc_u32 s57, s31, 0
	s_add_i32 s55, s51, s39
	global_load_lds_dwordx4 v[216:217], off
	v_lshl_add_u64 v[218:219], s[56:57], 0, v[148:149]
	s_mov_b32 m0, s55
	v_lshl_add_u64 v[220:221], s[34:35], 0, v[150:151]
	global_load_lds_dwordx4 v[218:219], off
	v_lshl_add_u64 v[218:219], s[56:57], 0, v[152:153]
	s_add_i32 m0, s55, 0x2000
	s_nop 0
	global_load_lds_dwordx4 v[218:219], off
	v_lshl_add_u64 v[218:219], s[34:35], 0, v[146:147]
	s_mov_b32 m0, s40
	s_nop 0
	global_load_lds_dwordx4 v[218:219], off
	s_mov_b32 m0, s41
	s_nop 0
	global_load_lds_dwordx4 v[220:221], off
	s_waitcnt vmcnt(8)
	s_waitcnt lgkmcnt(0)
	s_barrier
; #define PG8_STAGE(bufoff, gbase, voff) do { _Pragma("unroll") for (int _i = 0; _i < 2; ++_i) \
;         __builtin_amdgcn_global_load_lds((const unsigned*)((const char*)(gbase) + (voff)[_i]), (PG8_LAS unsigned*)(lds + (bufoff) + ldsw + _i * 8192), 16, 0, 0); } while (0)
; #define PG8_LDA(dst, b, h) do { _Pragma("unroll") for (int m = 0; m < 4; ++m) _Pragma("unroll") for (int k = 0; k < 2; ++k) dst[m][k] = *(const PG8_LAS bf16x8*)(lds + PG8_SA(b, h) + aoff + m * 2048 + k * 1024); } while (0)
; #define PG8_LDB(dst, b, h) do { _Pragma("unroll") for (int n = 0; n < 2; ++n) _Pragma("unroll") for (int k = 0; k < 2; ++k) dst[n][k] = *(const PG8_LAS bf16x8*)(lds + PG8_SB(b, h) + boff + n * 2048 + k * 1024); } while (0)
; #define PG8_MMA(ai, bj, At, Bt) do { __builtin_amdgcn_s_setprio(1); _Pragma("unroll") for (int m = 0; m < 4; ++m) _Pragma("unroll") for (int n = 0; n < 2; ++n) _Pragma("unroll") for (int k = 0; k < 2; ++k) \
;         acc[ai][bj][m][n] = mma_<I8>(Bt[n][k], At[m][k], acc[ai][bj][m][n]); __builtin_amdgcn_s_setprio(0); } while (0)
; #define PG8_WAIT_V(n) asm volatile("s_waitcnt vmcnt(" #n ")" ::: "memory")
; #define PG8_WAIT_L(n) asm volatile("s_waitcnt lgkmcnt(" #n ")" ::: "memory")
; #define PG8_BAR __builtin_amdgcn_s_barrier()
; #define PG8_SCHED __builtin_amdgcn_sched_barrier(0)
; template <class Epi, class Sched, bool ALIGN_EPI = false, bool SP2 = false, bool I8 = false>
; __device__ __forceinline__ void gemm_phase(PG8_LAS unsigned char* lds, const Gemm g, const Sched& S, const Epi& E) {
;     ...
;             PG8_WAIT_V(8); PG8_WAIT_L(0); PG8_BAR; PG8_MMA(1, 0, At, B0); PG8_MMA(1, 1, At, B1); PG8_BAR; PG8_SCHED;
;             PG8_LDB(B0, 1, 0); PG8_LDB(B1, 1, 1); PG8_SCHED; PG8_LDA(At, 1, 0); PG8_STAGE(PG8_SA(0, 1), a2 + hstepA, voffA);
;             PG8_WAIT_V(8); PG8_WAIT_L(0); PG8_BAR; PG8_MMA(0, 0, At, B0); PG8_MMA(0, 1, At, B1); PG8_BAR; PG8_SCHED;
	s_waitcnt lgkmcnt(0)
	v_mfma_f32_16x16x32_bf16 v[62:65], v[130:133], v[184:187], v[62:65]
	v_mfma_f32_16x16x32_bf16 v[58:61], v[138:141], v[184:187], v[58:61]
	v_mfma_f32_16x16x32_bf16 v[46:49], v[130:133], v[192:195], v[46:49]
	v_mfma_f32_16x16x32_bf16 v[42:45], v[138:141], v[192:195], v[42:45]
	v_mfma_f32_16x16x32_bf16 v[30:33], v[130:133], v[200:203], v[30:33]
	v_mfma_f32_16x16x32_bf16 v[26:29], v[138:141], v[200:203], v[26:29]
	v_mfma_f32_16x16x32_bf16 v[14:17], v[130:133], v[208:211], v[14:17]
	v_mfma_f32_16x16x32_bf16 v[10:13], v[138:141], v[208:211], v[10:13]
	v_mfma_f32_16x16x32_bf16 v[62:65], v[134:137], v[188:191], v[62:65]
	v_mfma_f32_16x16x32_bf16 v[58:61], v[142:145], v[188:191], v[58:61]
	v_mfma_f32_16x16x32_bf16 v[46:49], v[134:137], v[196:199], v[46:49]
	v_mfma_f32_16x16x32_bf16 v[42:45], v[142:145], v[196:199], v[42:45]
	v_mfma_f32_16x16x32_bf16 v[30:33], v[134:137], v[204:207], v[30:33]
	v_mfma_f32_16x16x32_bf16 v[26:29], v[142:145], v[204:207], v[26:29]
	v_mfma_f32_16x16x32_bf16 v[14:17], v[134:137], v[212:215], v[14:17]
	v_mfma_f32_16x16x32_bf16 v[10:13], v[142:145], v[212:215], v[10:13]
	v_mfma_f32_16x16x32_bf16 v[54:57], v[162:165], v[184:187], v[54:57]
	v_mfma_f32_16x16x32_bf16 v[50:53], v[170:173], v[184:187], v[50:53]
	v_mfma_f32_16x16x32_bf16 v[38:41], v[162:165], v[192:195], v[38:41]
	v_mfma_f32_16x16x32_bf16 v[34:37], v[170:173], v[192:195], v[34:37]
	v_mfma_f32_16x16x32_bf16 v[22:25], v[162:165], v[200:203], v[22:25]
	v_mfma_f32_16x16x32_bf16 v[18:21], v[170:173], v[200:203], v[18:21]
	v_mfma_f32_16x16x32_bf16 v[6:9], v[162:165], v[208:211], v[6:9]
	v_mfma_f32_16x16x32_bf16 v[2:5], v[170:173], v[208:211], v[2:5]
	v_mfma_f32_16x16x32_bf16 v[54:57], v[166:169], v[188:191], v[54:57]
	v_mfma_f32_16x16x32_bf16 v[50:53], v[180:183], v[188:191], v[50:53]
	v_mfma_f32_16x16x32_bf16 v[38:41], v[166:169], v[196:199], v[38:41]
	v_mfma_f32_16x16x32_bf16 v[34:37], v[180:183], v[196:199], v[34:37]
	v_mfma_f32_16x16x32_bf16 v[22:25], v[166:169], v[204:207], v[22:25]
	v_mfma_f32_16x16x32_bf16 v[18:21], v[180:183], v[204:207], v[18:21]
	v_mfma_f32_16x16x32_bf16 v[6:9], v[166:169], v[212:215], v[6:9]
	v_mfma_f32_16x16x32_bf16 v[2:5], v[180:183], v[212:215], v[2:5]
	s_barrier
	s_add_i32 s55, 0, 0x18000
	s_add_i32 s56, 0, 0x1c000
	v_add_u32_e32 v142, s55, v1
	v_add_u32_e32 v180, s56, v1
	ds_read_b128 v[130:133], v142
	ds_read_b128 v[134:137], v142 offset:1024
	ds_read_b128 v[138:141], v142 offset:2048
	ds_read_b128 v[142:145], v142 offset:3072
	ds_read_b128 v[162:165], v180
	ds_read_b128 v[166:169], v180 offset:1024
	ds_read_b128 v[170:173], v180 offset:2048
	ds_read_b128 v[180:183], v180 offset:3072
	s_add_u32 s34, s34, 0x80000
	s_addc_u32 s35, s35, 0
	s_mov_b32 m0, s42
	v_lshl_add_u64 v[222:223], s[34:35], 0, v[146:147]
	ds_read_b128 v[184:187], v178 offset:32768
	ds_read_b128 v[188:191], v178 offset:33792
	ds_read_b128 v[192:195], v178 offset:34816
	ds_read_b128 v[196:199], v178 offset:35840
	ds_read_b128 v[200:203], v178 offset:36864
	ds_read_b128 v[204:207], v178 offset:37888
	ds_read_b128 v[208:211], v178 offset:38912
	ds_read_b128 v[212:215], v178 offset:39936
	global_load_lds_dwordx4 v[222:223], off
	v_lshl_add_u64 v[222:223], s[34:35], 0, v[150:151]
	s_mov_b32 m0, s43
	s_nop 0
	global_load_lds_dwordx4 v[222:223], off
	s_waitcnt vmcnt(8)
	s_waitcnt lgkmcnt(0)
	s_barrier
	s_waitcnt lgkmcnt(0)
	v_mfma_f32_16x16x32_bf16 v[126:129], v[130:133], v[184:187], v[126:129]
	v_mfma_f32_16x16x32_bf16 v[122:125], v[138:141], v[184:187], v[122:125]
	v_mfma_f32_16x16x32_bf16 v[110:113], v[130:133], v[192:195], v[110:113]
	v_mfma_f32_16x16x32_bf16 v[106:109], v[138:141], v[192:195], v[106:109]
	v_mfma_f32_16x16x32_bf16 v[94:97], v[130:133], v[200:203], v[94:97]
	v_mfma_f32_16x16x32_bf16 v[90:93], v[138:141], v[200:203], v[90:93]
	v_mfma_f32_16x16x32_bf16 v[78:81], v[130:133], v[208:211], v[78:81]
	v_mfma_f32_16x16x32_bf16 v[74:77], v[138:141], v[208:211], v[74:77]
	v_mfma_f32_16x16x32_bf16 v[126:129], v[134:137], v[188:191], v[126:129]
	v_mfma_f32_16x16x32_bf16 v[122:125], v[142:145], v[188:191], v[122:125]
	v_mfma_f32_16x16x32_bf16 v[110:113], v[134:137], v[196:199], v[110:113]
	v_mfma_f32_16x16x32_bf16 v[106:109], v[142:145], v[196:199], v[106:109]
	v_mfma_f32_16x16x32_bf16 v[94:97], v[134:137], v[204:207], v[94:97]
	v_mfma_f32_16x16x32_bf16 v[90:93], v[142:145], v[204:207], v[90:93]
	v_mfma_f32_16x16x32_bf16 v[78:81], v[134:137], v[212:215], v[78:81]
	v_mfma_f32_16x16x32_bf16 v[74:77], v[142:145], v[212:215], v[74:77]
	v_mfma_f32_16x16x32_bf16 v[118:121], v[162:165], v[184:187], v[118:121]
	v_mfma_f32_16x16x32_bf16 v[114:117], v[170:173], v[184:187], v[114:117]
	v_mfma_f32_16x16x32_bf16 v[102:105], v[162:165], v[192:195], v[102:105]
	v_mfma_f32_16x16x32_bf16 v[98:101], v[170:173], v[192:195], v[98:101]
	v_mfma_f32_16x16x32_bf16 v[86:89], v[162:165], v[200:203], v[86:89]
	v_mfma_f32_16x16x32_bf16 v[82:85], v[170:173], v[200:203], v[82:85]
	v_mfma_f32_16x16x32_bf16 v[70:73], v[162:165], v[208:211], v[70:73]
	v_mfma_f32_16x16x32_bf16 v[66:69], v[170:173], v[208:211], v[66:69]
	v_mfma_f32_16x16x32_bf16 v[118:121], v[166:169], v[188:191], v[118:121]
	v_mfma_f32_16x16x32_bf16 v[114:117], v[180:183], v[188:191], v[114:117]
	v_mfma_f32_16x16x32_bf16 v[102:105], v[166:169], v[196:199], v[102:105]
	v_mfma_f32_16x16x32_bf16 v[98:101], v[180:183], v[196:199], v[98:101]
	v_mfma_f32_16x16x32_bf16 v[86:89], v[166:169], v[204:207], v[86:89]
	v_mfma_f32_16x16x32_bf16 v[82:85], v[180:183], v[204:207], v[82:85]
	v_mfma_f32_16x16x32_bf16 v[70:73], v[166:169], v[212:215], v[70:73]
	v_mfma_f32_16x16x32_bf16 v[66:69], v[180:183], v[212:215], v[66:69]
	s_barrier
; #define PG8_STAGE(bufoff, gbase, voff) do { _Pragma("unroll") for (int _i = 0; _i < 2; ++_i) \
;         __builtin_amdgcn_global_load_lds((const unsigned*)((const char*)(gbase) + (voff)[_i]), (PG8_LAS unsigned*)(lds + (bufoff) + ldsw + _i * 8192), 16, 0, 0); } while (0)
; #define PG8_LDA(dst, b, h) do { _Pragma("unroll") for (int m = 0; m < 4; ++m) _Pragma("unroll") for (int k = 0; k < 2; ++k) dst[m][k] = *(const PG8_LAS bf16x8*)(lds + PG8_SA(b, h) + aoff + m * 2048 + k * 1024); } while (0)
; #define PG8_MMA(ai, bj, At, Bt) do { __builtin_amdgcn_s_setprio(1); _Pragma("unroll") for (int m = 0; m < 4; ++m) _Pragma("unroll") for (int n = 0; n < 2; ++n) _Pragma("unroll") for (int k = 0; k < 2; ++k) \
;         acc[ai][bj][m][n] = mma_<I8>(Bt[n][k], At[m][k], acc[ai][bj][m][n]); __builtin_amdgcn_s_setprio(0); } while (0)
; #define PG8_WAIT_V(n) asm volatile("s_waitcnt vmcnt(" #n ")" ::: "memory")
; #define PG8_WAIT_L(n) asm volatile("s_waitcnt lgkmcnt(" #n ")" ::: "memory")
; #define PG8_BAR __builtin_amdgcn_s_barrier()
; #define PG8_SCHED __builtin_amdgcn_sched_barrier(0)
; template <class Epi, class Sched, bool ALIGN_EPI = false, bool SP2 = false, bool I8 = false>
; __device__ __forceinline__ void gemm_phase(PG8_LAS unsigned char* lds, const Gemm g, const Sched& S, const Epi& E) {
;     ...
;         for (int t = 0; t < nt; t += 2) {
;             const bool last = (t == nt - 2);
;             const char* a1 = cA + (size_t)(t + 1) * kstep;
;             const char* a2 = last ? nA : cA + (size_t)(t + 2) * kstep; const char* b2 = last ? nB : cB + (size_t)(t + 2) * kstep;
;     ...
;             PG8_LDA(At, 1, 1); PG8_STAGE(PG8_SB(1, 0), b3, voffB); PG8_STAGE(PG8_SB(1, 1), b3 + hstepB, voffB); PG8_STAGE(PG8_SA(1, 0), a3, voffA);
;             PG8_WAIT_V(8); PG8_WAIT_L(0); PG8_BAR; PG8_MMA(1, 0, At, B0); PG8_MMA(1, 1, At, B1); PG8_BAR; PG8_SCHED;
	s_add_i32 s34, s55, s39
	v_lshl_add_u64 v[174:175], v[174:175], 0, s[14:15]
	s_mov_b32 m0, s34
	ds_read_b128 v[184:187], v178 offset:49152
	ds_read_b128 v[188:191], v178 offset:50176
	ds_read_b128 v[192:195], v178 offset:51200
	ds_read_b128 v[196:199], v178 offset:52224
	ds_read_b128 v[200:203], v178 offset:53248
	ds_read_b128 v[204:207], v178 offset:54272
	ds_read_b128 v[208:211], v178 offset:55296
	ds_read_b128 v[212:215], v178 offset:56320
	global_load_lds_dwordx4 v[174:175], off
	s_add_i32 m0, s34, 0x2000
	s_add_u32 s30, s30, 0x80080
	v_lshl_add_u64 v[174:175], v[216:217], 0, s[14:15]
	s_addc_u32 s31, s31, 0
	s_add_i32 s34, s56, s39
	global_load_lds_dwordx4 v[174:175], off
	v_lshl_add_u64 v[174:175], s[30:31], 0, v[148:149]
	s_mov_b32 m0, s34
	s_nop 0
	global_load_lds_dwordx4 v[174:175], off
	v_lshl_add_u64 v[174:175], s[30:31], 0, v[152:153]
	s_add_i32 m0, s34, 0x2000
	s_nop 0
	global_load_lds_dwordx4 v[174:175], off
	v_lshl_add_u64 v[174:175], v[218:219], 0, s[14:15]
	s_mov_b32 m0, s46
	s_nop 0
	global_load_lds_dwordx4 v[174:175], off
	v_lshl_add_u64 v[174:175], v[220:221], 0, s[14:15]
	s_mov_b32 m0, s47
	s_nop 0
	global_load_lds_dwordx4 v[174:175], off
	s_waitcnt vmcnt(8)
	s_waitcnt lgkmcnt(0)
	s_barrier
	s_waitcnt lgkmcnt(0)
	v_mfma_f32_16x16x32_bf16 v[62:65], v[130:133], v[184:187], v[62:65]
	v_mfma_f32_16x16x32_bf16 v[58:61], v[138:141], v[184:187], v[58:61]
	v_mfma_f32_16x16x32_bf16 v[46:49], v[130:133], v[192:195], v[46:49]
	v_mfma_f32_16x16x32_bf16 v[42:45], v[138:141], v[192:195], v[42:45]
	v_mfma_f32_16x16x32_bf16 v[30:33], v[130:133], v[200:203], v[30:33]
	v_mfma_f32_16x16x32_bf16 v[26:29], v[138:141], v[200:203], v[26:29]
	v_mfma_f32_16x16x32_bf16 v[14:17], v[130:133], v[208:211], v[14:17]
	v_mfma_f32_16x16x32_bf16 v[10:13], v[138:141], v[208:211], v[10:13]
	v_mfma_f32_16x16x32_bf16 v[62:65], v[134:137], v[188:191], v[62:65]
	v_mfma_f32_16x16x32_bf16 v[58:61], v[142:145], v[188:191], v[58:61]
	v_mfma_f32_16x16x32_bf16 v[46:49], v[134:137], v[196:199], v[46:49]
	v_mfma_f32_16x16x32_bf16 v[42:45], v[142:145], v[196:199], v[42:45]
	v_mfma_f32_16x16x32_bf16 v[30:33], v[134:137], v[204:207], v[30:33]
	v_mfma_f32_16x16x32_bf16 v[26:29], v[142:145], v[204:207], v[26:29]
	v_mfma_f32_16x16x32_bf16 v[14:17], v[134:137], v[212:215], v[14:17]
	v_mfma_f32_16x16x32_bf16 v[10:13], v[142:145], v[212:215], v[10:13]
	v_mfma_f32_16x16x32_bf16 v[54:57], v[162:165], v[184:187], v[54:57]
	v_mfma_f32_16x16x32_bf16 v[50:53], v[170:173], v[184:187], v[50:53]
	v_mfma_f32_16x16x32_bf16 v[38:41], v[162:165], v[192:195], v[38:41]
	v_mfma_f32_16x16x32_bf16 v[34:37], v[170:173], v[192:195], v[34:37]
	v_mfma_f32_16x16x32_bf16 v[22:25], v[162:165], v[200:203], v[22:25]
	v_mfma_f32_16x16x32_bf16 v[18:21], v[170:173], v[200:203], v[18:21]
	v_mfma_f32_16x16x32_bf16 v[6:9], v[162:165], v[208:211], v[6:9]
	v_mfma_f32_16x16x32_bf16 v[2:5], v[170:173], v[208:211], v[2:5]
	v_mfma_f32_16x16x32_bf16 v[54:57], v[166:169], v[188:191], v[54:57]
	v_mfma_f32_16x16x32_bf16 v[50:53], v[180:183], v[188:191], v[50:53]
	v_mfma_f32_16x16x32_bf16 v[38:41], v[166:169], v[196:199], v[38:41]
	v_mfma_f32_16x16x32_bf16 v[34:37], v[180:183], v[196:199], v[34:37]
	v_mfma_f32_16x16x32_bf16 v[22:25], v[166:169], v[204:207], v[22:25]
	v_mfma_f32_16x16x32_bf16 v[18:21], v[180:183], v[204:207], v[18:21]
	v_mfma_f32_16x16x32_bf16 v[6:9], v[166:169], v[212:215], v[6:9]
	v_mfma_f32_16x16x32_bf16 v[2:5], v[180:183], v[212:215], v[2:5]
	s_barrier
	s_add_i32 s54, s54, 2
	s_add_u32 s28, s28, 0x100
	s_addc_u32 s29, s29, 0
	s_add_u32 s52, s52, 0x100
	s_addc_u32 s53, s53, 0
	s_cmp_gt_u32 s54, 29
	s_cbranch_scc0 .LBB0_1565
	s_and_b64 vcc, exec, s[16:17]
	s_cbranch_vccz .LBB0_1568
	s_barrier

; __device__ __forceinline__ void rows_bf16_to_i8(Frame& F, const bf16* XBp, const unsigned* rmax, unsigned* X8, float* sx, int pitch4 = D / 4) {
;     const int gw = F.vcu * NWAVES + F.wave, NGW = F.G * NWAVES, lane = F.lane;
;     v4u w[8], wn[8]; unsigned rb = 0, rbn = 0;
;     int m = gw;
;     if (m < M) { const v4u* src = (const v4u*)(XBp + (size_t)m * D) + lane; rb = rmax[m];
; #pragma unroll
;         for (int j = 0; j < 8; ++j) w[j] = src[64 * j]; }
; __global__ void __launch_bounds__(NWAVES * 64, 2) mk_fwd(Args args) {
;     ...
;     if (IN(G_OUT)) {
;         rows_bf16_to_i8(F, (const bf16*)(ws + WS_MERGED), (const unsigned*)(ws + CTL_RMAX3), (unsigned*)(ws + WS_X8C), (float*)(ws + WS_SX3));
.LBB0_1642:
	s_setprio 0
	s_cmp_lt_i32 s72, 10
	s_cselect_b64 s[0:1], -1, 0
	s_cmp_gt_i32 s73, 9
	s_cselect_b64 s[2:3], -1, 0
	s_and_b64 s[0:1], s[0:1], s[2:3]
	s_andn2_b64 vcc, exec, s[0:1]
	s_cbranch_vccnz .LBB0_1846
	v_readlane_b32 s0, v254, 5
	s_lshl_b32 s0, s0, 3
	v_readlane_b32 s1, v254, 39
	s_add_i32 s0, s0, s1
	s_cmpk_gt_i32 s0, 0x3fff
	s_cbranch_scc1 .LBB0_1650
	v_readlane_b32 s2, v254, 6
	s_ashr_i32 s1, s0, 31
	s_lshl_b32 s2, s2, 3
	s_lshl_b64 s[4:5], s[0:1], 13
	s_add_u32 s4, s96, s4
	v_readlane_b32 s3, v254, 7
	s_addc_u32 s5, s97, s5
	v_lshlrev_b32_e32 v66, 4, v232
	v_mov_b32_e32 v67, 0
	s_waitcnt vmcnt(0) lgkmcnt(0)
	v_lshl_add_u64 v[2:3], s[4:5], 0, v[66:67]
	s_mov_b64 s[4:5], 0x1e400000
	s_lshl_b64 s[6:7], s[0:1], 2
	s_mov_b32 s3, 0x1e401000
	v_lshl_add_u64 v[4:5], v[2:3], 0, s[4:5]
	s_add_u32 s4, s96, s6
	v_add_co_u32_e32 v2, vcc, s3, v2
	s_addc_u32 s5, s97, s7
	v_mov_b32_e32 v6, 0xc0000
	v_addc_co_u32_e32 v3, vcc, 0, v3, vcc
	global_load_dwordx4 v[58:61], v[4:5], off offset:1024
	global_load_dwordx4 v[54:57], v[4:5], off offset:2048
	global_load_dword v1, v6, s[4:5]
	global_load_dwordx4 v[50:53], v[4:5], off offset:3072
	global_load_dwordx4 v[62:65], v[2:3], off offset:-4096
	global_load_dwordx4 v[46:49], v[2:3], off
	global_load_dwordx4 v[42:45], v[2:3], off offset:1024
	global_load_dwordx4 v[38:41], v[2:3], off offset:2048
	global_load_dwordx4 v[34:37], v[2:3], off offset:3072
	s_add_u32 s16, s6, 0x4d4b0000
	s_addc_u32 s17, s7, 0
	s_add_i32 s10, s0, s2
	s_ashr_i32 s3, s2, 31
	s_lshl_b64 s[8:9], s[0:1], 12
	s_ashr_i32 s11, s10, 31
	s_lshl_b64 s[6:7], s[2:3], 2
	v_lshl_or_b32 v68, v232, 3, s8
	v_mov_b32_e32 v69, s9
	s_lshl_b64 s[8:9], s[2:3], 12
	s_lshl_b64 s[12:13], s[10:11], 2
	s_add_u32 s1, s12, 0xc0000
	s_addc_u32 s18, s13, 0
	s_lshl_b64 s[10:11], s[10:11], 13
	v_cmp_eq_u32_e64 s[4:5], 0, v232
	v_or_b32_e32 v70, s10, v66
	v_mov_b32_e32 v71, s11
	s_lshl_b64 s[10:11], s[2:3], 13
	s_mov_b32 s3, 0x42fe0000
	s_mov_b32 s19, 0xc0c0500
	s_mov_b32 s20, 0x40c0c00
	s_mov_b32 s21, 0x15400000
	v_mov_b32_e32 v66, 0
	s_branch .LBB0_1646

; #define GRID_BAR() xcd_barrier(bar)
; #define GRID_BAR() do {} while (0)
; __global__ void __launch_bounds__(NWAVES * 64, 2) mk_fwd(Args args) {
;     ...
;         GRID_BAR();
;         pg8::Gemm g{(const bf16*)(ws + WS_X8C), (const bf16*)(ws + WS_W8O), M, D, D / 2, D / 2, D / 2, 0}; pg8::StaticOrder S; S.init(M, D, F.G, bx);
;         pg8::EpiF<0, true> E{F.in[0], F.out, nullptr, nullptr, XB, (float*)(ws + CTL_SS2), (unsigned*)(ws + CTL_RMAX2), (const float*)(ws + WS_SX3), (const float*)(ws + WS_SWO)};
;         pg8::gemm_phase<pg8::EpiF<0, true>, pg8::StaticOrder, true, true, true>(F.lds + RING_OFF, g, S, E);
.LBB0_1702:
	s_or_b64 exec, exec, s[0:1]
	v_readfirstlane_b32 s98, v0
	s_nop 3
	s_and_b32 s98, s98, 0x3ff
	s_lshr_b32 s98, s98, 6
	s_cmp_ge_u32 s98, 4
	s_cbranch_scc0 .Lprio_gout
	s_setprio 1

; #define PG8_STAGE(bufoff, gbase, voff) do { _Pragma("unroll") for (int _i = 0; _i < 2; ++_i) \
;         __builtin_amdgcn_global_load_lds((const unsigned*)((const char*)(gbase) + (voff)[_i]), (PG8_LAS unsigned*)(lds + (bufoff) + ldsw + _i * 8192), 16, 0, 0); } while (0)
; #define PG8_LDA(dst, b, h) do { _Pragma("unroll") for (int m = 0; m < 4; ++m) _Pragma("unroll") for (int k = 0; k < 2; ++k) dst[m][k] = *(const PG8_LAS bf16x8*)(lds + PG8_SA(b, h) + aoff + m * 2048 + k * 1024); } while (0)
; #define PG8_LDB(dst, b, h) do { _Pragma("unroll") for (int n = 0; n < 2; ++n) _Pragma("unroll") for (int k = 0; k < 2; ++k) dst[n][k] = *(const PG8_LAS bf16x8*)(lds + PG8_SB(b, h) + boff + n * 2048 + k * 1024); } while (0)
; #define PG8_MMA(ai, bj, At, Bt) do { __builtin_amdgcn_s_setprio(1); _Pragma("unroll") for (int m = 0; m < 4; ++m) _Pragma("unroll") for (int n = 0; n < 2; ++n) _Pragma("unroll") for (int k = 0; k < 2; ++k) \
;         acc[ai][bj][m][n] = mma_<I8>(Bt[n][k], At[m][k], acc[ai][bj][m][n]); __builtin_amdgcn_s_setprio(0); } while (0)
; #define PG8_WAIT_V(n) asm volatile("s_waitcnt vmcnt(" #n ")" ::: "memory")
; #define PG8_WAIT_L(n) asm volatile("s_waitcnt lgkmcnt(" #n ")" ::: "memory")
; #define PG8_BAR __builtin_amdgcn_s_barrier()
; #define PG8_SCHED __builtin_amdgcn_sched_barrier(0)
; template <class Epi, class Sched, bool ALIGN_EPI = false, bool SP2 = false, bool I8 = false>
; __device__ __forceinline__ void gemm_phase(PG8_LAS unsigned char* lds, const Gemm g, const Sched& S, const Epi& E) {
;     ...
;         for (int t = 0; t < nt; t += 2) {
;             const bool last = (t == nt - 2);
;             const char* a1 = cA + (size_t)(t + 1) * kstep;
;             const char* a2 = last ? nA : cA + (size_t)(t + 2) * kstep; const char* b2 = last ? nB : cB + (size_t)(t + 2) * kstep;
;             const char* a3 = a2 + kstep; const char* b3 = b2 + kstep;
;             if (last && has_next) S.a_ready(nxt);
;             if constexpr (SP2) {
;             PG8_LDB(B0, 0, 0); PG8_LDB(B1, 0, 1); PG8_SCHED; PG8_LDA(At, 0, 0); PG8_STAGE(PG8_SA(1, 1), a1 + hstepA, voffA);
;             PG8_WAIT_V(8); PG8_WAIT_L(0); PG8_BAR; PG8_MMA(0, 0, At, B0); PG8_MMA(0, 1, At, B1); PG8_BAR; PG8_SCHED;
;             PG8_LDA(At, 0, 1); PG8_STAGE(PG8_SB(0, 0), b2, voffB); PG8_STAGE(PG8_SB(0, 1), b2 + hstepB, voffB); PG8_STAGE(PG8_SA(0, 0), a2, voffA);
.LBB0_1721:
	ds_read_b128 v[34:37], v233
	ds_read_b128 v[38:41], v233 offset:1024
	ds_read_b128 v[42:45], v233 offset:2048
	ds_read_b128 v[62:65], v233 offset:3072
	ds_read_b128 v[146:149], v234
	ds_read_b128 v[150:153], v234 offset:1024
	ds_read_b128 v[154:157], v234 offset:2048
	ds_read_b128 v[158:161], v234 offset:3072
	s_add_u32 s34, s8, 0xfff80080
	s_addc_u32 s35, s9, -1
	s_cmp_eq_u32 s55, 28
	s_cselect_b32 s37, s3, s35
	s_cselect_b32 s36, s7, s34
	s_cselect_b32 s35, s25, s54
	s_cselect_b32 s34, s27, s33
	v_lshl_add_u64 v[206:207], s[8:9], 0, v[178:179]
	s_add_i32 m0, s43, 0xc000
	ds_read_b128 v[162:165], v235
	ds_read_b128 v[166:169], v235 offset:1024
	ds_read_b128 v[170:173], v235 offset:2048
	ds_read_b128 v[186:189], v235 offset:3072
	ds_read_b128 v[190:193], v235 offset:4096
	ds_read_b128 v[194:197], v235 offset:5120
	ds_read_b128 v[198:201], v235 offset:6144
	ds_read_b128 v[202:205], v235 offset:7168
	global_load_lds_dwordx4 v[206:207], off
	v_lshl_add_u64 v[206:207], s[8:9], 0, v[180:181]
	s_add_i32 m0, s43, 0xe000
	s_nop 0
	global_load_lds_dwordx4 v[206:207], off
	s_waitcnt vmcnt(8)
	s_waitcnt lgkmcnt(0)
	s_barrier
	s_waitcnt lgkmcnt(0)
	v_mfma_i32_16x16x64_i8 v[142:145], v[34:37], v[162:165], v[142:145]
	v_mfma_i32_16x16x64_i8 v[138:141], v[42:45], v[162:165], v[138:141]
	v_mfma_i32_16x16x64_i8 v[126:129], v[34:37], v[170:173], v[126:129]
	v_mfma_i32_16x16x64_i8 v[122:125], v[42:45], v[170:173], v[122:125]
	v_mfma_i32_16x16x64_i8 v[110:113], v[34:37], v[190:193], v[110:113]
	v_mfma_i32_16x16x64_i8 v[106:109], v[42:45], v[190:193], v[106:109]
	v_mfma_i32_16x16x64_i8 v[94:97], v[34:37], v[198:201], v[94:97]
	v_mfma_i32_16x16x64_i8 v[90:93], v[42:45], v[198:201], v[90:93]
	v_mfma_i32_16x16x64_i8 v[142:145], v[38:41], v[166:169], v[142:145]
	v_mfma_i32_16x16x64_i8 v[138:141], v[62:65], v[166:169], v[138:141]
	v_mfma_i32_16x16x64_i8 v[126:129], v[38:41], v[186:189], v[126:129]
	v_mfma_i32_16x16x64_i8 v[122:125], v[62:65], v[186:189], v[122:125]
	v_mfma_i32_16x16x64_i8 v[110:113], v[38:41], v[194:197], v[110:113]
	v_mfma_i32_16x16x64_i8 v[106:109], v[62:65], v[194:197], v[106:109]
	v_mfma_i32_16x16x64_i8 v[94:97], v[38:41], v[202:205], v[94:97]
	v_mfma_i32_16x16x64_i8 v[90:93], v[62:65], v[202:205], v[90:93]
	v_mfma_i32_16x16x64_i8 v[134:137], v[146:149], v[162:165], v[134:137]
	v_mfma_i32_16x16x64_i8 v[130:133], v[154:157], v[162:165], v[130:133]
	v_mfma_i32_16x16x64_i8 v[118:121], v[146:149], v[170:173], v[118:121]
	v_mfma_i32_16x16x64_i8 v[114:117], v[154:157], v[170:173], v[114:117]
	v_mfma_i32_16x16x64_i8 v[102:105], v[146:149], v[190:193], v[102:105]
	v_mfma_i32_16x16x64_i8 v[98:101], v[154:157], v[190:193], v[98:101]
	v_mfma_i32_16x16x64_i8 v[86:89], v[146:149], v[198:201], v[86:89]
	v_mfma_i32_16x16x64_i8 v[82:85], v[154:157], v[198:201], v[82:85]
	v_mfma_i32_16x16x64_i8 v[134:137], v[150:153], v[166:169], v[134:137]
	v_mfma_i32_16x16x64_i8 v[130:133], v[158:161], v[166:169], v[130:133]
	v_mfma_i32_16x16x64_i8 v[118:121], v[150:153], v[186:189], v[118:121]
	v_mfma_i32_16x16x64_i8 v[114:117], v[158:161], v[186:189], v[114:117]
	v_mfma_i32_16x16x64_i8 v[102:105], v[150:153], v[194:197], v[102:105]
	v_mfma_i32_16x16x64_i8 v[98:101], v[158:161], v[194:197], v[98:101]
	v_mfma_i32_16x16x64_i8 v[86:89], v[150:153], v[202:205], v[86:89]
	v_mfma_i32_16x16x64_i8 v[82:85], v[158:161], v[202:205], v[82:85]
	s_barrier
	s_add_i32 s56, s52, s40
	v_lshl_add_u64 v[206:207], s[34:35], 0, v[174:175]
	s_mov_b32 m0, s56
	ds_read_b128 v[162:165], v235 offset:16384
	ds_read_b128 v[166:169], v235 offset:17408
	ds_read_b128 v[170:173], v235 offset:18432
	ds_read_b128 v[186:189], v235 offset:19456
	ds_read_b128 v[190:193], v235 offset:20480
	ds_read_b128 v[194:197], v235 offset:21504
	ds_read_b128 v[198:201], v235 offset:22528
	ds_read_b128 v[202:205], v235 offset:23552
	global_load_lds_dwordx4 v[206:207], off
	s_add_i32 m0, s56, 0x2000
	s_add_u32 s56, s34, 0x80000
	v_lshl_add_u64 v[208:209], s[34:35], 0, v[176:177]
	s_addc_u32 s57, s35, 0
	s_add_i32 s58, s53, s40
	global_load_lds_dwordx4 v[208:209], off
	v_lshl_add_u64 v[210:211], s[56:57], 0, v[174:175]
	s_mov_b32 m0, s58
	v_lshl_add_u64 v[212:213], s[36:37], 0, v[176:177]
	global_load_lds_dwordx4 v[210:211], off
	v_lshl_add_u64 v[210:211], s[56:57], 0, v[176:177]
	s_add_i32 m0, s58, 0x2000
	s_nop 0
	global_load_lds_dwordx4 v[210:211], off
	v_lshl_add_u64 v[210:211], s[36:37], 0, v[174:175]
	s_mov_b32 m0, s43
	s_nop 0
	global_load_lds_dwordx4 v[210:211], off
	s_mov_b32 m0, s44
	s_nop 0
	global_load_lds_dwordx4 v[212:213], off
	s_waitcnt vmcnt(8)
	s_waitcnt lgkmcnt(0)
	s_barrier
; #define PG8_STAGE(bufoff, gbase, voff) do { _Pragma("unroll") for (int _i = 0; _i < 2; ++_i) \
;         __builtin_amdgcn_global_load_lds((const unsigned*)((const char*)(gbase) + (voff)[_i]), (PG8_LAS unsigned*)(lds + (bufoff) + ldsw + _i * 8192), 16, 0, 0); } while (0)
; #define PG8_LDA(dst, b, h) do { _Pragma("unroll") for (int m = 0; m < 4; ++m) _Pragma("unroll") for (int k = 0; k < 2; ++k) dst[m][k] = *(const PG8_LAS bf16x8*)(lds + PG8_SA(b, h) + aoff + m * 2048 + k * 1024); } while (0)
; #define PG8_LDB(dst, b, h) do { _Pragma("unroll") for (int n = 0; n < 2; ++n) _Pragma("unroll") for (int k = 0; k < 2; ++k) dst[n][k] = *(const PG8_LAS bf16x8*)(lds + PG8_SB(b, h) + boff + n * 2048 + k * 1024); } while (0)
; #define PG8_MMA(ai, bj, At, Bt) do { __builtin_amdgcn_s_setprio(1); _Pragma("unroll") for (int m = 0; m < 4; ++m) _Pragma("unroll") for (int n = 0; n < 2; ++n) _Pragma("unroll") for (int k = 0; k < 2; ++k) \
;         acc[ai][bj][m][n] = mma_<I8>(Bt[n][k], At[m][k], acc[ai][bj][m][n]); __builtin_amdgcn_s_setprio(0); } while (0)
; #define PG8_WAIT_V(n) asm volatile("s_waitcnt vmcnt(" #n ")" ::: "memory")
; #define PG8_WAIT_L(n) asm volatile("s_waitcnt lgkmcnt(" #n ")" ::: "memory")
; #define PG8_BAR __builtin_amdgcn_s_barrier()
; #define PG8_SCHED __builtin_amdgcn_sched_barrier(0)
; template <class Epi, class Sched, bool ALIGN_EPI = false, bool SP2 = false, bool I8 = false>
; __device__ __forceinline__ void gemm_phase(PG8_LAS unsigned char* lds, const Gemm g, const Sched& S, const Epi& E) {
;     ...
;             PG8_WAIT_V(8); PG8_WAIT_L(0); PG8_BAR; PG8_MMA(1, 0, At, B0); PG8_MMA(1, 1, At, B1); PG8_BAR; PG8_SCHED;
;             PG8_LDB(B0, 1, 0); PG8_LDB(B1, 1, 1); PG8_SCHED; PG8_LDA(At, 1, 0); PG8_STAGE(PG8_SA(0, 1), a2 + hstepA, voffA);
;             PG8_WAIT_V(8); PG8_WAIT_L(0); PG8_BAR; PG8_MMA(0, 0, At, B0); PG8_MMA(0, 1, At, B1); PG8_BAR; PG8_SCHED;
	s_waitcnt lgkmcnt(0)
	v_mfma_i32_16x16x64_i8 v[78:81], v[34:37], v[162:165], v[78:81]
	v_mfma_i32_16x16x64_i8 v[74:77], v[42:45], v[162:165], v[74:77]
	v_mfma_i32_16x16x64_i8 v[58:61], v[34:37], v[170:173], v[58:61]
	v_mfma_i32_16x16x64_i8 v[54:57], v[42:45], v[170:173], v[54:57]
	v_mfma_i32_16x16x64_i8 v[30:33], v[34:37], v[190:193], v[30:33]
	v_mfma_i32_16x16x64_i8 v[26:29], v[42:45], v[190:193], v[26:29]
	v_mfma_i32_16x16x64_i8 v[14:17], v[34:37], v[198:201], v[14:17]
	v_mfma_i32_16x16x64_i8 v[10:13], v[42:45], v[198:201], v[10:13]
	v_mfma_i32_16x16x64_i8 v[78:81], v[38:41], v[166:169], v[78:81]
	v_mfma_i32_16x16x64_i8 v[74:77], v[62:65], v[166:169], v[74:77]
	v_mfma_i32_16x16x64_i8 v[58:61], v[38:41], v[186:189], v[58:61]
	v_mfma_i32_16x16x64_i8 v[54:57], v[62:65], v[186:189], v[54:57]
	v_mfma_i32_16x16x64_i8 v[30:33], v[38:41], v[194:197], v[30:33]
	v_mfma_i32_16x16x64_i8 v[26:29], v[62:65], v[194:197], v[26:29]
	v_mfma_i32_16x16x64_i8 v[14:17], v[38:41], v[202:205], v[14:17]
	v_mfma_i32_16x16x64_i8 v[10:13], v[62:65], v[202:205], v[10:13]
	v_mfma_i32_16x16x64_i8 v[46:49], v[154:157], v[170:173], v[46:49]
	v_mfma_i32_16x16x64_i8 v[22:25], v[146:149], v[190:193], v[22:25]
	v_mfma_i32_16x16x64_i8 v[18:21], v[154:157], v[190:193], v[18:21]
	v_mfma_i32_16x16x64_i8 v[6:9], v[146:149], v[198:201], v[6:9]
	v_mfma_i32_16x16x64_i8 v[2:5], v[154:157], v[198:201], v[2:5]
	v_mfma_i32_16x16x64_i8 v[34:37], v[146:149], v[162:165], v[70:73]
	v_mfma_i32_16x16x64_i8 v[38:41], v[154:157], v[162:165], v[66:69]
	v_mfma_i32_16x16x64_i8 v[42:45], v[146:149], v[170:173], v[50:53]
	v_mfma_i32_16x16x64_i8 v[46:49], v[158:161], v[186:189], v[46:49]
	v_mfma_i32_16x16x64_i8 v[22:25], v[150:153], v[194:197], v[22:25]
	v_mfma_i32_16x16x64_i8 v[18:21], v[158:161], v[194:197], v[18:21]
	v_mfma_i32_16x16x64_i8 v[6:9], v[150:153], v[202:205], v[6:9]
	v_mfma_i32_16x16x64_i8 v[2:5], v[158:161], v[202:205], v[2:5]
	v_mfma_i32_16x16x64_i8 v[34:37], v[150:153], v[166:169], v[34:37]
	v_mfma_i32_16x16x64_i8 v[38:41], v[158:161], v[166:169], v[38:41]
	v_mfma_i32_16x16x64_i8 v[42:45], v[150:153], v[186:189], v[42:45]
	s_barrier
	s_add_i32 s56, 0, 0x18000
	s_add_i32 s57, 0, 0x1c000
	v_add_u32_e32 v70, s56, v1
	v_add_u32_e32 v158, s57, v1
	ds_read_b128 v[50:53], v70
	ds_read_b128 v[62:65], v70 offset:1024
	ds_read_b128 v[66:69], v70 offset:2048
	ds_read_b128 v[70:73], v70 offset:3072
	ds_read_b128 v[146:149], v158
	ds_read_b128 v[150:153], v158 offset:1024
	ds_read_b128 v[154:157], v158 offset:2048
	ds_read_b128 v[158:161], v158 offset:3072
	s_add_u32 s36, s36, 0x80000
	s_addc_u32 s37, s37, 0
	s_mov_b32 m0, s45
	v_lshl_add_u64 v[214:215], s[36:37], 0, v[174:175]
	ds_read_b128 v[162:165], v235 offset:32768
	ds_read_b128 v[166:169], v235 offset:33792
	ds_read_b128 v[170:173], v235 offset:34816
	ds_read_b128 v[186:189], v235 offset:35840
	ds_read_b128 v[190:193], v235 offset:36864
	ds_read_b128 v[194:197], v235 offset:37888
	ds_read_b128 v[198:201], v235 offset:38912
	ds_read_b128 v[202:205], v235 offset:39936
	global_load_lds_dwordx4 v[214:215], off
	v_lshl_add_u64 v[214:215], s[36:37], 0, v[176:177]
	s_mov_b32 m0, s46
	s_nop 0
	global_load_lds_dwordx4 v[214:215], off
	s_waitcnt vmcnt(8)
	s_waitcnt lgkmcnt(0)
	s_barrier
	s_waitcnt lgkmcnt(0)
	v_mfma_i32_16x16x64_i8 v[142:145], v[50:53], v[162:165], v[142:145]
	v_mfma_i32_16x16x64_i8 v[138:141], v[66:69], v[162:165], v[138:141]
	v_mfma_i32_16x16x64_i8 v[126:129], v[50:53], v[170:173], v[126:129]
	v_mfma_i32_16x16x64_i8 v[122:125], v[66:69], v[170:173], v[122:125]
	v_mfma_i32_16x16x64_i8 v[110:113], v[50:53], v[190:193], v[110:113]
	v_mfma_i32_16x16x64_i8 v[106:109], v[66:69], v[190:193], v[106:109]
	v_mfma_i32_16x16x64_i8 v[94:97], v[50:53], v[198:201], v[94:97]
	v_mfma_i32_16x16x64_i8 v[90:93], v[66:69], v[198:201], v[90:93]
	v_mfma_i32_16x16x64_i8 v[142:145], v[62:65], v[166:169], v[142:145]
	v_mfma_i32_16x16x64_i8 v[138:141], v[70:73], v[166:169], v[138:141]
	v_mfma_i32_16x16x64_i8 v[126:129], v[62:65], v[186:189], v[126:129]
	v_mfma_i32_16x16x64_i8 v[122:125], v[70:73], v[186:189], v[122:125]
	v_mfma_i32_16x16x64_i8 v[110:113], v[62:65], v[194:197], v[110:113]
	v_mfma_i32_16x16x64_i8 v[106:109], v[70:73], v[194:197], v[106:109]
	v_mfma_i32_16x16x64_i8 v[94:97], v[62:65], v[202:205], v[94:97]
	v_mfma_i32_16x16x64_i8 v[90:93], v[70:73], v[202:205], v[90:93]
	v_mfma_i32_16x16x64_i8 v[134:137], v[146:149], v[162:165], v[134:137]
	v_mfma_i32_16x16x64_i8 v[130:133], v[154:157], v[162:165], v[130:133]
	v_mfma_i32_16x16x64_i8 v[118:121], v[146:149], v[170:173], v[118:121]
	v_mfma_i32_16x16x64_i8 v[114:117], v[154:157], v[170:173], v[114:117]
	v_mfma_i32_16x16x64_i8 v[102:105], v[146:149], v[190:193], v[102:105]
	v_mfma_i32_16x16x64_i8 v[98:101], v[154:157], v[190:193], v[98:101]
	v_mfma_i32_16x16x64_i8 v[86:89], v[146:149], v[198:201], v[86:89]
	v_mfma_i32_16x16x64_i8 v[82:85], v[154:157], v[198:201], v[82:85]
	v_mfma_i32_16x16x64_i8 v[134:137], v[150:153], v[166:169], v[134:137]
	v_mfma_i32_16x16x64_i8 v[130:133], v[158:161], v[166:169], v[130:133]
	v_mfma_i32_16x16x64_i8 v[118:121], v[150:153], v[186:189], v[118:121]
	v_mfma_i32_16x16x64_i8 v[114:117], v[158:161], v[186:189], v[114:117]
	v_mfma_i32_16x16x64_i8 v[102:105], v[150:153], v[194:197], v[102:105]
	v_mfma_i32_16x16x64_i8 v[98:101], v[158:161], v[194:197], v[98:101]
	v_mfma_i32_16x16x64_i8 v[86:89], v[150:153], v[202:205], v[86:89]
	v_mfma_i32_16x16x64_i8 v[82:85], v[158:161], v[202:205], v[82:85]
	s_barrier
; #define PG8_STAGE(bufoff, gbase, voff) do { _Pragma("unroll") for (int _i = 0; _i < 2; ++_i) \
;         __builtin_amdgcn_global_load_lds((const unsigned*)((const char*)(gbase) + (voff)[_i]), (PG8_LAS unsigned*)(lds + (bufoff) + ldsw + _i * 8192), 16, 0, 0); } while (0)
; #define PG8_LDA(dst, b, h) do { _Pragma("unroll") for (int m = 0; m < 4; ++m) _Pragma("unroll") for (int k = 0; k < 2; ++k) dst[m][k] = *(const PG8_LAS bf16x8*)(lds + PG8_SA(b, h) + aoff + m * 2048 + k * 1024); } while (0)
; #define PG8_MMA(ai, bj, At, Bt) do { __builtin_amdgcn_s_setprio(1); _Pragma("unroll") for (int m = 0; m < 4; ++m) _Pragma("unroll") for (int n = 0; n < 2; ++n) _Pragma("unroll") for (int k = 0; k < 2; ++k) \
;         acc[ai][bj][m][n] = mma_<I8>(Bt[n][k], At[m][k], acc[ai][bj][m][n]); __builtin_amdgcn_s_setprio(0); } while (0)
; #define PG8_WAIT_V(n) asm volatile("s_waitcnt vmcnt(" #n ")" ::: "memory")
; #define PG8_WAIT_L(n) asm volatile("s_waitcnt lgkmcnt(" #n ")" ::: "memory")
; #define PG8_BAR __builtin_amdgcn_s_barrier()
; #define PG8_SCHED __builtin_amdgcn_sched_barrier(0)
; template <class Epi, class Sched, bool ALIGN_EPI = false, bool SP2 = false, bool I8 = false>
; __device__ __forceinline__ void gemm_phase(PG8_LAS unsigned char* lds, const Gemm g, const Sched& S, const Epi& E) {
;     ...
;         for (int t = 0; t < nt; t += 2) {
;             const bool last = (t == nt - 2);
;             const char* a1 = cA + (size_t)(t + 1) * kstep;
;             const char* a2 = last ? nA : cA + (size_t)(t + 2) * kstep; const char* b2 = last ? nB : cB + (size_t)(t + 2) * kstep;
;     ...
;             PG8_LDA(At, 1, 1); PG8_STAGE(PG8_SB(1, 0), b3, voffB); PG8_STAGE(PG8_SB(1, 1), b3 + hstepB, voffB); PG8_STAGE(PG8_SA(1, 0), a3, voffA);
;             PG8_WAIT_V(8); PG8_WAIT_L(0); PG8_BAR; PG8_MMA(1, 0, At, B0); PG8_MMA(1, 1, At, B1); PG8_BAR; PG8_SCHED;
	s_add_i32 s36, s56, s40
	v_lshl_add_u64 v[206:207], v[206:207], 0, s[18:19]
	s_mov_b32 m0, s36
	ds_read_b128 v[162:165], v235 offset:49152
	ds_read_b128 v[166:169], v235 offset:50176
	ds_read_b128 v[170:173], v235 offset:51200
	ds_read_b128 v[186:189], v235 offset:52224
	ds_read_b128 v[190:193], v235 offset:53248
	ds_read_b128 v[194:197], v235 offset:54272
	ds_read_b128 v[198:201], v235 offset:55296
	ds_read_b128 v[202:205], v235 offset:56320
	global_load_lds_dwordx4 v[206:207], off
	s_add_i32 m0, s36, 0x2000
	s_add_u32 s34, s34, 0x80080
	v_lshl_add_u64 v[206:207], v[208:209], 0, s[18:19]
	s_addc_u32 s35, s35, 0
	s_add_i32 s36, s57, s40
	global_load_lds_dwordx4 v[206:207], off
	v_lshl_add_u64 v[206:207], s[34:35], 0, v[174:175]
	s_mov_b32 m0, s36
	s_nop 0
	global_load_lds_dwordx4 v[206:207], off
	v_lshl_add_u64 v[206:207], s[34:35], 0, v[176:177]
	s_add_i32 m0, s36, 0x2000
	s_nop 0
	global_load_lds_dwordx4 v[206:207], off
	v_lshl_add_u64 v[206:207], v[210:211], 0, s[18:19]
	s_mov_b32 m0, s48
	s_nop 0
	global_load_lds_dwordx4 v[206:207], off
	v_lshl_add_u64 v[206:207], v[212:213], 0, s[18:19]
	s_mov_b32 m0, s49
	s_nop 0
	global_load_lds_dwordx4 v[206:207], off
	s_waitcnt vmcnt(8)
	s_waitcnt lgkmcnt(0)
	s_barrier
	s_waitcnt lgkmcnt(0)
	v_mfma_i32_16x16x64_i8 v[78:81], v[50:53], v[162:165], v[78:81]
	v_mfma_i32_16x16x64_i8 v[74:77], v[66:69], v[162:165], v[74:77]
	v_mfma_i32_16x16x64_i8 v[58:61], v[50:53], v[170:173], v[58:61]
	v_mfma_i32_16x16x64_i8 v[54:57], v[66:69], v[170:173], v[54:57]
	v_mfma_i32_16x16x64_i8 v[30:33], v[50:53], v[190:193], v[30:33]
	v_mfma_i32_16x16x64_i8 v[26:29], v[66:69], v[190:193], v[26:29]
	v_mfma_i32_16x16x64_i8 v[14:17], v[50:53], v[198:201], v[14:17]
	v_mfma_i32_16x16x64_i8 v[10:13], v[66:69], v[198:201], v[10:13]
	v_mfma_i32_16x16x64_i8 v[78:81], v[62:65], v[166:169], v[78:81]
	v_mfma_i32_16x16x64_i8 v[74:77], v[70:73], v[166:169], v[74:77]
	v_mfma_i32_16x16x64_i8 v[58:61], v[62:65], v[186:189], v[58:61]
	v_mfma_i32_16x16x64_i8 v[54:57], v[70:73], v[186:189], v[54:57]
	v_mfma_i32_16x16x64_i8 v[30:33], v[62:65], v[194:197], v[30:33]
	v_mfma_i32_16x16x64_i8 v[26:29], v[70:73], v[194:197], v[26:29]
	v_mfma_i32_16x16x64_i8 v[14:17], v[62:65], v[202:205], v[14:17]
	v_mfma_i32_16x16x64_i8 v[10:13], v[70:73], v[202:205], v[10:13]
	v_mfma_i32_16x16x64_i8 v[34:37], v[146:149], v[162:165], v[34:37]
	v_mfma_i32_16x16x64_i8 v[70:73], v[150:153], v[166:169], v[34:37]
	v_mfma_i32_16x16x64_i8 v[34:37], v[154:157], v[162:165], v[38:41]
	v_mfma_i32_16x16x64_i8 v[66:69], v[158:161], v[166:169], v[34:37]
	v_mfma_i32_16x16x64_i8 v[34:37], v[146:149], v[170:173], v[42:45]
	v_mfma_i32_16x16x64_i8 v[50:53], v[150:153], v[186:189], v[34:37]
	v_mfma_i32_16x16x64_i8 v[34:37], v[154:157], v[170:173], v[46:49]
	v_mfma_i32_16x16x64_i8 v[22:25], v[146:149], v[190:193], v[22:25]
	v_mfma_i32_16x16x64_i8 v[18:21], v[154:157], v[190:193], v[18:21]
	v_mfma_i32_16x16x64_i8 v[6:9], v[146:149], v[198:201], v[6:9]
	v_mfma_i32_16x16x64_i8 v[2:5], v[154:157], v[198:201], v[2:5]
	v_mfma_i32_16x16x64_i8 v[46:49], v[158:161], v[186:189], v[34:37]
	v_mfma_i32_16x16x64_i8 v[22:25], v[150:153], v[194:197], v[22:25]
	v_mfma_i32_16x16x64_i8 v[18:21], v[158:161], v[194:197], v[18:21]
	v_mfma_i32_16x16x64_i8 v[6:9], v[150:153], v[202:205], v[6:9]
	v_mfma_i32_16x16x64_i8 v[2:5], v[158:161], v[202:205], v[2:5]
	s_barrier
	s_add_i32 s55, s55, 2
	s_add_u32 s8, s8, 0x100
	s_addc_u32 s9, s9, 0
	s_add_u32 s33, s33, 0x100
	s_addc_u32 s54, s54, 0
	s_cmp_gt_u32 s55, 29
	s_cbranch_scc0 .LBB0_1721
	s_and_b64 vcc, exec, s[20:21]
	s_cbranch_vccz .LBB0_1724
	s_barrier

; __device__ __forceinline__ void rows_bf16_to_i8(Frame& F, const bf16* XBp, const unsigned* rmax, unsigned* X8, float* sx, int pitch4 = D / 4) {
;     const int gw = F.vcu * NWAVES + F.wave, NGW = F.G * NWAVES, lane = F.lane;
;     v4u w[8], wn[8]; unsigned rb = 0, rbn = 0;
;     int m = gw;
;     if (m < M) { const v4u* src = (const v4u*)(XBp + (size_t)m * D) + lane; rb = rmax[m];
; #pragma unroll
;         for (int j = 0; j < 8; ++j) w[j] = src[64 * j]; }
; __global__ void __launch_bounds__(NWAVES * 64, 2) mk_fwd(Args args) {
;     ...
;     if (IN(T_N2)) {
;         rows_bf16_to_i8(F, XB, (const unsigned*)(ws + CTL_RMAX2), (unsigned*)(ws + WS_X8B), (float*)(ws + WS_SX2));
.LBB0_1846:
	s_setprio 0
	s_cmp_lt_i32 s72, 11
	s_cselect_b64 s[0:1], -1, 0
	s_cmp_gt_i32 s73, 10
	s_cselect_b64 s[2:3], -1, 0
	s_and_b64 s[0:1], s[0:1], s[2:3]
	s_andn2_b64 vcc, exec, s[0:1]
	s_cbranch_vccnz .LBB0_1996
	v_readlane_b32 s0, v254, 5
	s_lshl_b32 s0, s0, 3
	v_readlane_b32 s2, v254, 39
	s_add_i32 s6, s0, s2
	v_readlane_b32 s0, v254, 6
	s_lshl_b32 s0, s0, 3
	s_cmpk_gt_i32 s6, 0x3fff
	s_mul_i32 s16, s2, 0x4100
	v_readlane_b32 s1, v254, 7
	s_cbranch_scc1 .LBB0_1862
	s_ashr_i32 s7, s6, 31
	s_lshl_b64 s[2:3], s[6:7], 13
	v_readlane_b32 s4, v254, 40
	v_readlane_b32 s5, v254, 41
	s_add_u32 s2, s4, s2
	s_addc_u32 s3, s5, s3
	v_lshlrev_b32_e32 v66, 4, v232
	v_mov_b32_e32 v67, 0
	s_lshl_b64 s[8:9], s[6:7], 2
	s_waitcnt vmcnt(0) lgkmcnt(0)
	v_lshl_add_u64 v[2:3], s[2:3], 0, v[66:67]
	s_add_u32 s4, s96, s8
	s_movk_i32 s1, 0x1000
	s_addc_u32 s5, s97, s9
	v_mov_b32_e32 v4, 0xb0000
	v_add_co_u32_e32 v2, vcc, s1, v2
	global_load_dwordx4 v[58:61], v66, s[2:3] offset:1024
	global_load_dwordx4 v[54:57], v66, s[2:3] offset:2048
	global_load_dwordx4 v[50:53], v66, s[2:3] offset:3072
	v_addc_co_u32_e32 v3, vcc, 0, v3, vcc
	global_load_dword v1, v4, s[4:5]
	global_load_dwordx4 v[46:49], v[2:3], off
	global_load_dwordx4 v[42:45], v[2:3], off offset:1024
	global_load_dwordx4 v[38:41], v[2:3], off offset:2048
	global_load_dwordx4 v[62:65], v66, s[2:3]
	global_load_dwordx4 v[34:37], v[2:3], off offset:3072
	s_add_u32 s17, s8, 0x4d490000
	s_addc_u32 s18, s9, 0
	s_add_i32 s10, s6, s0
	s_ashr_i32 s1, s0, 31
	s_lshl_b64 s[8:9], s[6:7], 12
	s_ashr_i32 s11, s10, 31
	s_lshl_b64 s[2:3], s[0:1], 2
	v_lshl_or_b32 v68, v232, 3, s8
	v_mov_b32_e32 v69, s9
	s_lshl_b64 s[8:9], s[0:1], 12
	s_lshl_b64 s[12:13], s[10:11], 2
	s_add_u32 s19, s12, 0xb0000
	s_addc_u32 s20, s13, 0
	s_lshl_b64 s[10:11], s[10:11], 13
	v_cmp_eq_u32_e64 s[4:5], 0, v232
	v_or_b32_e32 v70, s10, v66
	v_mov_b32_e32 v71, s11
	s_lshl_b64 s[10:11], s[0:1], 13
	s_mov_b32 s1, 0x42fe0000
	s_mov_b32 s21, 0xc0c0500
	s_mov_b32 s22, 0x40c0c00
	s_mov_b32 s23, 0x8200000
	v_mov_b32_e32 v66, 0
	s_mov_b32 s24, s6
	s_branch .LBB0_1850

; __global__ void __launch_bounds__(NWAVES * 64, 2) mk_fwd(Args args) {
;     ...
;     if (IN(G_MLPIN)) {
;         pg8::Gemm g{(const bf16*)(ws + WS_X8B), (const bf16*)(ws + WS_W8M), M, DFF, D / 2, D / 2, D / 2, 0}; pg8::StaticOrder S; S.init(M, DFF, F.G, bx);
.LBB0_1996:
	s_cmp_lt_i32 s72, 12
	s_cselect_b64 s[0:1], -1, 0
	s_cmp_gt_i32 s73, 11
	s_cselect_b64 s[2:3], -1, 0
	s_and_b64 s[0:1], s[0:1], s[2:3]
	s_andn2_b64 vcc, exec, s[0:1]
	v_readlane_b32 s70, v254, 6
	v_readlane_b32 s71, v254, 7
	s_cbranch_vccnz .LBB0_2075
	v_readfirstlane_b32 s98, v0
	s_nop 3
	s_and_b32 s98, s98, 0x3ff
	s_lshr_b32 s98, s98, 6
	s_cmp_ge_u32 s98, 4
	s_cbranch_scc0 .Lprio_mlpin
	s_setprio 1

; #define PG8_STAGE(bufoff, gbase, voff) do { _Pragma("unroll") for (int _i = 0; _i < 2; ++_i) \
;         __builtin_amdgcn_global_load_lds((const unsigned*)((const char*)(gbase) + (voff)[_i]), (PG8_LAS unsigned*)(lds + (bufoff) + ldsw + _i * 8192), 16, 0, 0); } while (0)
; #define PG8_LDA(dst, b, h) do { _Pragma("unroll") for (int m = 0; m < 4; ++m) _Pragma("unroll") for (int k = 0; k < 2; ++k) dst[m][k] = *(const PG8_LAS bf16x8*)(lds + PG8_SA(b, h) + aoff + m * 2048 + k * 1024); } while (0)
; #define PG8_LDB(dst, b, h) do { _Pragma("unroll") for (int n = 0; n < 2; ++n) _Pragma("unroll") for (int k = 0; k < 2; ++k) dst[n][k] = *(const PG8_LAS bf16x8*)(lds + PG8_SB(b, h) + boff + n * 2048 + k * 1024); } while (0)
; #define PG8_MMA(ai, bj, At, Bt) do { __builtin_amdgcn_s_setprio(1); _Pragma("unroll") for (int m = 0; m < 4; ++m) _Pragma("unroll") for (int n = 0; n < 2; ++n) _Pragma("unroll") for (int k = 0; k < 2; ++k) \
;         acc[ai][bj][m][n] = mma_<I8>(Bt[n][k], At[m][k], acc[ai][bj][m][n]); __builtin_amdgcn_s_setprio(0); } while (0)
; #define PG8_WAIT_V(n) asm volatile("s_waitcnt vmcnt(" #n ")" ::: "memory")
; #define PG8_WAIT_L(n) asm volatile("s_waitcnt lgkmcnt(" #n ")" ::: "memory")
; #define PG8_BAR __builtin_amdgcn_s_barrier()
; #define PG8_SCHED __builtin_amdgcn_sched_barrier(0)
; template <class Epi, class Sched, bool ALIGN_EPI = false, bool SP2 = false, bool I8 = false>
; __device__ __forceinline__ void gemm_phase(PG8_LAS unsigned char* lds, const Gemm g, const Sched& S, const Epi& E) {
;     ...
;         for (int t = 0; t < nt; t += 2) {
;             const bool last = (t == nt - 2);
;             const char* a1 = cA + (size_t)(t + 1) * kstep;
;             const char* a2 = last ? nA : cA + (size_t)(t + 2) * kstep; const char* b2 = last ? nB : cB + (size_t)(t + 2) * kstep;
;             const char* a3 = a2 + kstep; const char* b3 = b2 + kstep;
;             if (last && has_next) S.a_ready(nxt);
;             if constexpr (SP2) {
;             PG8_LDB(B0, 0, 0); PG8_LDB(B1, 0, 1); PG8_SCHED; PG8_LDA(At, 0, 0); PG8_STAGE(PG8_SA(1, 1), a1 + hstepA, voffA);
;             PG8_WAIT_V(8); PG8_WAIT_L(0); PG8_BAR; PG8_MMA(0, 0, At, B0); PG8_MMA(0, 1, At, B1); PG8_BAR; PG8_SCHED;
;             PG8_LDA(At, 0, 1); PG8_STAGE(PG8_SB(0, 0), b2, voffB); PG8_STAGE(PG8_SB(0, 1), b2 + hstepB, voffB); PG8_STAGE(PG8_SA(0, 0), a2, voffA);
.LBB0_2014:
	ds_read_b128 v[118:121], v163
	ds_read_b128 v[126:129], v163 offset:1024
	ds_read_b128 v[130:133], v163 offset:2048
	ds_read_b128 v[134:137], v163 offset:3072
	ds_read_b128 v[168:171], v167
	ds_read_b128 v[176:179], v167 offset:1024
	ds_read_b128 v[180:183], v167 offset:2048
	ds_read_b128 v[184:187], v167 offset:3072
	s_add_u32 s38, s36, 0xfff80080
	s_addc_u32 s39, s37, -1
	s_cmp_eq_u32 s65, 28
	s_cselect_b32 s41, s27, s39
	s_cselect_b32 s40, s61, s38
	s_cselect_b32 s39, s25, s64
	s_cselect_b32 s38, s62, s63
	v_lshl_add_u64 v[164:165], s[36:37], 0, v[154:155]
	s_add_i32 m0, s35, 0xc000
	ds_read_b128 v[188:191], v173
	ds_read_b128 v[192:195], v173 offset:1024
	ds_read_b128 v[196:199], v173 offset:2048
	ds_read_b128 v[200:203], v173 offset:3072
	ds_read_b128 v[204:207], v173 offset:4096
	ds_read_b128 v[208:211], v173 offset:5120
	ds_read_b128 v[212:215], v173 offset:6144
	ds_read_b128 v[216:219], v173 offset:7168
	global_load_lds_dwordx4 v[164:165], off
	v_lshl_add_u64 v[164:165], s[36:37], 0, v[156:157]
	s_add_i32 m0, s35, 0xe000
	s_nop 0
	global_load_lds_dwordx4 v[164:165], off
	s_waitcnt vmcnt(8)
	s_waitcnt lgkmcnt(0)
	s_barrier
	s_waitcnt lgkmcnt(0)
	v_mfma_i32_16x16x64_i8 v[142:145], v[118:121], v[188:191], v[142:145]
	v_mfma_i32_16x16x64_i8 v[138:141], v[130:133], v[188:191], v[138:141]
	v_mfma_i32_16x16x64_i8 v[110:113], v[118:121], v[196:199], v[110:113]
	v_mfma_i32_16x16x64_i8 v[106:109], v[130:133], v[196:199], v[106:109]
	v_mfma_i32_16x16x64_i8 v[94:97], v[118:121], v[204:207], v[94:97]
	v_mfma_i32_16x16x64_i8 v[90:93], v[130:133], v[204:207], v[90:93]
	v_mfma_i32_16x16x64_i8 v[78:81], v[118:121], v[212:215], v[78:81]
	v_mfma_i32_16x16x64_i8 v[74:77], v[130:133], v[212:215], v[74:77]
	v_mfma_i32_16x16x64_i8 v[142:145], v[126:129], v[192:195], v[142:145]
	v_mfma_i32_16x16x64_i8 v[138:141], v[134:137], v[192:195], v[138:141]
	v_mfma_i32_16x16x64_i8 v[110:113], v[126:129], v[200:203], v[110:113]
	v_mfma_i32_16x16x64_i8 v[106:109], v[134:137], v[200:203], v[106:109]
	v_mfma_i32_16x16x64_i8 v[94:97], v[126:129], v[208:211], v[94:97]
	v_mfma_i32_16x16x64_i8 v[90:93], v[134:137], v[208:211], v[90:93]
	v_mfma_i32_16x16x64_i8 v[78:81], v[126:129], v[216:219], v[78:81]
	v_mfma_i32_16x16x64_i8 v[74:77], v[134:137], v[216:219], v[74:77]
	v_mfma_i32_16x16x64_i8 v[122:125], v[168:171], v[188:191], v[122:125]
	v_mfma_i32_16x16x64_i8 v[114:117], v[180:183], v[188:191], v[114:117]
	v_mfma_i32_16x16x64_i8 v[102:105], v[168:171], v[196:199], v[102:105]
	v_mfma_i32_16x16x64_i8 v[98:101], v[180:183], v[196:199], v[98:101]
	v_mfma_i32_16x16x64_i8 v[86:89], v[168:171], v[204:207], v[86:89]
	v_mfma_i32_16x16x64_i8 v[82:85], v[180:183], v[204:207], v[82:85]
	v_mfma_i32_16x16x64_i8 v[70:73], v[168:171], v[212:215], v[70:73]
	v_mfma_i32_16x16x64_i8 v[66:69], v[180:183], v[212:215], v[66:69]
	v_mfma_i32_16x16x64_i8 v[122:125], v[176:179], v[192:195], v[122:125]
	v_mfma_i32_16x16x64_i8 v[114:117], v[184:187], v[192:195], v[114:117]
	v_mfma_i32_16x16x64_i8 v[102:105], v[176:179], v[200:203], v[102:105]
	v_mfma_i32_16x16x64_i8 v[98:101], v[184:187], v[200:203], v[98:101]
	v_mfma_i32_16x16x64_i8 v[86:89], v[176:179], v[208:211], v[86:89]
	v_mfma_i32_16x16x64_i8 v[82:85], v[184:187], v[208:211], v[82:85]
	v_mfma_i32_16x16x64_i8 v[70:73], v[176:179], v[216:219], v[70:73]
	v_mfma_i32_16x16x64_i8 v[66:69], v[184:187], v[216:219], v[66:69]
	s_barrier
	s_add_i32 s66, s54, s46
	v_lshl_add_u64 v[164:165], s[38:39], 0, v[148:149]
	s_mov_b32 m0, s66
	ds_read_b128 v[188:191], v173 offset:16384
	ds_read_b128 v[192:195], v173 offset:17408
	ds_read_b128 v[196:199], v173 offset:18432
	ds_read_b128 v[200:203], v173 offset:19456
	ds_read_b128 v[204:207], v173 offset:20480
	ds_read_b128 v[208:211], v173 offset:21504
	ds_read_b128 v[212:215], v173 offset:22528
	ds_read_b128 v[216:219], v173 offset:23552
	global_load_lds_dwordx4 v[164:165], off
	s_add_i32 m0, s66, 0x2000
	s_add_u32 s66, s38, 0x80000
	v_lshl_add_u64 v[220:221], s[38:39], 0, v[152:153]
	s_addc_u32 s67, s39, 0
	s_add_i32 s68, s55, s46
	global_load_lds_dwordx4 v[220:221], off
	v_lshl_add_u64 v[222:223], s[66:67], 0, v[148:149]
	s_mov_b32 m0, s68
	v_lshl_add_u64 v[224:225], s[40:41], 0, v[150:151]
	global_load_lds_dwordx4 v[222:223], off
	v_lshl_add_u64 v[222:223], s[66:67], 0, v[152:153]
	s_add_i32 m0, s68, 0x2000
	s_nop 0
	global_load_lds_dwordx4 v[222:223], off
	v_lshl_add_u64 v[222:223], s[40:41], 0, v[146:147]
	s_mov_b32 m0, s35
	s_nop 0
	global_load_lds_dwordx4 v[222:223], off
	s_mov_b32 m0, s47
	s_nop 0
	global_load_lds_dwordx4 v[224:225], off
	s_waitcnt vmcnt(8)
	s_waitcnt lgkmcnt(0)
	s_barrier
; #define PG8_STAGE(bufoff, gbase, voff) do { _Pragma("unroll") for (int _i = 0; _i < 2; ++_i) \
;         __builtin_amdgcn_global_load_lds((const unsigned*)((const char*)(gbase) + (voff)[_i]), (PG8_LAS unsigned*)(lds + (bufoff) + ldsw + _i * 8192), 16, 0, 0); } while (0)
; #define PG8_LDA(dst, b, h) do { _Pragma("unroll") for (int m = 0; m < 4; ++m) _Pragma("unroll") for (int k = 0; k < 2; ++k) dst[m][k] = *(const PG8_LAS bf16x8*)(lds + PG8_SA(b, h) + aoff + m * 2048 + k * 1024); } while (0)
; #define PG8_LDB(dst, b, h) do { _Pragma("unroll") for (int n = 0; n < 2; ++n) _Pragma("unroll") for (int k = 0; k < 2; ++k) dst[n][k] = *(const PG8_LAS bf16x8*)(lds + PG8_SB(b, h) + boff + n * 2048 + k * 1024); } while (0)
; #define PG8_MMA(ai, bj, At, Bt) do { __builtin_amdgcn_s_setprio(1); _Pragma("unroll") for (int m = 0; m < 4; ++m) _Pragma("unroll") for (int n = 0; n < 2; ++n) _Pragma("unroll") for (int k = 0; k < 2; ++k) \
;         acc[ai][bj][m][n] = mma_<I8>(Bt[n][k], At[m][k], acc[ai][bj][m][n]); __builtin_amdgcn_s_setprio(0); } while (0)
; #define PG8_WAIT_V(n) asm volatile("s_waitcnt vmcnt(" #n ")" ::: "memory")
; #define PG8_WAIT_L(n) asm volatile("s_waitcnt lgkmcnt(" #n ")" ::: "memory")
; #define PG8_BAR __builtin_amdgcn_s_barrier()
; #define PG8_SCHED __builtin_amdgcn_sched_barrier(0)
; template <class Epi, class Sched, bool ALIGN_EPI = false, bool SP2 = false, bool I8 = false>
; __device__ __forceinline__ void gemm_phase(PG8_LAS unsigned char* lds, const Gemm g, const Sched& S, const Epi& E) {
;     ...
;             PG8_WAIT_V(8); PG8_WAIT_L(0); PG8_BAR; PG8_MMA(1, 0, At, B0); PG8_MMA(1, 1, At, B1); PG8_BAR; PG8_SCHED;
;             PG8_LDB(B0, 1, 0); PG8_LDB(B1, 1, 1); PG8_SCHED; PG8_LDA(At, 1, 0); PG8_STAGE(PG8_SA(0, 1), a2 + hstepA, voffA);
;             PG8_WAIT_V(8); PG8_WAIT_L(0); PG8_BAR; PG8_MMA(0, 0, At, B0); PG8_MMA(0, 1, At, B1); PG8_BAR; PG8_SCHED;
	s_waitcnt lgkmcnt(0)
	v_mfma_i32_16x16x64_i8 v[62:65], v[118:121], v[188:191], v[62:65]
	v_mfma_i32_16x16x64_i8 v[58:61], v[130:133], v[188:191], v[58:61]
	v_mfma_i32_16x16x64_i8 v[46:49], v[118:121], v[196:199], v[46:49]
	v_mfma_i32_16x16x64_i8 v[42:45], v[130:133], v[196:199], v[42:45]
	v_mfma_i32_16x16x64_i8 v[30:33], v[118:121], v[204:207], v[30:33]
	v_mfma_i32_16x16x64_i8 v[26:29], v[130:133], v[204:207], v[26:29]
	v_mfma_i32_16x16x64_i8 v[14:17], v[118:121], v[212:215], v[14:17]
	v_mfma_i32_16x16x64_i8 v[10:13], v[130:133], v[212:215], v[10:13]
	v_mfma_i32_16x16x64_i8 v[62:65], v[126:129], v[192:195], v[62:65]
	v_mfma_i32_16x16x64_i8 v[58:61], v[134:137], v[192:195], v[58:61]
	v_mfma_i32_16x16x64_i8 v[46:49], v[126:129], v[200:203], v[46:49]
	v_mfma_i32_16x16x64_i8 v[42:45], v[134:137], v[200:203], v[42:45]
	v_mfma_i32_16x16x64_i8 v[30:33], v[126:129], v[208:211], v[30:33]
	v_mfma_i32_16x16x64_i8 v[26:29], v[134:137], v[208:211], v[26:29]
	v_mfma_i32_16x16x64_i8 v[14:17], v[126:129], v[216:219], v[14:17]
	v_mfma_i32_16x16x64_i8 v[10:13], v[134:137], v[216:219], v[10:13]
	v_mfma_i32_16x16x64_i8 v[54:57], v[168:171], v[188:191], v[54:57]
	v_mfma_i32_16x16x64_i8 v[50:53], v[180:183], v[188:191], v[50:53]
	v_mfma_i32_16x16x64_i8 v[38:41], v[168:171], v[196:199], v[38:41]
	v_mfma_i32_16x16x64_i8 v[34:37], v[180:183], v[196:199], v[34:37]
	v_mfma_i32_16x16x64_i8 v[22:25], v[168:171], v[204:207], v[22:25]
	v_mfma_i32_16x16x64_i8 v[18:21], v[180:183], v[204:207], v[18:21]
	v_mfma_i32_16x16x64_i8 v[6:9], v[168:171], v[212:215], v[6:9]
	v_mfma_i32_16x16x64_i8 v[2:5], v[180:183], v[212:215], v[2:5]
	v_mfma_i32_16x16x64_i8 v[54:57], v[176:179], v[192:195], v[54:57]
	v_mfma_i32_16x16x64_i8 v[50:53], v[184:187], v[192:195], v[50:53]
	v_mfma_i32_16x16x64_i8 v[38:41], v[176:179], v[200:203], v[38:41]
	v_mfma_i32_16x16x64_i8 v[34:37], v[184:187], v[200:203], v[34:37]
	v_mfma_i32_16x16x64_i8 v[22:25], v[176:179], v[208:211], v[22:25]
	v_mfma_i32_16x16x64_i8 v[18:21], v[184:187], v[208:211], v[18:21]
	v_mfma_i32_16x16x64_i8 v[6:9], v[176:179], v[216:219], v[6:9]
	v_mfma_i32_16x16x64_i8 v[2:5], v[184:187], v[216:219], v[2:5]
	s_barrier
	s_add_i32 s66, 0, 0x18000
	s_add_i32 s67, 0, 0x1c000
	v_add_u32_e32 v134, s66, v1
	v_add_u32_e32 v162, s67, v1
	ds_read_b128 v[118:121], v134
	ds_read_b128 v[126:129], v134 offset:1024
	ds_read_b128 v[130:133], v134 offset:2048
	ds_read_b128 v[134:137], v134 offset:3072
	ds_read_b128 v[168:171], v162
	ds_read_b128 v[176:179], v162 offset:1024
	ds_read_b128 v[180:183], v162 offset:2048
	ds_read_b128 v[184:187], v162 offset:3072
	s_add_u32 s40, s40, 0x80000
	s_addc_u32 s41, s41, 0
	s_mov_b32 m0, s48
	v_lshl_add_u64 v[226:227], s[40:41], 0, v[146:147]
	ds_read_b128 v[188:191], v173 offset:32768
	ds_read_b128 v[192:195], v173 offset:33792
	ds_read_b128 v[196:199], v173 offset:34816
	ds_read_b128 v[200:203], v173 offset:35840
	ds_read_b128 v[204:207], v173 offset:36864
	ds_read_b128 v[208:211], v173 offset:37888
	ds_read_b128 v[212:215], v173 offset:38912
	ds_read_b128 v[216:219], v173 offset:39936
	global_load_lds_dwordx4 v[226:227], off
	v_lshl_add_u64 v[226:227], s[40:41], 0, v[150:151]
	s_mov_b32 m0, s49
	s_nop 0
	global_load_lds_dwordx4 v[226:227], off
	s_waitcnt vmcnt(8)
	s_waitcnt lgkmcnt(0)
	s_barrier
	s_waitcnt lgkmcnt(0)
	v_mfma_i32_16x16x64_i8 v[142:145], v[118:121], v[188:191], v[142:145]
	v_mfma_i32_16x16x64_i8 v[138:141], v[130:133], v[188:191], v[138:141]
	v_mfma_i32_16x16x64_i8 v[110:113], v[118:121], v[196:199], v[110:113]
	v_mfma_i32_16x16x64_i8 v[106:109], v[130:133], v[196:199], v[106:109]
	v_mfma_i32_16x16x64_i8 v[94:97], v[118:121], v[204:207], v[94:97]
	v_mfma_i32_16x16x64_i8 v[90:93], v[130:133], v[204:207], v[90:93]
	v_mfma_i32_16x16x64_i8 v[78:81], v[118:121], v[212:215], v[78:81]
	v_mfma_i32_16x16x64_i8 v[74:77], v[130:133], v[212:215], v[74:77]
	v_mfma_i32_16x16x64_i8 v[142:145], v[126:129], v[192:195], v[142:145]
	v_mfma_i32_16x16x64_i8 v[138:141], v[134:137], v[192:195], v[138:141]
	v_mfma_i32_16x16x64_i8 v[110:113], v[126:129], v[200:203], v[110:113]
	v_mfma_i32_16x16x64_i8 v[106:109], v[134:137], v[200:203], v[106:109]
	v_mfma_i32_16x16x64_i8 v[94:97], v[126:129], v[208:211], v[94:97]
	v_mfma_i32_16x16x64_i8 v[90:93], v[134:137], v[208:211], v[90:93]
	v_mfma_i32_16x16x64_i8 v[78:81], v[126:129], v[216:219], v[78:81]
	v_mfma_i32_16x16x64_i8 v[74:77], v[134:137], v[216:219], v[74:77]
	v_mfma_i32_16x16x64_i8 v[122:125], v[168:171], v[188:191], v[122:125]
	v_mfma_i32_16x16x64_i8 v[114:117], v[180:183], v[188:191], v[114:117]
	v_mfma_i32_16x16x64_i8 v[102:105], v[168:171], v[196:199], v[102:105]
	v_mfma_i32_16x16x64_i8 v[98:101], v[180:183], v[196:199], v[98:101]
	v_mfma_i32_16x16x64_i8 v[86:89], v[168:171], v[204:207], v[86:89]
	v_mfma_i32_16x16x64_i8 v[82:85], v[180:183], v[204:207], v[82:85]
	v_mfma_i32_16x16x64_i8 v[70:73], v[168:171], v[212:215], v[70:73]
	v_mfma_i32_16x16x64_i8 v[66:69], v[180:183], v[212:215], v[66:69]
	v_mfma_i32_16x16x64_i8 v[122:125], v[176:179], v[192:195], v[122:125]
	v_mfma_i32_16x16x64_i8 v[114:117], v[184:187], v[192:195], v[114:117]
	v_mfma_i32_16x16x64_i8 v[102:105], v[176:179], v[200:203], v[102:105]
	v_mfma_i32_16x16x64_i8 v[98:101], v[184:187], v[200:203], v[98:101]
	v_mfma_i32_16x16x64_i8 v[86:89], v[176:179], v[208:211], v[86:89]
	v_mfma_i32_16x16x64_i8 v[82:85], v[184:187], v[208:211], v[82:85]
	v_mfma_i32_16x16x64_i8 v[70:73], v[176:179], v[216:219], v[70:73]
	v_mfma_i32_16x16x64_i8 v[66:69], v[184:187], v[216:219], v[66:69]
	s_barrier
; #define PG8_STAGE(bufoff, gbase, voff) do { _Pragma("unroll") for (int _i = 0; _i < 2; ++_i) \
;         __builtin_amdgcn_global_load_lds((const unsigned*)((const char*)(gbase) + (voff)[_i]), (PG8_LAS unsigned*)(lds + (bufoff) + ldsw + _i * 8192), 16, 0, 0); } while (0)
; #define PG8_LDA(dst, b, h) do { _Pragma("unroll") for (int m = 0; m < 4; ++m) _Pragma("unroll") for (int k = 0; k < 2; ++k) dst[m][k] = *(const PG8_LAS bf16x8*)(lds + PG8_SA(b, h) + aoff + m * 2048 + k * 1024); } while (0)
; #define PG8_MMA(ai, bj, At, Bt) do { __builtin_amdgcn_s_setprio(1); _Pragma("unroll") for (int m = 0; m < 4; ++m) _Pragma("unroll") for (int n = 0; n < 2; ++n) _Pragma("unroll") for (int k = 0; k < 2; ++k) \
;         acc[ai][bj][m][n] = mma_<I8>(Bt[n][k], At[m][k], acc[ai][bj][m][n]); __builtin_amdgcn_s_setprio(0); } while (0)
; #define PG8_WAIT_V(n) asm volatile("s_waitcnt vmcnt(" #n ")" ::: "memory")
; #define PG8_WAIT_L(n) asm volatile("s_waitcnt lgkmcnt(" #n ")" ::: "memory")
; #define PG8_BAR __builtin_amdgcn_s_barrier()
; #define PG8_SCHED __builtin_amdgcn_sched_barrier(0)
; template <class Epi, class Sched, bool ALIGN_EPI = false, bool SP2 = false, bool I8 = false>
; __device__ __forceinline__ void gemm_phase(PG8_LAS unsigned char* lds, const Gemm g, const Sched& S, const Epi& E) {
;     ...
;         for (int t = 0; t < nt; t += 2) {
;             const bool last = (t == nt - 2);
;             const char* a1 = cA + (size_t)(t + 1) * kstep;
;             const char* a2 = last ? nA : cA + (size_t)(t + 2) * kstep; const char* b2 = last ? nB : cB + (size_t)(t + 2) * kstep;
;     ...
;             PG8_LDA(At, 1, 1); PG8_STAGE(PG8_SB(1, 0), b3, voffB); PG8_STAGE(PG8_SB(1, 1), b3 + hstepB, voffB); PG8_STAGE(PG8_SA(1, 0), a3, voffA);
;             PG8_WAIT_V(8); PG8_WAIT_L(0); PG8_BAR; PG8_MMA(1, 0, At, B0); PG8_MMA(1, 1, At, B1); PG8_BAR; PG8_SCHED;
	s_add_i32 s40, s66, s46
	v_lshl_add_u64 v[164:165], v[164:165], 0, s[12:13]
	s_mov_b32 m0, s40
	ds_read_b128 v[188:191], v173 offset:49152
	ds_read_b128 v[192:195], v173 offset:50176
	ds_read_b128 v[196:199], v173 offset:51200
	ds_read_b128 v[200:203], v173 offset:52224
	ds_read_b128 v[204:207], v173 offset:53248
	ds_read_b128 v[208:211], v173 offset:54272
	ds_read_b128 v[212:215], v173 offset:55296
	ds_read_b128 v[216:219], v173 offset:56320
	global_load_lds_dwordx4 v[164:165], off
	s_add_i32 m0, s40, 0x2000
	s_add_u32 s38, s38, 0x80080
	v_lshl_add_u64 v[164:165], v[220:221], 0, s[12:13]
	s_addc_u32 s39, s39, 0
	s_add_i32 s40, s67, s46
	global_load_lds_dwordx4 v[164:165], off
	v_lshl_add_u64 v[164:165], s[38:39], 0, v[148:149]
	s_mov_b32 m0, s40
	s_nop 0
	global_load_lds_dwordx4 v[164:165], off
	v_lshl_add_u64 v[164:165], s[38:39], 0, v[152:153]
	s_add_i32 m0, s40, 0x2000
	s_nop 0
	global_load_lds_dwordx4 v[164:165], off
	v_lshl_add_u64 v[164:165], v[222:223], 0, s[12:13]
	s_mov_b32 m0, s51
	s_nop 0
	global_load_lds_dwordx4 v[164:165], off
	v_lshl_add_u64 v[164:165], v[224:225], 0, s[12:13]
	s_mov_b32 m0, s52
	s_nop 0
	global_load_lds_dwordx4 v[164:165], off
	s_waitcnt vmcnt(8)
	s_waitcnt lgkmcnt(0)
	s_barrier
	s_waitcnt lgkmcnt(0)
	v_mfma_i32_16x16x64_i8 v[62:65], v[118:121], v[188:191], v[62:65]
	v_mfma_i32_16x16x64_i8 v[58:61], v[130:133], v[188:191], v[58:61]
	v_mfma_i32_16x16x64_i8 v[46:49], v[118:121], v[196:199], v[46:49]
	v_mfma_i32_16x16x64_i8 v[42:45], v[130:133], v[196:199], v[42:45]
	v_mfma_i32_16x16x64_i8 v[30:33], v[118:121], v[204:207], v[30:33]
	v_mfma_i32_16x16x64_i8 v[26:29], v[130:133], v[204:207], v[26:29]
	v_mfma_i32_16x16x64_i8 v[14:17], v[118:121], v[212:215], v[14:17]
	v_mfma_i32_16x16x64_i8 v[10:13], v[130:133], v[212:215], v[10:13]
	v_mfma_i32_16x16x64_i8 v[62:65], v[126:129], v[192:195], v[62:65]
	v_mfma_i32_16x16x64_i8 v[58:61], v[134:137], v[192:195], v[58:61]
	v_mfma_i32_16x16x64_i8 v[46:49], v[126:129], v[200:203], v[46:49]
	v_mfma_i32_16x16x64_i8 v[42:45], v[134:137], v[200:203], v[42:45]
	v_mfma_i32_16x16x64_i8 v[30:33], v[126:129], v[208:211], v[30:33]
	v_mfma_i32_16x16x64_i8 v[26:29], v[134:137], v[208:211], v[26:29]
	v_mfma_i32_16x16x64_i8 v[14:17], v[126:129], v[216:219], v[14:17]
	v_mfma_i32_16x16x64_i8 v[10:13], v[134:137], v[216:219], v[10:13]
	v_mfma_i32_16x16x64_i8 v[54:57], v[168:171], v[188:191], v[54:57]
	v_mfma_i32_16x16x64_i8 v[50:53], v[180:183], v[188:191], v[50:53]
	v_mfma_i32_16x16x64_i8 v[38:41], v[168:171], v[196:199], v[38:41]
	v_mfma_i32_16x16x64_i8 v[34:37], v[180:183], v[196:199], v[34:37]
	v_mfma_i32_16x16x64_i8 v[22:25], v[168:171], v[204:207], v[22:25]
	v_mfma_i32_16x16x64_i8 v[18:21], v[180:183], v[204:207], v[18:21]
	v_mfma_i32_16x16x64_i8 v[6:9], v[168:171], v[212:215], v[6:9]
	v_mfma_i32_16x16x64_i8 v[2:5], v[180:183], v[212:215], v[2:5]
	v_mfma_i32_16x16x64_i8 v[54:57], v[176:179], v[192:195], v[54:57]
	v_mfma_i32_16x16x64_i8 v[50:53], v[184:187], v[192:195], v[50:53]
	v_mfma_i32_16x16x64_i8 v[38:41], v[176:179], v[200:203], v[38:41]
	v_mfma_i32_16x16x64_i8 v[34:37], v[184:187], v[200:203], v[34:37]
	v_mfma_i32_16x16x64_i8 v[22:25], v[176:179], v[208:211], v[22:25]
	v_mfma_i32_16x16x64_i8 v[18:21], v[184:187], v[208:211], v[18:21]
	v_mfma_i32_16x16x64_i8 v[6:9], v[176:179], v[216:219], v[6:9]
	v_mfma_i32_16x16x64_i8 v[2:5], v[184:187], v[216:219], v[2:5]
	s_barrier
	s_add_i32 s65, s65, 2
	s_add_u32 s36, s36, 0x100
	s_addc_u32 s37, s37, 0
	s_add_u32 s63, s63, 0x100
	s_addc_u32 s64, s64, 0
	s_cmp_gt_u32 s65, 29
	s_cbranch_scc0 .LBB0_2014
	s_and_b64 vcc, exec, s[14:15]
	s_cbranch_vccz .LBB0_2017
	s_barrier

; __global__ void __launch_bounds__(NWAVES * 64, 2) mk_fwd(Args args) {
;     ...
;     if (IN(G_MLPOUT)) {
;         pg8::Gemm g{(const bf16*)(ws + WS_HID), (const bf16*)(ws + WS_WMLPOUT), M, D, DFF, DFF, DFF, 0}; pg8::StaticOrder S; S.init(M, D, F.G, bx);
.LBB0_2075:
	s_cmp_lt_i32 s72, 13
	s_cselect_b64 s[0:1], -1, 0
	s_cmp_gt_i32 s73, 12
	s_cselect_b64 s[2:3], -1, 0
	s_and_b64 s[0:1], s[0:1], s[2:3]
	s_andn2_b64 vcc, exec, s[0:1]
	s_cbranch_vccnz .LBB0_2220
	v_readfirstlane_b32 s98, v0
	s_nop 3
	s_and_b32 s98, s98, 0x3ff
	s_lshr_b32 s98, s98, 6
	s_cmp_ge_u32 s98, 4
	s_cbranch_scc0 .Lprio_mlpout
	s_setprio 1

; #define PG8_STAGE(bufoff, gbase, voff) do { _Pragma("unroll") for (int _i = 0; _i < 2; ++_i) \
;         __builtin_amdgcn_global_load_lds((const unsigned*)((const char*)(gbase) + (voff)[_i]), (PG8_LAS unsigned*)(lds + (bufoff) + ldsw + _i * 8192), 16, 0, 0); } while (0)
; #define PG8_LDA(dst, b, h) do { _Pragma("unroll") for (int m = 0; m < 4; ++m) _Pragma("unroll") for (int k = 0; k < 2; ++k) dst[m][k] = *(const PG8_LAS bf16x8*)(lds + PG8_SA(b, h) + aoff + m * 2048 + k * 1024); } while (0)
; #define PG8_LDB(dst, b, h) do { _Pragma("unroll") for (int n = 0; n < 2; ++n) _Pragma("unroll") for (int k = 0; k < 2; ++k) dst[n][k] = *(const PG8_LAS bf16x8*)(lds + PG8_SB(b, h) + boff + n * 2048 + k * 1024); } while (0)
; #define PG8_MMA(ai, bj, At, Bt) do { __builtin_amdgcn_s_setprio(1); _Pragma("unroll") for (int m = 0; m < 4; ++m) _Pragma("unroll") for (int n = 0; n < 2; ++n) _Pragma("unroll") for (int k = 0; k < 2; ++k) \
;         acc[ai][bj][m][n] = mma_<I8>(Bt[n][k], At[m][k], acc[ai][bj][m][n]); __builtin_amdgcn_s_setprio(0); } while (0)
; #define PG8_WAIT_V(n) asm volatile("s_waitcnt vmcnt(" #n ")" ::: "memory")
; #define PG8_WAIT_L(n) asm volatile("s_waitcnt lgkmcnt(" #n ")" ::: "memory")
; template <class Epi, class Sched, bool ALIGN_EPI = false, bool SP2 = false, bool I8 = false>
; __device__ __forceinline__ void gemm_phase(PG8_LAS unsigned char* lds, const Gemm g, const Sched& S, const Epi& E) {
;     ...
;         for (int t = 0; t < nt; t += 2) {
;             const bool last = (t == nt - 2);
;             const char* a1 = cA + (size_t)(t + 1) * kstep;
;             const char* a2 = last ? nA : cA + (size_t)(t + 2) * kstep; const char* b2 = last ? nB : cB + (size_t)(t + 2) * kstep;
;             const char* a3 = a2 + kstep; const char* b3 = b2 + kstep;
;             if (last && has_next) S.a_ready(nxt);
;             if constexpr (SP2) {
;             PG8_LDB(B0, 0, 0); PG8_LDB(B1, 0, 1); PG8_SCHED; PG8_LDA(At, 0, 0); PG8_STAGE(PG8_SA(1, 1), a1 + hstepA, voffA);
;             PG8_WAIT_V(8); PG8_WAIT_L(0); PG8_BAR; PG8_MMA(0, 0, At, B0); PG8_MMA(0, 1, At, B1); PG8_BAR; PG8_SCHED;
;             PG8_LDA(At, 0, 1); PG8_STAGE(PG8_SB(0, 0), b2, voffB); PG8_STAGE(PG8_SB(0, 1), b2 + hstepB, voffB); PG8_STAGE(PG8_SA(0, 0), a2, voffA);
;             PG8_WAIT_V(8); PG8_WAIT_L(0); PG8_BAR; PG8_MMA(1, 0, At, B0); PG8_MMA(1, 1, At, B1); PG8_BAR; PG8_SCHED;
.LBB0_2092:
	ds_read_b128 v[130:133], v192
	ds_read_b128 v[134:137], v192 offset:1024
	ds_read_b128 v[138:141], v192 offset:2048
	ds_read_b128 v[142:145], v192 offset:3072
	ds_read_b128 v[146:149], v193
	ds_read_b128 v[150:153], v193 offset:1024
	ds_read_b128 v[154:157], v193 offset:2048
	ds_read_b128 v[158:161], v193 offset:3072
	s_add_u32 s28, s8, 0xffc00080
	s_addc_u32 s29, s9, -1
	s_cmpk_eq_i32 s51, 0xfc
	s_cselect_b32 s31, s3, s29
	s_cselect_b32 s30, s7, s28
	s_cselect_b32 s29, s21, s50
	s_cselect_b32 s28, s23, s49
	v_lshl_add_u64 v[190:191], s[8:9], 0, v[174:175]
	s_add_i32 m0, s38, 0xc000
	ds_read_b128 v[162:165], v194
	ds_read_b128 v[166:169], v194 offset:1024
	ds_read_b128 v[182:185], v194 offset:2048
	ds_read_b128 v[186:189], v194 offset:3072
	ds_read_b128 v[196:199], v194 offset:4096
	ds_read_b128 v[200:203], v194 offset:5120
	ds_read_b128 v[204:207], v194 offset:6144
	ds_read_b128 v[208:211], v194 offset:7168
	global_load_lds_dwordx4 v[190:191], off
	v_lshl_add_u64 v[190:191], s[8:9], 0, v[176:177]
	s_add_i32 m0, s38, 0xe000
	s_nop 0
	global_load_lds_dwordx4 v[190:191], off
	s_waitcnt vmcnt(8)
	s_waitcnt lgkmcnt(0)
	s_barrier
	s_waitcnt lgkmcnt(0)
	v_mfma_f32_16x16x32_bf16 v[126:129], v[130:133], v[162:165], v[126:129]
	v_mfma_f32_16x16x32_bf16 v[122:125], v[138:141], v[162:165], v[122:125]
	v_mfma_f32_16x16x32_bf16 v[110:113], v[130:133], v[182:185], v[110:113]
	v_mfma_f32_16x16x32_bf16 v[106:109], v[138:141], v[182:185], v[106:109]
	v_mfma_f32_16x16x32_bf16 v[94:97], v[130:133], v[196:199], v[94:97]
	v_mfma_f32_16x16x32_bf16 v[90:93], v[138:141], v[196:199], v[90:93]
	v_mfma_f32_16x16x32_bf16 v[78:81], v[130:133], v[204:207], v[78:81]
	v_mfma_f32_16x16x32_bf16 v[74:77], v[138:141], v[204:207], v[74:77]
	v_mfma_f32_16x16x32_bf16 v[126:129], v[134:137], v[166:169], v[126:129]
	v_mfma_f32_16x16x32_bf16 v[122:125], v[142:145], v[166:169], v[122:125]
	v_mfma_f32_16x16x32_bf16 v[110:113], v[134:137], v[186:189], v[110:113]
	v_mfma_f32_16x16x32_bf16 v[106:109], v[142:145], v[186:189], v[106:109]
	v_mfma_f32_16x16x32_bf16 v[94:97], v[134:137], v[200:203], v[94:97]
	v_mfma_f32_16x16x32_bf16 v[90:93], v[142:145], v[200:203], v[90:93]
	v_mfma_f32_16x16x32_bf16 v[78:81], v[134:137], v[208:211], v[78:81]
	v_mfma_f32_16x16x32_bf16 v[74:77], v[142:145], v[208:211], v[74:77]
	v_mfma_f32_16x16x32_bf16 v[118:121], v[146:149], v[162:165], v[118:121]
	v_mfma_f32_16x16x32_bf16 v[114:117], v[154:157], v[162:165], v[114:117]
	v_mfma_f32_16x16x32_bf16 v[102:105], v[146:149], v[182:185], v[102:105]
	v_mfma_f32_16x16x32_bf16 v[98:101], v[154:157], v[182:185], v[98:101]
	v_mfma_f32_16x16x32_bf16 v[86:89], v[146:149], v[196:199], v[86:89]
	v_mfma_f32_16x16x32_bf16 v[82:85], v[154:157], v[196:199], v[82:85]
	v_mfma_f32_16x16x32_bf16 v[70:73], v[146:149], v[204:207], v[70:73]
	v_mfma_f32_16x16x32_bf16 v[66:69], v[154:157], v[204:207], v[66:69]
	v_mfma_f32_16x16x32_bf16 v[118:121], v[150:153], v[166:169], v[118:121]
	v_mfma_f32_16x16x32_bf16 v[114:117], v[158:161], v[166:169], v[114:117]
	v_mfma_f32_16x16x32_bf16 v[102:105], v[150:153], v[186:189], v[102:105]
	v_mfma_f32_16x16x32_bf16 v[98:101], v[158:161], v[186:189], v[98:101]
	v_mfma_f32_16x16x32_bf16 v[86:89], v[150:153], v[200:203], v[86:89]
	v_mfma_f32_16x16x32_bf16 v[82:85], v[158:161], v[200:203], v[82:85]
	v_mfma_f32_16x16x32_bf16 v[70:73], v[150:153], v[208:211], v[70:73]
	v_mfma_f32_16x16x32_bf16 v[66:69], v[158:161], v[208:211], v[66:69]
	s_barrier
	s_add_i32 s52, s47, s33
	v_lshl_add_u64 v[190:191], s[28:29], 0, v[170:171]
	s_mov_b32 m0, s52
	ds_read_b128 v[162:165], v194 offset:16384
	ds_read_b128 v[166:169], v194 offset:17408
	ds_read_b128 v[182:185], v194 offset:18432
	ds_read_b128 v[186:189], v194 offset:19456
	ds_read_b128 v[196:199], v194 offset:20480
	ds_read_b128 v[200:203], v194 offset:21504
	ds_read_b128 v[204:207], v194 offset:22528
	ds_read_b128 v[208:211], v194 offset:23552
	global_load_lds_dwordx4 v[190:191], off
	s_add_i32 m0, s52, 0x2000
	s_add_u32 s52, s28, 0x400000
	v_lshl_add_u64 v[212:213], s[28:29], 0, v[172:173]
	s_addc_u32 s53, s29, 0
	s_add_i32 s54, s48, s33
	global_load_lds_dwordx4 v[212:213], off
	v_lshl_add_u64 v[214:215], s[52:53], 0, v[170:171]
	s_mov_b32 m0, s54
	v_lshl_add_u64 v[216:217], s[30:31], 0, v[172:173]
	global_load_lds_dwordx4 v[214:215], off
	v_lshl_add_u64 v[214:215], s[52:53], 0, v[172:173]
	s_add_i32 m0, s54, 0x2000
	s_nop 0
	global_load_lds_dwordx4 v[214:215], off
	v_lshl_add_u64 v[214:215], s[30:31], 0, v[170:171]
	s_mov_b32 m0, s38
	s_nop 0
	global_load_lds_dwordx4 v[214:215], off
	s_mov_b32 m0, s39
	s_nop 0
	global_load_lds_dwordx4 v[216:217], off
	s_waitcnt vmcnt(8)
	s_waitcnt lgkmcnt(0)
	s_barrier
; #define PG8_STAGE(bufoff, gbase, voff) do { _Pragma("unroll") for (int _i = 0; _i < 2; ++_i) \
;         __builtin_amdgcn_global_load_lds((const unsigned*)((const char*)(gbase) + (voff)[_i]), (PG8_LAS unsigned*)(lds + (bufoff) + ldsw + _i * 8192), 16, 0, 0); } while (0)
; #define PG8_LDA(dst, b, h) do { _Pragma("unroll") for (int m = 0; m < 4; ++m) _Pragma("unroll") for (int k = 0; k < 2; ++k) dst[m][k] = *(const PG8_LAS bf16x8*)(lds + PG8_SA(b, h) + aoff + m * 2048 + k * 1024); } while (0)
; #define PG8_LDB(dst, b, h) do { _Pragma("unroll") for (int n = 0; n < 2; ++n) _Pragma("unroll") for (int k = 0; k < 2; ++k) dst[n][k] = *(const PG8_LAS bf16x8*)(lds + PG8_SB(b, h) + boff + n * 2048 + k * 1024); } while (0)
; #define PG8_MMA(ai, bj, At, Bt) do { __builtin_amdgcn_s_setprio(1); _Pragma("unroll") for (int m = 0; m < 4; ++m) _Pragma("unroll") for (int n = 0; n < 2; ++n) _Pragma("unroll") for (int k = 0; k < 2; ++k) \
;         acc[ai][bj][m][n] = mma_<I8>(Bt[n][k], At[m][k], acc[ai][bj][m][n]); __builtin_amdgcn_s_setprio(0); } while (0)
; #define PG8_WAIT_V(n) asm volatile("s_waitcnt vmcnt(" #n ")" ::: "memory")
; #define PG8_WAIT_L(n) asm volatile("s_waitcnt lgkmcnt(" #n ")" ::: "memory")
; #define PG8_BAR __builtin_amdgcn_s_barrier()
; #define PG8_SCHED __builtin_amdgcn_sched_barrier(0)
; template <class Epi, class Sched, bool ALIGN_EPI = false, bool SP2 = false, bool I8 = false>
; __device__ __forceinline__ void gemm_phase(PG8_LAS unsigned char* lds, const Gemm g, const Sched& S, const Epi& E) {
;     ...
;             PG8_WAIT_V(8); PG8_WAIT_L(0); PG8_BAR; PG8_MMA(1, 0, At, B0); PG8_MMA(1, 1, At, B1); PG8_BAR; PG8_SCHED;
;             PG8_LDB(B0, 1, 0); PG8_LDB(B1, 1, 1); PG8_SCHED; PG8_LDA(At, 1, 0); PG8_STAGE(PG8_SA(0, 1), a2 + hstepA, voffA);
;             PG8_WAIT_V(8); PG8_WAIT_L(0); PG8_BAR; PG8_MMA(0, 0, At, B0); PG8_MMA(0, 1, At, B1); PG8_BAR; PG8_SCHED;
	s_waitcnt lgkmcnt(0)
	v_mfma_f32_16x16x32_bf16 v[62:65], v[130:133], v[162:165], v[62:65]
	v_mfma_f32_16x16x32_bf16 v[58:61], v[138:141], v[162:165], v[58:61]
	v_mfma_f32_16x16x32_bf16 v[46:49], v[130:133], v[182:185], v[46:49]
	v_mfma_f32_16x16x32_bf16 v[42:45], v[138:141], v[182:185], v[42:45]
	v_mfma_f32_16x16x32_bf16 v[30:33], v[130:133], v[196:199], v[30:33]
	v_mfma_f32_16x16x32_bf16 v[26:29], v[138:141], v[196:199], v[26:29]
	v_mfma_f32_16x16x32_bf16 v[22:25], v[130:133], v[204:207], v[22:25]
	v_mfma_f32_16x16x32_bf16 v[10:13], v[138:141], v[204:207], v[10:13]
	v_mfma_f32_16x16x32_bf16 v[62:65], v[134:137], v[166:169], v[62:65]
	v_mfma_f32_16x16x32_bf16 v[58:61], v[142:145], v[166:169], v[58:61]
	v_mfma_f32_16x16x32_bf16 v[46:49], v[134:137], v[186:189], v[46:49]
	v_mfma_f32_16x16x32_bf16 v[42:45], v[142:145], v[186:189], v[42:45]
	v_mfma_f32_16x16x32_bf16 v[30:33], v[134:137], v[200:203], v[30:33]
	v_mfma_f32_16x16x32_bf16 v[26:29], v[142:145], v[200:203], v[26:29]
	v_mfma_f32_16x16x32_bf16 v[22:25], v[134:137], v[208:211], v[22:25]
	v_mfma_f32_16x16x32_bf16 v[10:13], v[142:145], v[208:211], v[10:13]
	v_mfma_f32_16x16x32_bf16 v[54:57], v[146:149], v[162:165], v[54:57]
	v_mfma_f32_16x16x32_bf16 v[50:53], v[154:157], v[162:165], v[50:53]
	v_mfma_f32_16x16x32_bf16 v[38:41], v[146:149], v[182:185], v[38:41]
	v_mfma_f32_16x16x32_bf16 v[34:37], v[154:157], v[182:185], v[34:37]
	v_mfma_f32_16x16x32_bf16 v[18:21], v[146:149], v[196:199], v[18:21]
	v_mfma_f32_16x16x32_bf16 v[14:17], v[154:157], v[196:199], v[14:17]
	v_mfma_f32_16x16x32_bf16 v[6:9], v[146:149], v[204:207], v[6:9]
	v_mfma_f32_16x16x32_bf16 v[2:5], v[154:157], v[204:207], v[2:5]
	v_mfma_f32_16x16x32_bf16 v[54:57], v[150:153], v[166:169], v[54:57]
	v_mfma_f32_16x16x32_bf16 v[50:53], v[158:161], v[166:169], v[50:53]
	v_mfma_f32_16x16x32_bf16 v[38:41], v[150:153], v[186:189], v[38:41]
	v_mfma_f32_16x16x32_bf16 v[34:37], v[158:161], v[186:189], v[34:37]
	v_mfma_f32_16x16x32_bf16 v[18:21], v[150:153], v[200:203], v[18:21]
	v_mfma_f32_16x16x32_bf16 v[14:17], v[158:161], v[200:203], v[14:17]
	v_mfma_f32_16x16x32_bf16 v[6:9], v[150:153], v[208:211], v[6:9]
	v_mfma_f32_16x16x32_bf16 v[2:5], v[158:161], v[208:211], v[2:5]
	s_barrier
	s_add_i32 s52, 0, 0x18000
	s_add_i32 s53, 0, 0x1c000
	v_add_u32_e32 v142, s52, v1
	v_add_u32_e32 v158, s53, v1
	ds_read_b128 v[130:133], v142
	ds_read_b128 v[134:137], v142 offset:1024
	ds_read_b128 v[138:141], v142 offset:2048
	ds_read_b128 v[142:145], v142 offset:3072
	ds_read_b128 v[146:149], v158
	ds_read_b128 v[150:153], v158 offset:1024
	ds_read_b128 v[154:157], v158 offset:2048
	ds_read_b128 v[158:161], v158 offset:3072
	s_add_u32 s30, s30, 0x400000
	s_addc_u32 s31, s31, 0
	s_mov_b32 m0, s40
	v_lshl_add_u64 v[218:219], s[30:31], 0, v[170:171]
	ds_read_b128 v[162:165], v194 offset:32768
	ds_read_b128 v[166:169], v194 offset:33792
	ds_read_b128 v[182:185], v194 offset:34816
	ds_read_b128 v[186:189], v194 offset:35840
	ds_read_b128 v[196:199], v194 offset:36864
	ds_read_b128 v[200:203], v194 offset:37888
	ds_read_b128 v[204:207], v194 offset:38912
	ds_read_b128 v[208:211], v194 offset:39936
	global_load_lds_dwordx4 v[218:219], off
	v_lshl_add_u64 v[218:219], s[30:31], 0, v[172:173]
	s_mov_b32 m0, s41
	s_nop 0
	global_load_lds_dwordx4 v[218:219], off
	s_waitcnt vmcnt(8)
	s_waitcnt lgkmcnt(0)
	s_barrier
	s_waitcnt lgkmcnt(0)
	v_mfma_f32_16x16x32_bf16 v[126:129], v[130:133], v[162:165], v[126:129]
	v_mfma_f32_16x16x32_bf16 v[122:125], v[138:141], v[162:165], v[122:125]
	v_mfma_f32_16x16x32_bf16 v[110:113], v[130:133], v[182:185], v[110:113]
	v_mfma_f32_16x16x32_bf16 v[106:109], v[138:141], v[182:185], v[106:109]
	v_mfma_f32_16x16x32_bf16 v[94:97], v[130:133], v[196:199], v[94:97]
	v_mfma_f32_16x16x32_bf16 v[90:93], v[138:141], v[196:199], v[90:93]
	v_mfma_f32_16x16x32_bf16 v[78:81], v[130:133], v[204:207], v[78:81]
	v_mfma_f32_16x16x32_bf16 v[74:77], v[138:141], v[204:207], v[74:77]
	v_mfma_f32_16x16x32_bf16 v[126:129], v[134:137], v[166:169], v[126:129]
	v_mfma_f32_16x16x32_bf16 v[122:125], v[142:145], v[166:169], v[122:125]
	v_mfma_f32_16x16x32_bf16 v[110:113], v[134:137], v[186:189], v[110:113]
	v_mfma_f32_16x16x32_bf16 v[106:109], v[142:145], v[186:189], v[106:109]
	v_mfma_f32_16x16x32_bf16 v[94:97], v[134:137], v[200:203], v[94:97]
	v_mfma_f32_16x16x32_bf16 v[90:93], v[142:145], v[200:203], v[90:93]
	v_mfma_f32_16x16x32_bf16 v[78:81], v[134:137], v[208:211], v[78:81]
	v_mfma_f32_16x16x32_bf16 v[74:77], v[142:145], v[208:211], v[74:77]
	v_mfma_f32_16x16x32_bf16 v[118:121], v[146:149], v[162:165], v[118:121]
	v_mfma_f32_16x16x32_bf16 v[114:117], v[154:157], v[162:165], v[114:117]
	v_mfma_f32_16x16x32_bf16 v[102:105], v[146:149], v[182:185], v[102:105]
	v_mfma_f32_16x16x32_bf16 v[98:101], v[154:157], v[182:185], v[98:101]
	v_mfma_f32_16x16x32_bf16 v[86:89], v[146:149], v[196:199], v[86:89]
	v_mfma_f32_16x16x32_bf16 v[82:85], v[154:157], v[196:199], v[82:85]
	v_mfma_f32_16x16x32_bf16 v[70:73], v[146:149], v[204:207], v[70:73]
	v_mfma_f32_16x16x32_bf16 v[66:69], v[154:157], v[204:207], v[66:69]
	v_mfma_f32_16x16x32_bf16 v[118:121], v[150:153], v[166:169], v[118:121]
	v_mfma_f32_16x16x32_bf16 v[114:117], v[158:161], v[166:169], v[114:117]
	v_mfma_f32_16x16x32_bf16 v[102:105], v[150:153], v[186:189], v[102:105]
	v_mfma_f32_16x16x32_bf16 v[98:101], v[158:161], v[186:189], v[98:101]
	v_mfma_f32_16x16x32_bf16 v[86:89], v[150:153], v[200:203], v[86:89]
	v_mfma_f32_16x16x32_bf16 v[82:85], v[158:161], v[200:203], v[82:85]
	v_mfma_f32_16x16x32_bf16 v[70:73], v[150:153], v[208:211], v[70:73]
	v_mfma_f32_16x16x32_bf16 v[66:69], v[158:161], v[208:211], v[66:69]
	s_barrier
; #define PG8_STAGE(bufoff, gbase, voff) do { _Pragma("unroll") for (int _i = 0; _i < 2; ++_i) \
;         __builtin_amdgcn_global_load_lds((const unsigned*)((const char*)(gbase) + (voff)[_i]), (PG8_LAS unsigned*)(lds + (bufoff) + ldsw + _i * 8192), 16, 0, 0); } while (0)
; #define PG8_LDA(dst, b, h) do { _Pragma("unroll") for (int m = 0; m < 4; ++m) _Pragma("unroll") for (int k = 0; k < 2; ++k) dst[m][k] = *(const PG8_LAS bf16x8*)(lds + PG8_SA(b, h) + aoff + m * 2048 + k * 1024); } while (0)
; #define PG8_MMA(ai, bj, At, Bt) do { __builtin_amdgcn_s_setprio(1); _Pragma("unroll") for (int m = 0; m < 4; ++m) _Pragma("unroll") for (int n = 0; n < 2; ++n) _Pragma("unroll") for (int k = 0; k < 2; ++k) \
;         acc[ai][bj][m][n] = mma_<I8>(Bt[n][k], At[m][k], acc[ai][bj][m][n]); __builtin_amdgcn_s_setprio(0); } while (0)
; #define PG8_WAIT_V(n) asm volatile("s_waitcnt vmcnt(" #n ")" ::: "memory")
; #define PG8_WAIT_L(n) asm volatile("s_waitcnt lgkmcnt(" #n ")" ::: "memory")
; #define PG8_BAR __builtin_amdgcn_s_barrier()
; #define PG8_SCHED __builtin_amdgcn_sched_barrier(0)
; template <class Epi, class Sched, bool ALIGN_EPI = false, bool SP2 = false, bool I8 = false>
; __device__ __forceinline__ void gemm_phase(PG8_LAS unsigned char* lds, const Gemm g, const Sched& S, const Epi& E) {
;     ...
;             PG8_WAIT_V(8); PG8_WAIT_L(0); PG8_BAR; PG8_MMA(0, 0, At, B0); PG8_MMA(0, 1, At, B1); PG8_BAR; PG8_SCHED;
;             PG8_LDA(At, 1, 1); PG8_STAGE(PG8_SB(1, 0), b3, voffB); PG8_STAGE(PG8_SB(1, 1), b3 + hstepB, voffB); PG8_STAGE(PG8_SA(1, 0), a3, voffA);
;             PG8_WAIT_V(8); PG8_WAIT_L(0); PG8_BAR; PG8_MMA(1, 0, At, B0); PG8_MMA(1, 1, At, B1); PG8_BAR; PG8_SCHED;
;     ...
;         if constexpr (ALIGN_EPI) { if (wr == 0) PG8_BAR; }
	s_add_i32 s30, s52, s33
	v_lshl_add_u64 v[190:191], v[190:191], 0, s[14:15]
	s_mov_b32 m0, s30
	ds_read_b128 v[162:165], v194 offset:49152
	ds_read_b128 v[166:169], v194 offset:50176
	ds_read_b128 v[182:185], v194 offset:51200
	ds_read_b128 v[186:189], v194 offset:52224
	ds_read_b128 v[196:199], v194 offset:53248
	ds_read_b128 v[200:203], v194 offset:54272
	ds_read_b128 v[204:207], v194 offset:55296
	ds_read_b128 v[208:211], v194 offset:56320
	global_load_lds_dwordx4 v[190:191], off
	s_add_i32 m0, s30, 0x2000
	s_add_u32 s28, s28, 0x400080
	v_lshl_add_u64 v[190:191], v[212:213], 0, s[14:15]
	s_addc_u32 s29, s29, 0
	s_add_i32 s30, s53, s33
	global_load_lds_dwordx4 v[190:191], off
	v_lshl_add_u64 v[190:191], s[28:29], 0, v[170:171]
	s_mov_b32 m0, s30
	s_nop 0
	global_load_lds_dwordx4 v[190:191], off
	v_lshl_add_u64 v[190:191], s[28:29], 0, v[172:173]
	s_add_i32 m0, s30, 0x2000
	s_nop 0
	global_load_lds_dwordx4 v[190:191], off
	v_lshl_add_u64 v[190:191], v[214:215], 0, s[14:15]
	s_mov_b32 m0, s43
	s_nop 0
	global_load_lds_dwordx4 v[190:191], off
	v_lshl_add_u64 v[190:191], v[216:217], 0, s[14:15]
	s_mov_b32 m0, s44
	s_nop 0
	global_load_lds_dwordx4 v[190:191], off
	s_waitcnt vmcnt(8)
	s_waitcnt lgkmcnt(0)
	s_barrier
	s_waitcnt lgkmcnt(0)
	v_mfma_f32_16x16x32_bf16 v[62:65], v[130:133], v[162:165], v[62:65]
	v_mfma_f32_16x16x32_bf16 v[58:61], v[138:141], v[162:165], v[58:61]
	v_mfma_f32_16x16x32_bf16 v[46:49], v[130:133], v[182:185], v[46:49]
	v_mfma_f32_16x16x32_bf16 v[42:45], v[138:141], v[182:185], v[42:45]
	v_mfma_f32_16x16x32_bf16 v[30:33], v[130:133], v[196:199], v[30:33]
	v_mfma_f32_16x16x32_bf16 v[26:29], v[138:141], v[196:199], v[26:29]
	v_mfma_f32_16x16x32_bf16 v[22:25], v[130:133], v[204:207], v[22:25]
	v_mfma_f32_16x16x32_bf16 v[10:13], v[138:141], v[204:207], v[10:13]
	v_mfma_f32_16x16x32_bf16 v[62:65], v[134:137], v[166:169], v[62:65]
	v_mfma_f32_16x16x32_bf16 v[58:61], v[142:145], v[166:169], v[58:61]
	v_mfma_f32_16x16x32_bf16 v[46:49], v[134:137], v[186:189], v[46:49]
	v_mfma_f32_16x16x32_bf16 v[42:45], v[142:145], v[186:189], v[42:45]
	v_mfma_f32_16x16x32_bf16 v[30:33], v[134:137], v[200:203], v[30:33]
	v_mfma_f32_16x16x32_bf16 v[26:29], v[142:145], v[200:203], v[26:29]
	v_mfma_f32_16x16x32_bf16 v[22:25], v[134:137], v[208:211], v[22:25]
	v_mfma_f32_16x16x32_bf16 v[10:13], v[142:145], v[208:211], v[10:13]
	v_mfma_f32_16x16x32_bf16 v[54:57], v[146:149], v[162:165], v[54:57]
	v_mfma_f32_16x16x32_bf16 v[50:53], v[154:157], v[162:165], v[50:53]
	v_mfma_f32_16x16x32_bf16 v[38:41], v[146:149], v[182:185], v[38:41]
	v_mfma_f32_16x16x32_bf16 v[34:37], v[154:157], v[182:185], v[34:37]
	v_mfma_f32_16x16x32_bf16 v[18:21], v[146:149], v[196:199], v[18:21]
	v_mfma_f32_16x16x32_bf16 v[14:17], v[154:157], v[196:199], v[14:17]
	v_mfma_f32_16x16x32_bf16 v[6:9], v[146:149], v[204:207], v[6:9]
	v_mfma_f32_16x16x32_bf16 v[2:5], v[154:157], v[204:207], v[2:5]
	v_mfma_f32_16x16x32_bf16 v[54:57], v[150:153], v[166:169], v[54:57]
	v_mfma_f32_16x16x32_bf16 v[50:53], v[158:161], v[166:169], v[50:53]
	v_mfma_f32_16x16x32_bf16 v[38:41], v[150:153], v[186:189], v[38:41]
	v_mfma_f32_16x16x32_bf16 v[34:37], v[158:161], v[186:189], v[34:37]
	v_mfma_f32_16x16x32_bf16 v[18:21], v[150:153], v[200:203], v[18:21]
	v_mfma_f32_16x16x32_bf16 v[14:17], v[158:161], v[200:203], v[14:17]
	v_mfma_f32_16x16x32_bf16 v[6:9], v[150:153], v[208:211], v[6:9]
	v_mfma_f32_16x16x32_bf16 v[2:5], v[158:161], v[208:211], v[2:5]
	s_barrier
	s_add_i32 s51, s51, 2
	s_add_u32 s8, s8, 0x100
	s_addc_u32 s9, s9, 0
	s_add_u32 s49, s49, 0x100
	s_addc_u32 s50, s50, 0
	s_cmpk_gt_u32 s51, 0xfd
	s_cbranch_scc0 .LBB0_2092
	s_and_b64 vcc, exec, s[16:17]
	s_cbranch_vccz .LBB0_2095
	s_barrier

; __device__ __forceinline__ void rows_bf16_to_i8(Frame& F, const bf16* XBp, const unsigned* rmax, unsigned* X8, float* sx, int pitch4 = D / 4) {
;     const int gw = F.vcu * NWAVES + F.wave, NGW = F.G * NWAVES, lane = F.lane;
;     v4u w[8], wn[8]; unsigned rb = 0, rbn = 0;
;     int m = gw;
;     if (m < M) { const v4u* src = (const v4u*)(XBp + (size_t)m * D) + lane; rb = rmax[m];
; #pragma unroll
;         for (int j = 0; j < 8; ++j) w[j] = src[64 * j]; }
;     for (; m < M; m += NGW) {
;         const int mn = m + NGW;
;         if (mn < M) { const v4u* src = (const v4u*)(XBp + (size_t)mn * D) + lane; rbn = rmax[mn];
; #pragma unroll
;             for (int j = 0; j < 8; ++j) wn[j] = src[64 * j]; }
.LBB0_2220:
	s_setprio 0
	s_cmp_lt_i32 s72, 14
	s_cselect_b64 s[0:1], -1, 0
	s_cmp_gt_i32 s73, 13
	s_cselect_b64 s[2:3], -1, 0
	s_and_b64 s[0:1], s[0:1], s[2:3]
	s_andn2_b64 vcc, exec, s[0:1]
	s_cbranch_vccnz .LBB0_2304
	v_readlane_b32 s0, v254, 5
	s_lshl_b32 s0, s0, 3
	v_readlane_b32 s1, v254, 39
	s_add_i32 s0, s0, s1
	s_cmpk_gt_i32 s0, 0x3fff
	s_cbranch_scc1 .LBB0_2228
	s_ashr_i32 s1, s0, 31
	s_lshl_b32 s2, s70, 3
	s_lshl_b64 s[4:5], s[0:1], 13
	v_readlane_b32 s6, v254, 40
	v_readlane_b32 s7, v254, 41
	s_add_u32 s4, s6, s4
	s_addc_u32 s5, s7, s5
	v_lshlrev_b32_e32 v66, 4, v232
	v_mov_b32_e32 v67, 0
	s_lshl_b64 s[6:7], s[0:1], 2
	s_waitcnt vmcnt(0) lgkmcnt(0)
	v_lshl_add_u64 v[2:3], s[4:5], 0, v[66:67]
	s_add_u32 s8, s96, s6
	s_movk_i32 s3, 0x1000
	s_addc_u32 s9, s97, s7
	v_mov_b32_e32 v4, 0xd0000
	v_add_co_u32_e32 v2, vcc, s3, v2
	global_load_dwordx4 v[58:61], v66, s[4:5] offset:1024
	global_load_dwordx4 v[54:57], v66, s[4:5] offset:2048
	global_load_dwordx4 v[50:53], v66, s[4:5] offset:3072
	v_addc_co_u32_e32 v3, vcc, 0, v3, vcc
	global_load_dword v1, v4, s[8:9]
	global_load_dwordx4 v[46:49], v[2:3], off
	global_load_dwordx4 v[42:45], v[2:3], off offset:1024
	global_load_dwordx4 v[38:41], v[2:3], off offset:2048
	global_load_dwordx4 v[62:65], v66, s[4:5]
	global_load_dwordx4 v[34:37], v[2:3], off offset:3072
	s_add_u32 s16, s6, 0x4d4c0000
	s_addc_u32 s17, s7, 0
	s_add_i32 s10, s0, s2
	s_ashr_i32 s3, s2, 31
	s_lshl_b64 s[8:9], s[0:1], 12
	s_ashr_i32 s11, s10, 31
	s_lshl_b64 s[6:7], s[2:3], 2
	v_lshl_or_b32 v68, v232, 3, s8
	v_mov_b32_e32 v69, s9
	s_lshl_b64 s[8:9], s[2:3], 12
	s_lshl_b64 s[12:13], s[10:11], 2
	s_add_u32 s1, s12, 0xd0000
	s_addc_u32 s18, s13, 0
	s_lshl_b64 s[10:11], s[10:11], 13
	v_cmp_eq_u32_e64 s[4:5], 0, v232
	v_or_b32_e32 v70, s10, v66
	v_mov_b32_e32 v71, s11
	s_lshl_b64 s[10:11], s[2:3], 13
	s_mov_b32 s3, 0x42fe0000
	s_mov_b32 s19, 0xc0c0500
	s_mov_b32 s20, 0x40c0c00
	s_mov_b32 s21, 0x8200000
	v_mov_b32_e32 v66, 0
	s_branch .LBB0_2224

; __global__ void __launch_bounds__(NWAVES * 64, 2) mk_fwd(Args args) {
;     ...
;         pg8::Gemm g{(const bf16*)(ws + WS_PB), (const bf16*)(ws + WS_WPLEP), M, D, PLE, PLE, PLE, 0}; pg8::StaticOrder S; S.init(M, D, F.G, bx);
;         pg8::EpiB<0> E{(bf16*)(ws + WS_PP), D, nullptr, nullptr, nullptr, nullptr};
;         pg8::gemm_phase<pg8::EpiB<0>, pg8::StaticOrder, true, true>(F.lds + RING_OFF, g, S, E);
.LBB0_2228:
	v_readfirstlane_b32 s98, v0
	s_nop 3
	s_and_b32 s98, s98, 0x3ff
	s_lshr_b32 s98, s98, 6
	s_cmp_ge_u32 s98, 4
	s_cbranch_scc0 .Lprio_gpp
	s_setprio 1

; #define PG8_STAGE(bufoff, gbase, voff) do { _Pragma("unroll") for (int _i = 0; _i < 2; ++_i) \
;         __builtin_amdgcn_global_load_lds((const unsigned*)((const char*)(gbase) + (voff)[_i]), (PG8_LAS unsigned*)(lds + (bufoff) + ldsw + _i * 8192), 16, 0, 0); } while (0)
; #define PG8_LDA(dst, b, h) do { _Pragma("unroll") for (int m = 0; m < 4; ++m) _Pragma("unroll") for (int k = 0; k < 2; ++k) dst[m][k] = *(const PG8_LAS bf16x8*)(lds + PG8_SA(b, h) + aoff + m * 2048 + k * 1024); } while (0)
; #define PG8_LDB(dst, b, h) do { _Pragma("unroll") for (int n = 0; n < 2; ++n) _Pragma("unroll") for (int k = 0; k < 2; ++k) dst[n][k] = *(const PG8_LAS bf16x8*)(lds + PG8_SB(b, h) + boff + n * 2048 + k * 1024); } while (0)
; #define PG8_MMA(ai, bj, At, Bt) do { __builtin_amdgcn_s_setprio(1); _Pragma("unroll") for (int m = 0; m < 4; ++m) _Pragma("unroll") for (int n = 0; n < 2; ++n) _Pragma("unroll") for (int k = 0; k < 2; ++k) \
;         acc[ai][bj][m][n] = mma_<I8>(Bt[n][k], At[m][k], acc[ai][bj][m][n]); __builtin_amdgcn_s_setprio(0); } while (0)
; #define PG8_WAIT_V(n) asm volatile("s_waitcnt vmcnt(" #n ")" ::: "memory")
; #define PG8_WAIT_L(n) asm volatile("s_waitcnt lgkmcnt(" #n ")" ::: "memory")
; template <class Epi, class Sched, bool ALIGN_EPI = false, bool SP2 = false, bool I8 = false>
; __device__ __forceinline__ void gemm_phase(PG8_LAS unsigned char* lds, const Gemm g, const Sched& S, const Epi& E) {
;     ...
;         for (int t = 0; t < nt; t += 2) {
;             const bool last = (t == nt - 2);
;             const char* a1 = cA + (size_t)(t + 1) * kstep;
;             const char* a2 = last ? nA : cA + (size_t)(t + 2) * kstep; const char* b2 = last ? nB : cB + (size_t)(t + 2) * kstep;
;             const char* a3 = a2 + kstep; const char* b3 = b2 + kstep;
;             if (last && has_next) S.a_ready(nxt);
;             if constexpr (SP2) {
;             PG8_LDB(B0, 0, 0); PG8_LDB(B1, 0, 1); PG8_SCHED; PG8_LDA(At, 0, 0); PG8_STAGE(PG8_SA(1, 1), a1 + hstepA, voffA);
;             PG8_WAIT_V(8); PG8_WAIT_L(0); PG8_BAR; PG8_MMA(0, 0, At, B0); PG8_MMA(0, 1, At, B1); PG8_BAR; PG8_SCHED;
;             PG8_LDA(At, 0, 1); PG8_STAGE(PG8_SB(0, 0), b2, voffB); PG8_STAGE(PG8_SB(0, 1), b2 + hstepB, voffB); PG8_STAGE(PG8_SA(0, 0), a2, voffA);
;             PG8_WAIT_V(8); PG8_WAIT_L(0); PG8_BAR; PG8_MMA(1, 0, At, B0); PG8_MMA(1, 1, At, B1); PG8_BAR; PG8_SCHED;
.LBB0_2244:
	ds_read_b128 v[2:5], v146
	ds_read_b128 v[6:9], v146 offset:1024
	ds_read_b128 v[10:13], v146 offset:2048
	ds_read_b128 v[14:17], v146 offset:3072
	ds_read_b128 v[18:21], v147
	ds_read_b128 v[22:25], v147 offset:1024
	ds_read_b128 v[26:29], v147 offset:2048
	ds_read_b128 v[30:33], v147 offset:3072
	s_ashr_i32 s21, s20, 31
	s_lshl_b64 s[22:23], s[20:21], 17
	s_add_u32 s22, s33, s22
	s_addc_u32 s23, s38, s23
	s_and_b64 s[24:25], s[4:5], exec
	s_cselect_b32 s37, s23, s29
	s_cselect_b32 s36, s22, s28
	s_ashr_i32 s19, s18, 31
	s_lshl_b64 s[24:25], s[18:19], 17
	s_add_u32 s24, s39, s24
	s_addc_u32 s25, s40, s25
	s_and_b64 s[34:35], s[4:5], exec
	s_cselect_b32 s35, s25, s31
	s_cselect_b32 s34, s24, s30
	s_add_u32 s52, s28, 0x10080
	s_addc_u32 s53, s29, 0
	s_add_i32 s56, s27, 0xc000
	v_lshl_add_u64 v[66:67], s[52:53], 0, v[130:131]
	s_mov_b32 m0, s56
	s_add_i32 s19, s27, 0xe000
	ds_read_b128 v[34:37], v148
	ds_read_b128 v[38:41], v148 offset:1024
	ds_read_b128 v[42:45], v148 offset:2048
	ds_read_b128 v[46:49], v148 offset:3072
	ds_read_b128 v[50:53], v148 offset:4096
	ds_read_b128 v[54:57], v148 offset:5120
	ds_read_b128 v[58:61], v148 offset:6144
	ds_read_b128 v[62:65], v148 offset:7168
	global_load_lds_dwordx4 v[66:67], off
	v_lshl_add_u64 v[66:67], s[52:53], 0, v[134:135]
	s_mov_b32 m0, s19
	s_nop 0
	global_load_lds_dwordx4 v[66:67], off
	s_waitcnt vmcnt(8)
	s_waitcnt lgkmcnt(0)
	s_barrier
	s_waitcnt lgkmcnt(0)
	v_mfma_f32_16x16x32_bf16 v[66:69], v[2:5], v[34:37], 0
	v_mfma_f32_16x16x32_bf16 v[70:73], v[10:13], v[34:37], 0
	v_mfma_f32_16x16x32_bf16 v[74:77], v[2:5], v[42:45], 0
	v_mfma_f32_16x16x32_bf16 v[78:81], v[10:13], v[42:45], 0
	v_mfma_f32_16x16x32_bf16 v[82:85], v[2:5], v[50:53], 0
	v_mfma_f32_16x16x32_bf16 v[86:89], v[10:13], v[50:53], 0
	v_mfma_f32_16x16x32_bf16 v[90:93], v[2:5], v[58:61], 0
	v_mfma_f32_16x16x32_bf16 v[94:97], v[10:13], v[58:61], 0
	v_mfma_f32_16x16x32_bf16 v[66:69], v[6:9], v[38:41], v[66:69]
	v_mfma_f32_16x16x32_bf16 v[70:73], v[14:17], v[38:41], v[70:73]
	v_mfma_f32_16x16x32_bf16 v[74:77], v[6:9], v[46:49], v[74:77]
	v_mfma_f32_16x16x32_bf16 v[78:81], v[14:17], v[46:49], v[78:81]
	v_mfma_f32_16x16x32_bf16 v[82:85], v[6:9], v[54:57], v[82:85]
	v_mfma_f32_16x16x32_bf16 v[86:89], v[14:17], v[54:57], v[86:89]
	v_mfma_f32_16x16x32_bf16 v[90:93], v[6:9], v[62:65], v[90:93]
	v_mfma_f32_16x16x32_bf16 v[94:97], v[14:17], v[62:65], v[94:97]
	v_mfma_f32_16x16x32_bf16 v[98:101], v[18:21], v[34:37], 0
	v_mfma_f32_16x16x32_bf16 v[34:37], v[26:29], v[34:37], 0
	v_mfma_f32_16x16x32_bf16 v[98:101], v[22:25], v[38:41], v[98:101]
	v_mfma_f32_16x16x32_bf16 v[34:37], v[30:33], v[38:41], v[34:37]
	v_mfma_f32_16x16x32_bf16 v[38:41], v[18:21], v[42:45], 0
	v_mfma_f32_16x16x32_bf16 v[42:45], v[26:29], v[42:45], 0
	v_mfma_f32_16x16x32_bf16 v[38:41], v[22:25], v[46:49], v[38:41]
	v_mfma_f32_16x16x32_bf16 v[42:45], v[30:33], v[46:49], v[42:45]
	v_mfma_f32_16x16x32_bf16 v[46:49], v[18:21], v[50:53], 0
	v_mfma_f32_16x16x32_bf16 v[50:53], v[26:29], v[50:53], 0
	v_mfma_f32_16x16x32_bf16 v[46:49], v[22:25], v[54:57], v[46:49]
	v_mfma_f32_16x16x32_bf16 v[50:53], v[30:33], v[54:57], v[50:53]
	v_mfma_f32_16x16x32_bf16 v[54:57], v[18:21], v[58:61], 0
	v_mfma_f32_16x16x32_bf16 v[58:61], v[26:29], v[58:61], 0
	v_mfma_f32_16x16x32_bf16 v[54:57], v[22:25], v[62:65], v[54:57]
	v_mfma_f32_16x16x32_bf16 v[58:61], v[30:33], v[62:65], v[58:61]
	s_barrier
	s_add_i32 s54, s48, s41
	v_lshl_add_u64 v[210:211], s[30:31], 0, v[132:133]
	s_add_i32 s21, s54, 0x2000
	v_lshl_add_u64 v[142:143], v[210:211], 0, s[12:13]
	s_mov_b32 m0, s54
	v_lshl_add_u64 v[212:213], s[30:31], 0, v[136:137]
	s_add_u32 s58, s30, 0x10100
	ds_read_b128 v[62:65], v148 offset:16384
	ds_read_b128 v[102:105], v148 offset:17408
	ds_read_b128 v[106:109], v148 offset:18432
	ds_read_b128 v[110:113], v148 offset:19456
	ds_read_b128 v[114:117], v148 offset:20480
	ds_read_b128 v[118:121], v148 offset:21504
	ds_read_b128 v[122:125], v148 offset:22528
	ds_read_b128 v[126:129], v148 offset:23552
	global_load_lds_dwordx4 v[142:143], off
	v_lshl_add_u64 v[142:143], v[212:213], 0, s[12:13]
	s_mov_b32 m0, s21
	s_addc_u32 s59, s31, 0
	s_add_i32 s52, s49, s41
	global_load_lds_dwordx4 v[142:143], off
	v_lshl_add_u64 v[142:143], s[58:59], 0, v[132:133]
	s_mov_b32 m0, s52
	s_add_i32 s53, s52, 0x2000
	global_load_lds_dwordx4 v[142:143], off
	v_lshl_add_u64 v[142:143], s[58:59], 0, v[136:137]
	s_mov_b32 m0, s53
	v_lshl_add_u64 v[214:215], s[28:29], 0, v[130:131]
	global_load_lds_dwordx4 v[142:143], off
	v_lshl_add_u64 v[142:143], v[214:215], 0, s[12:13]
	s_mov_b32 m0, s27
	v_lshl_add_u64 v[216:217], s[28:29], 0, v[134:135]
	global_load_lds_dwordx4 v[142:143], off
	v_lshl_add_u64 v[142:143], v[216:217], 0, s[12:13]
	s_mov_b32 m0, s42
	s_nop 0
	global_load_lds_dwordx4 v[142:143], off
	s_waitcnt vmcnt(8)
	s_waitcnt lgkmcnt(0)
	s_barrier
; #define PG8_STAGE(bufoff, gbase, voff) do { _Pragma("unroll") for (int _i = 0; _i < 2; ++_i) \
;         __builtin_amdgcn_global_load_lds((const unsigned*)((const char*)(gbase) + (voff)[_i]), (PG8_LAS unsigned*)(lds + (bufoff) + ldsw + _i * 8192), 16, 0, 0); } while (0)
; #define PG8_LDA(dst, b, h) do { _Pragma("unroll") for (int m = 0; m < 4; ++m) _Pragma("unroll") for (int k = 0; k < 2; ++k) dst[m][k] = *(const PG8_LAS bf16x8*)(lds + PG8_SA(b, h) + aoff + m * 2048 + k * 1024); } while (0)
; #define PG8_LDB(dst, b, h) do { _Pragma("unroll") for (int n = 0; n < 2; ++n) _Pragma("unroll") for (int k = 0; k < 2; ++k) dst[n][k] = *(const PG8_LAS bf16x8*)(lds + PG8_SB(b, h) + boff + n * 2048 + k * 1024); } while (0)
; #define PG8_MMA(ai, bj, At, Bt) do { __builtin_amdgcn_s_setprio(1); _Pragma("unroll") for (int m = 0; m < 4; ++m) _Pragma("unroll") for (int n = 0; n < 2; ++n) _Pragma("unroll") for (int k = 0; k < 2; ++k) \
;         acc[ai][bj][m][n] = mma_<I8>(Bt[n][k], At[m][k], acc[ai][bj][m][n]); __builtin_amdgcn_s_setprio(0); } while (0)
; #define PG8_WAIT_V(n) asm volatile("s_waitcnt vmcnt(" #n ")" ::: "memory")
; #define PG8_WAIT_L(n) asm volatile("s_waitcnt lgkmcnt(" #n ")" ::: "memory")
; #define PG8_BAR __builtin_amdgcn_s_barrier()
; #define PG8_SCHED __builtin_amdgcn_sched_barrier(0)
; template <class Epi, class Sched, bool ALIGN_EPI = false, bool SP2 = false, bool I8 = false>
; __device__ __forceinline__ void gemm_phase(PG8_LAS unsigned char* lds, const Gemm g, const Sched& S, const Epi& E) {
;     ...
;             PG8_WAIT_V(8); PG8_WAIT_L(0); PG8_BAR; PG8_MMA(1, 0, At, B0); PG8_MMA(1, 1, At, B1); PG8_BAR; PG8_SCHED;
;             PG8_LDB(B0, 1, 0); PG8_LDB(B1, 1, 1); PG8_SCHED; PG8_LDA(At, 1, 0); PG8_STAGE(PG8_SA(0, 1), a2 + hstepA, voffA);
;             PG8_WAIT_V(8); PG8_WAIT_L(0); PG8_BAR; PG8_MMA(0, 0, At, B0); PG8_MMA(0, 1, At, B1); PG8_BAR; PG8_SCHED;
	s_waitcnt lgkmcnt(0)
	v_mfma_f32_16x16x32_bf16 v[142:145], v[2:5], v[62:65], 0
	v_mfma_f32_16x16x32_bf16 v[154:157], v[2:5], v[106:109], 0
	v_mfma_f32_16x16x32_bf16 v[162:165], v[2:5], v[114:117], 0
	v_mfma_f32_16x16x32_bf16 v[2:5], v[2:5], v[122:125], 0
	v_mfma_f32_16x16x32_bf16 v[142:145], v[6:9], v[102:105], v[142:145]
	v_mfma_f32_16x16x32_bf16 v[154:157], v[6:9], v[110:113], v[154:157]
	v_mfma_f32_16x16x32_bf16 v[162:165], v[6:9], v[118:121], v[162:165]
	v_mfma_f32_16x16x32_bf16 v[2:5], v[6:9], v[126:129], v[2:5]
	v_mfma_f32_16x16x32_bf16 v[6:9], v[10:13], v[122:125], 0
	v_mfma_f32_16x16x32_bf16 v[150:153], v[10:13], v[62:65], 0
	v_mfma_f32_16x16x32_bf16 v[158:161], v[10:13], v[106:109], 0
	v_mfma_f32_16x16x32_bf16 v[166:169], v[10:13], v[114:117], 0
	v_mfma_f32_16x16x32_bf16 v[6:9], v[14:17], v[126:129], v[6:9]
	v_mfma_f32_16x16x32_bf16 v[150:153], v[14:17], v[102:105], v[150:153]
	v_mfma_f32_16x16x32_bf16 v[158:161], v[14:17], v[110:113], v[158:161]
	v_mfma_f32_16x16x32_bf16 v[166:169], v[14:17], v[118:121], v[166:169]
	v_mfma_f32_16x16x32_bf16 v[10:13], v[18:21], v[62:65], 0
	v_mfma_f32_16x16x32_bf16 v[14:17], v[26:29], v[62:65], 0
	v_mfma_f32_16x16x32_bf16 v[10:13], v[22:25], v[102:105], v[10:13]
	v_mfma_f32_16x16x32_bf16 v[14:17], v[30:33], v[102:105], v[14:17]
	v_mfma_f32_16x16x32_bf16 v[62:65], v[18:21], v[106:109], 0
	v_mfma_f32_16x16x32_bf16 v[102:105], v[26:29], v[106:109], 0
	v_mfma_f32_16x16x32_bf16 v[106:109], v[18:21], v[114:117], 0
	v_mfma_f32_16x16x32_bf16 v[18:21], v[18:21], v[122:125], 0
	v_mfma_f32_16x16x32_bf16 v[62:65], v[22:25], v[110:113], v[62:65]
	v_mfma_f32_16x16x32_bf16 v[102:105], v[30:33], v[110:113], v[102:105]
	v_mfma_f32_16x16x32_bf16 v[106:109], v[22:25], v[118:121], v[106:109]
	v_mfma_f32_16x16x32_bf16 v[110:113], v[26:29], v[114:117], 0
	v_mfma_f32_16x16x32_bf16 v[18:21], v[22:25], v[126:129], v[18:21]
	v_mfma_f32_16x16x32_bf16 v[22:25], v[26:29], v[122:125], 0
	v_mfma_f32_16x16x32_bf16 v[110:113], v[30:33], v[118:121], v[110:113]
	v_mfma_f32_16x16x32_bf16 v[22:25], v[30:33], v[126:129], v[22:25]
	s_barrier
	s_add_i32 s57, 0, 0x18000
	s_add_i32 s60, 0, 0x1c000
	v_add_u32_e32 v149, s57, v1
	v_add_u32_e32 v230, s60, v1
	ds_read_b128 v[26:29], v149
	ds_read_b128 v[30:33], v149 offset:1024
	ds_read_b128 v[114:117], v149 offset:2048
	ds_read_b128 v[118:121], v149 offset:3072
	ds_read_b128 v[122:125], v230
	ds_read_b128 v[126:129], v230 offset:1024
	ds_read_b128 v[170:173], v230 offset:2048
	ds_read_b128 v[174:177], v230 offset:3072
	s_add_u32 s58, s28, 0x10100
	s_addc_u32 s59, s29, 0
	s_mov_b32 m0, s43
	v_lshl_add_u64 v[218:219], s[58:59], 0, v[130:131]
	ds_read_b128 v[178:181], v148 offset:32768
	ds_read_b128 v[182:185], v148 offset:33792
	ds_read_b128 v[186:189], v148 offset:34816
	ds_read_b128 v[190:193], v148 offset:35840
	ds_read_b128 v[194:197], v148 offset:36864
	ds_read_b128 v[198:201], v148 offset:37888
	ds_read_b128 v[202:205], v148 offset:38912
	ds_read_b128 v[206:209], v148 offset:39936
	global_load_lds_dwordx4 v[218:219], off
	v_lshl_add_u64 v[218:219], s[58:59], 0, v[134:135]
	s_mov_b32 m0, s44
	s_nop 0
	global_load_lds_dwordx4 v[218:219], off
	s_waitcnt vmcnt(8)
	s_waitcnt lgkmcnt(0)
	s_barrier
	s_waitcnt lgkmcnt(0)
	v_mfma_f32_16x16x32_bf16 v[66:69], v[26:29], v[178:181], v[66:69]
	v_mfma_f32_16x16x32_bf16 v[70:73], v[114:117], v[178:181], v[70:73]
	v_mfma_f32_16x16x32_bf16 v[74:77], v[26:29], v[186:189], v[74:77]
	v_mfma_f32_16x16x32_bf16 v[78:81], v[114:117], v[186:189], v[78:81]
	v_mfma_f32_16x16x32_bf16 v[82:85], v[26:29], v[194:197], v[82:85]
	v_mfma_f32_16x16x32_bf16 v[86:89], v[114:117], v[194:197], v[86:89]
	v_mfma_f32_16x16x32_bf16 v[90:93], v[26:29], v[202:205], v[90:93]
	v_mfma_f32_16x16x32_bf16 v[94:97], v[114:117], v[202:205], v[94:97]
	v_mfma_f32_16x16x32_bf16 v[66:69], v[30:33], v[182:185], v[66:69]
	v_mfma_f32_16x16x32_bf16 v[70:73], v[118:121], v[182:185], v[70:73]
	v_mfma_f32_16x16x32_bf16 v[74:77], v[30:33], v[190:193], v[74:77]
	v_mfma_f32_16x16x32_bf16 v[78:81], v[118:121], v[190:193], v[78:81]
	v_mfma_f32_16x16x32_bf16 v[82:85], v[30:33], v[198:201], v[82:85]
	v_mfma_f32_16x16x32_bf16 v[86:89], v[118:121], v[198:201], v[86:89]
	v_mfma_f32_16x16x32_bf16 v[90:93], v[30:33], v[206:209], v[90:93]
	v_mfma_f32_16x16x32_bf16 v[94:97], v[118:121], v[206:209], v[94:97]
	v_mfma_f32_16x16x32_bf16 v[98:101], v[122:125], v[178:181], v[98:101]
	v_mfma_f32_16x16x32_bf16 v[34:37], v[170:173], v[178:181], v[34:37]
	v_mfma_f32_16x16x32_bf16 v[38:41], v[122:125], v[186:189], v[38:41]
	v_mfma_f32_16x16x32_bf16 v[42:45], v[170:173], v[186:189], v[42:45]
	v_mfma_f32_16x16x32_bf16 v[46:49], v[122:125], v[194:197], v[46:49]
	v_mfma_f32_16x16x32_bf16 v[50:53], v[170:173], v[194:197], v[50:53]
	v_mfma_f32_16x16x32_bf16 v[54:57], v[122:125], v[202:205], v[54:57]
	v_mfma_f32_16x16x32_bf16 v[58:61], v[170:173], v[202:205], v[58:61]
	v_mfma_f32_16x16x32_bf16 v[98:101], v[126:129], v[182:185], v[98:101]
	v_mfma_f32_16x16x32_bf16 v[34:37], v[174:177], v[182:185], v[34:37]
	v_mfma_f32_16x16x32_bf16 v[38:41], v[126:129], v[190:193], v[38:41]
	v_mfma_f32_16x16x32_bf16 v[42:45], v[174:177], v[190:193], v[42:45]
	v_mfma_f32_16x16x32_bf16 v[46:49], v[126:129], v[198:201], v[46:49]
	v_mfma_f32_16x16x32_bf16 v[50:53], v[174:177], v[198:201], v[50:53]
	v_mfma_f32_16x16x32_bf16 v[54:57], v[126:129], v[206:209], v[54:57]
	v_mfma_f32_16x16x32_bf16 v[58:61], v[174:177], v[206:209], v[58:61]
	s_barrier
; #define PG8_STAGE(bufoff, gbase, voff) do { _Pragma("unroll") for (int _i = 0; _i < 2; ++_i) \
;         __builtin_amdgcn_global_load_lds((const unsigned*)((const char*)(gbase) + (voff)[_i]), (PG8_LAS unsigned*)(lds + (bufoff) + ldsw + _i * 8192), 16, 0, 0); } while (0)
; #define PG8_LDA(dst, b, h) do { _Pragma("unroll") for (int m = 0; m < 4; ++m) _Pragma("unroll") for (int k = 0; k < 2; ++k) dst[m][k] = *(const PG8_LAS bf16x8*)(lds + PG8_SA(b, h) + aoff + m * 2048 + k * 1024); } while (0)
; #define PG8_LDB(dst, b, h) do { _Pragma("unroll") for (int n = 0; n < 2; ++n) _Pragma("unroll") for (int k = 0; k < 2; ++k) dst[n][k] = *(const PG8_LAS bf16x8*)(lds + PG8_SB(b, h) + boff + n * 2048 + k * 1024); } while (0)
; #define PG8_MMA(ai, bj, At, Bt) do { __builtin_amdgcn_s_setprio(1); _Pragma("unroll") for (int m = 0; m < 4; ++m) _Pragma("unroll") for (int n = 0; n < 2; ++n) _Pragma("unroll") for (int k = 0; k < 2; ++k) \
;         acc[ai][bj][m][n] = mma_<I8>(Bt[n][k], At[m][k], acc[ai][bj][m][n]); __builtin_amdgcn_s_setprio(0); } while (0)
; #define PG8_WAIT_V(n) asm volatile("s_waitcnt vmcnt(" #n ")" ::: "memory")
; template <class Epi, class Sched, bool ALIGN_EPI = false, bool SP2 = false, bool I8 = false>
; __device__ __forceinline__ void gemm_phase(PG8_LAS unsigned char* lds, const Gemm g, const Sched& S, const Epi& E) {
;     ...
;             PG8_LDB(B0, 0, 0); PG8_LDB(B1, 0, 1); PG8_SCHED; PG8_LDA(At, 0, 0); PG8_STAGE(PG8_SA(1, 1), a1 + hstepA, voffA);
;             PG8_WAIT_V(8); PG8_WAIT_L(0); PG8_BAR; PG8_MMA(0, 0, At, B0); PG8_MMA(0, 1, At, B1); PG8_BAR; PG8_SCHED;
;             PG8_LDA(At, 0, 1); PG8_STAGE(PG8_SB(0, 0), b2, voffB); PG8_STAGE(PG8_SB(0, 1), b2 + hstepB, voffB); PG8_STAGE(PG8_SA(0, 0), a2, voffA);
;             PG8_WAIT_V(8); PG8_WAIT_L(0); PG8_BAR; PG8_MMA(1, 0, At, B0); PG8_MMA(1, 1, At, B1); PG8_BAR; PG8_SCHED;
;             PG8_LDB(B0, 1, 0); PG8_LDB(B1, 1, 1); PG8_SCHED; PG8_LDA(At, 1, 0); PG8_STAGE(PG8_SA(0, 1), a2 + hstepA, voffA);
;             PG8_WAIT_V(8); PG8_WAIT_L(0); PG8_BAR; PG8_MMA(0, 0, At, B0); PG8_MMA(0, 1, At, B1); PG8_BAR; PG8_SCHED;
;             PG8_LDA(At, 1, 1); PG8_STAGE(PG8_SB(1, 0), b3, voffB); PG8_STAGE(PG8_SB(1, 1), b3 + hstepB, voffB); PG8_STAGE(PG8_SA(1, 0), a3, voffA);
;             PG8_WAIT_V(8); PG8_WAIT_L(0); PG8_BAR; PG8_MMA(1, 0, At, B0); PG8_MMA(1, 1, At, B1); PG8_BAR; PG8_SCHED;
	s_add_i32 s57, s57, s41
	s_add_i32 s55, s57, 0x2000
	v_lshl_add_u64 v[210:211], v[210:211], 0, s[14:15]
	s_mov_b32 m0, s57
	s_add_u32 s58, s30, 0x10180
	ds_read_b128 v[178:181], v148 offset:49152
	ds_read_b128 v[182:185], v148 offset:50176
	ds_read_b128 v[186:189], v148 offset:51200
	ds_read_b128 v[190:193], v148 offset:52224
	ds_read_b128 v[194:197], v148 offset:53248
	ds_read_b128 v[198:201], v148 offset:54272
	ds_read_b128 v[202:205], v148 offset:55296
	ds_read_b128 v[206:209], v148 offset:56320
	global_load_lds_dwordx4 v[210:211], off
	v_lshl_add_u64 v[210:211], v[212:213], 0, s[14:15]
	s_mov_b32 m0, s55
	s_addc_u32 s59, s31, 0
	s_add_i32 s30, s60, s41
	global_load_lds_dwordx4 v[210:211], off
	v_lshl_add_u64 v[210:211], s[58:59], 0, v[132:133]
	s_mov_b32 m0, s30
	s_add_i32 s31, s30, 0x2000
	global_load_lds_dwordx4 v[210:211], off
	v_lshl_add_u64 v[210:211], s[58:59], 0, v[136:137]
	s_mov_b32 m0, s31
	s_nop 0
	global_load_lds_dwordx4 v[210:211], off
	v_lshl_add_u64 v[210:211], v[214:215], 0, s[14:15]
	s_mov_b32 m0, s45
	s_nop 0
	global_load_lds_dwordx4 v[210:211], off
	v_lshl_add_u64 v[210:211], v[216:217], 0, s[14:15]
	s_mov_b32 m0, s46
	s_nop 0
	global_load_lds_dwordx4 v[210:211], off
	s_waitcnt vmcnt(8)
	s_waitcnt lgkmcnt(0)
	s_barrier
	s_waitcnt lgkmcnt(0)
	v_mfma_f32_16x16x32_bf16 v[2:5], v[26:29], v[202:205], v[2:5]
	v_mfma_f32_16x16x32_bf16 v[6:9], v[114:117], v[202:205], v[6:9]
	v_mfma_f32_16x16x32_bf16 v[142:145], v[26:29], v[178:181], v[142:145]
	v_mfma_f32_16x16x32_bf16 v[150:153], v[114:117], v[178:181], v[150:153]
	v_mfma_f32_16x16x32_bf16 v[154:157], v[26:29], v[186:189], v[154:157]
	v_mfma_f32_16x16x32_bf16 v[158:161], v[114:117], v[186:189], v[158:161]
	v_mfma_f32_16x16x32_bf16 v[162:165], v[26:29], v[194:197], v[162:165]
	v_mfma_f32_16x16x32_bf16 v[166:169], v[114:117], v[194:197], v[166:169]
	v_mfma_f32_16x16x32_bf16 v[2:5], v[30:33], v[206:209], v[2:5]
	v_mfma_f32_16x16x32_bf16 v[6:9], v[118:121], v[206:209], v[6:9]
	v_mfma_f32_16x16x32_bf16 v[142:145], v[30:33], v[182:185], v[142:145]
	v_mfma_f32_16x16x32_bf16 v[150:153], v[118:121], v[182:185], v[150:153]
	v_mfma_f32_16x16x32_bf16 v[154:157], v[30:33], v[190:193], v[154:157]
	v_mfma_f32_16x16x32_bf16 v[158:161], v[118:121], v[190:193], v[158:161]
	v_mfma_f32_16x16x32_bf16 v[162:165], v[30:33], v[198:201], v[162:165]
	v_mfma_f32_16x16x32_bf16 v[166:169], v[118:121], v[198:201], v[166:169]
	v_mfma_f32_16x16x32_bf16 v[10:13], v[122:125], v[178:181], v[10:13]
	v_mfma_f32_16x16x32_bf16 v[14:17], v[170:173], v[178:181], v[14:17]
	v_mfma_f32_16x16x32_bf16 v[26:29], v[122:125], v[186:189], v[62:65]
	v_mfma_f32_16x16x32_bf16 v[30:33], v[170:173], v[186:189], v[102:105]
	v_mfma_f32_16x16x32_bf16 v[62:65], v[122:125], v[194:197], v[106:109]
	v_mfma_f32_16x16x32_bf16 v[102:105], v[170:173], v[194:197], v[110:113]
	v_mfma_f32_16x16x32_bf16 v[18:21], v[122:125], v[202:205], v[18:21]
	v_mfma_f32_16x16x32_bf16 v[22:25], v[170:173], v[202:205], v[22:25]
	v_mfma_f32_16x16x32_bf16 v[10:13], v[126:129], v[182:185], v[10:13]
	v_mfma_f32_16x16x32_bf16 v[14:17], v[174:177], v[182:185], v[14:17]
	v_mfma_f32_16x16x32_bf16 v[26:29], v[126:129], v[190:193], v[26:29]
	v_mfma_f32_16x16x32_bf16 v[30:33], v[174:177], v[190:193], v[30:33]
	v_mfma_f32_16x16x32_bf16 v[62:65], v[126:129], v[198:201], v[62:65]
	v_mfma_f32_16x16x32_bf16 v[102:105], v[174:177], v[198:201], v[102:105]
	v_mfma_f32_16x16x32_bf16 v[18:21], v[126:129], v[206:209], v[18:21]
	v_mfma_f32_16x16x32_bf16 v[22:25], v[174:177], v[206:209], v[22:25]
	s_barrier
	ds_read_b128 v[106:109], v146
	ds_read_b128 v[110:113], v146 offset:1024
	ds_read_b128 v[114:117], v146 offset:2048
	ds_read_b128 v[118:121], v146 offset:3072
	ds_read_b128 v[122:125], v147
	ds_read_b128 v[126:129], v147 offset:1024
	ds_read_b128 v[170:173], v147 offset:2048
	ds_read_b128 v[174:177], v147 offset:3072
	s_add_u32 s28, s28, 0x10180
	s_addc_u32 s29, s29, 0
	s_mov_b32 m0, s56
	v_lshl_add_u64 v[210:211], s[28:29], 0, v[130:131]
	ds_read_b128 v[178:181], v148
	ds_read_b128 v[182:185], v148 offset:1024
	ds_read_b128 v[186:189], v148 offset:2048
	ds_read_b128 v[190:193], v148 offset:3072
	ds_read_b128 v[194:197], v148 offset:4096
	ds_read_b128 v[198:201], v148 offset:5120
	ds_read_b128 v[202:205], v148 offset:6144
	ds_read_b128 v[206:209], v148 offset:7168
	global_load_lds_dwordx4 v[210:211], off
	v_lshl_add_u64 v[210:211], s[28:29], 0, v[134:135]
	s_mov_b32 m0, s19
	s_nop 0
	global_load_lds_dwordx4 v[210:211], off
	s_waitcnt vmcnt(8)
	s_waitcnt lgkmcnt(0)
	s_barrier
; #define PG8_STAGE(bufoff, gbase, voff) do { _Pragma("unroll") for (int _i = 0; _i < 2; ++_i) \
;         __builtin_amdgcn_global_load_lds((const unsigned*)((const char*)(gbase) + (voff)[_i]), (PG8_LAS unsigned*)(lds + (bufoff) + ldsw + _i * 8192), 16, 0, 0); } while (0)
; #define PG8_LDA(dst, b, h) do { _Pragma("unroll") for (int m = 0; m < 4; ++m) _Pragma("unroll") for (int k = 0; k < 2; ++k) dst[m][k] = *(const PG8_LAS bf16x8*)(lds + PG8_SA(b, h) + aoff + m * 2048 + k * 1024); } while (0)
; #define PG8_LDB(dst, b, h) do { _Pragma("unroll") for (int n = 0; n < 2; ++n) _Pragma("unroll") for (int k = 0; k < 2; ++k) dst[n][k] = *(const PG8_LAS bf16x8*)(lds + PG8_SB(b, h) + boff + n * 2048 + k * 1024); } while (0)
; #define PG8_MMA(ai, bj, At, Bt) do { __builtin_amdgcn_s_setprio(1); _Pragma("unroll") for (int m = 0; m < 4; ++m) _Pragma("unroll") for (int n = 0; n < 2; ++n) _Pragma("unroll") for (int k = 0; k < 2; ++k) \
;         acc[ai][bj][m][n] = mma_<I8>(Bt[n][k], At[m][k], acc[ai][bj][m][n]); __builtin_amdgcn_s_setprio(0); } while (0)
; #define PG8_WAIT_V(n) asm volatile("s_waitcnt vmcnt(" #n ")" ::: "memory")
; #define PG8_WAIT_L(n) asm volatile("s_waitcnt lgkmcnt(" #n ")" ::: "memory")
; #define PG8_BAR __builtin_amdgcn_s_barrier()
; #define PG8_SCHED __builtin_amdgcn_sched_barrier(0)
; template <class Epi, class Sched, bool ALIGN_EPI = false, bool SP2 = false, bool I8 = false>
; __device__ __forceinline__ void gemm_phase(PG8_LAS unsigned char* lds, const Gemm g, const Sched& S, const Epi& E) {
;     ...
;             PG8_WAIT_V(8); PG8_WAIT_L(0); PG8_BAR; PG8_MMA(0, 0, At, B0); PG8_MMA(0, 1, At, B1); PG8_BAR; PG8_SCHED;
;             PG8_LDA(At, 0, 1); PG8_STAGE(PG8_SB(0, 0), b2, voffB); PG8_STAGE(PG8_SB(0, 1), b2 + hstepB, voffB); PG8_STAGE(PG8_SA(0, 0), a2, voffA);
;             PG8_WAIT_V(8); PG8_WAIT_L(0); PG8_BAR; PG8_MMA(1, 0, At, B0); PG8_MMA(1, 1, At, B1); PG8_BAR; PG8_SCHED;
;             PG8_LDB(B0, 1, 0); PG8_LDB(B1, 1, 1); PG8_SCHED; PG8_LDA(At, 1, 0); PG8_STAGE(PG8_SA(0, 1), a2 + hstepA, voffA);
;             PG8_WAIT_V(8); PG8_WAIT_L(0); PG8_BAR; PG8_MMA(0, 0, At, B0); PG8_MMA(0, 1, At, B1); PG8_BAR; PG8_SCHED;
	s_waitcnt lgkmcnt(0)
	v_mfma_f32_16x16x32_bf16 v[90:93], v[106:109], v[202:205], v[90:93]
	v_mfma_f32_16x16x32_bf16 v[66:69], v[106:109], v[178:181], v[66:69]
	v_mfma_f32_16x16x32_bf16 v[70:73], v[114:117], v[178:181], v[70:73]
	v_mfma_f32_16x16x32_bf16 v[74:77], v[106:109], v[186:189], v[74:77]
	v_mfma_f32_16x16x32_bf16 v[78:81], v[114:117], v[186:189], v[78:81]
	v_mfma_f32_16x16x32_bf16 v[82:85], v[106:109], v[194:197], v[82:85]
	v_mfma_f32_16x16x32_bf16 v[86:89], v[114:117], v[194:197], v[86:89]
	v_mfma_f32_16x16x32_bf16 v[210:213], v[110:113], v[206:209], v[90:93]
	v_mfma_f32_16x16x32_bf16 v[90:93], v[114:117], v[202:205], v[94:97]
	v_mfma_f32_16x16x32_bf16 v[66:69], v[110:113], v[182:185], v[66:69]
	v_mfma_f32_16x16x32_bf16 v[70:73], v[118:121], v[182:185], v[70:73]
	v_mfma_f32_16x16x32_bf16 v[74:77], v[110:113], v[190:193], v[74:77]
	v_mfma_f32_16x16x32_bf16 v[78:81], v[118:121], v[190:193], v[78:81]
	v_mfma_f32_16x16x32_bf16 v[82:85], v[110:113], v[198:201], v[82:85]
	v_mfma_f32_16x16x32_bf16 v[86:89], v[118:121], v[198:201], v[86:89]
	v_mfma_f32_16x16x32_bf16 v[94:97], v[118:121], v[206:209], v[90:93]
	v_mfma_f32_16x16x32_bf16 v[50:53], v[170:173], v[194:197], v[50:53]
	v_mfma_f32_16x16x32_bf16 v[90:93], v[122:125], v[178:181], v[98:101]
	v_mfma_f32_16x16x32_bf16 v[34:37], v[170:173], v[178:181], v[34:37]
	v_mfma_f32_16x16x32_bf16 v[38:41], v[122:125], v[186:189], v[38:41]
	v_mfma_f32_16x16x32_bf16 v[42:45], v[170:173], v[186:189], v[42:45]
	v_mfma_f32_16x16x32_bf16 v[46:49], v[122:125], v[194:197], v[46:49]
	v_mfma_f32_16x16x32_bf16 v[178:181], v[174:177], v[198:201], v[50:53]
	v_mfma_f32_16x16x32_bf16 v[50:53], v[122:125], v[202:205], v[54:57]
	v_mfma_f32_16x16x32_bf16 v[34:37], v[174:177], v[182:185], v[34:37]
	v_mfma_f32_16x16x32_bf16 v[38:41], v[126:129], v[190:193], v[38:41]
	v_mfma_f32_16x16x32_bf16 v[42:45], v[174:177], v[190:193], v[42:45]
	v_mfma_f32_16x16x32_bf16 v[46:49], v[126:129], v[198:201], v[46:49]
	v_mfma_f32_16x16x32_bf16 v[54:57], v[126:129], v[206:209], v[50:53]
	v_mfma_f32_16x16x32_bf16 v[50:53], v[170:173], v[202:205], v[58:61]
	v_mfma_f32_16x16x32_bf16 v[214:217], v[126:129], v[182:185], v[90:93]
	v_mfma_f32_16x16x32_bf16 v[182:185], v[174:177], v[206:209], v[50:53]
	s_barrier
	s_mov_b32 m0, s54
	v_lshl_add_u64 v[250:251], s[34:35], 0, v[132:133]
	s_add_u32 s28, s34, 0x10000
	s_nop 0
	ds_read_b128 v[50:53], v148 offset:16384
	ds_read_b128 v[58:61], v148 offset:17408
	ds_read_b128 v[90:93], v148 offset:18432
	ds_read_b128 v[98:101], v148 offset:19456
	ds_read_b128 v[186:189], v148 offset:20480
	ds_read_b128 v[190:193], v148 offset:21504
	ds_read_b128 v[194:197], v148 offset:22528
	ds_read_b128 v[198:201], v148 offset:23552
	global_load_lds_dwordx4 v[250:251], off
	v_lshl_add_u64 v[252:253], s[34:35], 0, v[136:137]
	s_mov_b32 m0, s21
	s_addc_u32 s29, s35, 0
	global_load_lds_dwordx4 v[252:253], off
	v_lshl_add_u64 v[202:203], s[28:29], 0, v[132:133]
	s_mov_b32 m0, s52
	v_lshl_add_u64 v[138:139], s[36:37], 0, v[130:131]
	global_load_lds_dwordx4 v[202:203], off
	v_lshl_add_u64 v[202:203], s[28:29], 0, v[136:137]
	s_mov_b32 m0, s53
	v_lshl_add_u64 v[140:141], s[36:37], 0, v[134:135]
	global_load_lds_dwordx4 v[202:203], off
	s_mov_b32 m0, s27
	s_nop 0
	global_load_lds_dwordx4 v[138:139], off
	s_mov_b32 m0, s42
	s_nop 0
	global_load_lds_dwordx4 v[140:141], off
	s_waitcnt vmcnt(8)
	s_waitcnt lgkmcnt(0)
	s_barrier
	s_waitcnt lgkmcnt(0)
	v_mfma_f32_16x16x32_bf16 v[2:5], v[106:109], v[194:197], v[2:5]
	v_mfma_f32_16x16x32_bf16 v[6:9], v[114:117], v[194:197], v[6:9]
	v_mfma_f32_16x16x32_bf16 v[142:145], v[106:109], v[50:53], v[142:145]
	v_mfma_f32_16x16x32_bf16 v[150:153], v[114:117], v[50:53], v[150:153]
	v_mfma_f32_16x16x32_bf16 v[154:157], v[106:109], v[90:93], v[154:157]
	v_mfma_f32_16x16x32_bf16 v[158:161], v[114:117], v[90:93], v[158:161]
	v_mfma_f32_16x16x32_bf16 v[162:165], v[106:109], v[186:189], v[162:165]
	v_mfma_f32_16x16x32_bf16 v[166:169], v[114:117], v[186:189], v[166:169]
	v_mfma_f32_16x16x32_bf16 v[2:5], v[110:113], v[198:201], v[2:5]
	v_mfma_f32_16x16x32_bf16 v[6:9], v[118:121], v[198:201], v[6:9]
	v_mfma_f32_16x16x32_bf16 v[142:145], v[110:113], v[58:61], v[142:145]
	v_mfma_f32_16x16x32_bf16 v[150:153], v[118:121], v[58:61], v[150:153]
	v_mfma_f32_16x16x32_bf16 v[154:157], v[110:113], v[98:101], v[154:157]
	v_mfma_f32_16x16x32_bf16 v[158:161], v[118:121], v[98:101], v[158:161]
	v_mfma_f32_16x16x32_bf16 v[162:165], v[110:113], v[190:193], v[162:165]
	v_mfma_f32_16x16x32_bf16 v[166:169], v[118:121], v[190:193], v[166:169]
	v_mfma_f32_16x16x32_bf16 v[10:13], v[122:125], v[50:53], v[10:13]
	v_mfma_f32_16x16x32_bf16 v[202:205], v[126:129], v[58:61], v[10:13]
	v_mfma_f32_16x16x32_bf16 v[10:13], v[170:173], v[50:53], v[14:17]
	v_mfma_f32_16x16x32_bf16 v[14:17], v[174:177], v[58:61], v[10:13]
	v_mfma_f32_16x16x32_bf16 v[10:13], v[122:125], v[90:93], v[26:29]
	v_mfma_f32_16x16x32_bf16 v[206:209], v[126:129], v[98:101], v[10:13]
	v_mfma_f32_16x16x32_bf16 v[10:13], v[170:173], v[90:93], v[30:33]
	v_mfma_f32_16x16x32_bf16 v[30:33], v[174:177], v[98:101], v[10:13]
	v_mfma_f32_16x16x32_bf16 v[10:13], v[122:125], v[186:189], v[62:65]
	v_mfma_f32_16x16x32_bf16 v[218:221], v[126:129], v[190:193], v[10:13]
	v_mfma_f32_16x16x32_bf16 v[10:13], v[170:173], v[186:189], v[102:105]
	v_mfma_f32_16x16x32_bf16 v[186:189], v[174:177], v[190:193], v[10:13]
	v_mfma_f32_16x16x32_bf16 v[10:13], v[122:125], v[194:197], v[18:21]
	v_mfma_f32_16x16x32_bf16 v[190:193], v[126:129], v[198:201], v[10:13]
	v_mfma_f32_16x16x32_bf16 v[10:13], v[170:173], v[194:197], v[22:25]
	v_mfma_f32_16x16x32_bf16 v[170:173], v[174:177], v[198:201], v[10:13]
	s_barrier
; #define PG8_STAGE(bufoff, gbase, voff) do { _Pragma("unroll") for (int _i = 0; _i < 2; ++_i) \
;         __builtin_amdgcn_global_load_lds((const unsigned*)((const char*)(gbase) + (voff)[_i]), (PG8_LAS unsigned*)(lds + (bufoff) + ldsw + _i * 8192), 16, 0, 0); } while (0)
; #define PG8_LDA(dst, b, h) do { _Pragma("unroll") for (int m = 0; m < 4; ++m) _Pragma("unroll") for (int k = 0; k < 2; ++k) dst[m][k] = *(const PG8_LAS bf16x8*)(lds + PG8_SA(b, h) + aoff + m * 2048 + k * 1024); } while (0)
; #define PG8_MMA(ai, bj, At, Bt) do { __builtin_amdgcn_s_setprio(1); _Pragma("unroll") for (int m = 0; m < 4; ++m) _Pragma("unroll") for (int n = 0; n < 2; ++n) _Pragma("unroll") for (int k = 0; k < 2; ++k) \
;         acc[ai][bj][m][n] = mma_<I8>(Bt[n][k], At[m][k], acc[ai][bj][m][n]); __builtin_amdgcn_s_setprio(0); } while (0)
; #define PG8_WAIT_V(n) asm volatile("s_waitcnt vmcnt(" #n ")" ::: "memory")
; #define PG8_WAIT_L(n) asm volatile("s_waitcnt lgkmcnt(" #n ")" ::: "memory")
; #define PG8_BAR __builtin_amdgcn_s_barrier()
; #define PG8_SCHED __builtin_amdgcn_sched_barrier(0)
; template <class Epi, class Sched, bool ALIGN_EPI = false, bool SP2 = false, bool I8 = false>
; __device__ __forceinline__ void gemm_phase(PG8_LAS unsigned char* lds, const Gemm g, const Sched& S, const Epi& E) {
;     ...
;             PG8_WAIT_V(8); PG8_WAIT_L(0); PG8_BAR; PG8_MMA(0, 0, At, B0); PG8_MMA(0, 1, At, B1); PG8_BAR; PG8_SCHED;
;             PG8_LDA(At, 1, 1); PG8_STAGE(PG8_SB(1, 0), b3, voffB); PG8_STAGE(PG8_SB(1, 1), b3 + hstepB, voffB); PG8_STAGE(PG8_SA(1, 0), a3, voffA);
;             PG8_WAIT_V(8); PG8_WAIT_L(0); PG8_BAR; PG8_MMA(1, 0, At, B0); PG8_MMA(1, 1, At, B1); PG8_BAR; PG8_SCHED;
;     ...
;         if constexpr (ALIGN_EPI) { if (wr == 0) PG8_BAR; }
	s_nop 4
	ds_read_b128 v[10:13], v149
	ds_read_b128 v[22:25], v149 offset:1024
	ds_read_b128 v[174:177], v149 offset:2048
	ds_read_b128 v[194:197], v149 offset:3072
	ds_read_b128 v[198:201], v230
	ds_read_b128 v[222:225], v230 offset:1024
	ds_read_b128 v[226:229], v230 offset:2048
	ds_read_b128 v[230:233], v230 offset:3072
	s_add_u32 s28, s36, 0x10000
	s_addc_u32 s29, s37, 0
	s_mov_b32 m0, s43
	v_lshl_add_u64 v[50:51], s[28:29], 0, v[130:131]
	ds_read_b128 v[18:21], v148 offset:32768
	ds_read_b128 v[26:29], v148 offset:33792
	ds_read_b128 v[62:65], v148 offset:34816
	ds_read_b128 v[102:105], v148 offset:35840
	ds_read_b128 v[234:237], v148 offset:36864
	ds_read_b128 v[238:241], v148 offset:37888
	ds_read_b128 v[242:245], v148 offset:38912
	ds_read_b128 v[246:249], v148 offset:39936
	global_load_lds_dwordx4 v[50:51], off
	v_lshl_add_u64 v[50:51], s[28:29], 0, v[134:135]
	s_mov_b32 m0, s44
	s_nop 0
	global_load_lds_dwordx4 v[50:51], off
	s_waitcnt vmcnt(8)
	s_waitcnt lgkmcnt(0)
	s_barrier
	s_waitcnt lgkmcnt(0)
	v_mfma_f32_16x16x32_bf16 v[50:53], v[10:13], v[18:21], v[66:69]
	v_mfma_f32_16x16x32_bf16 v[122:125], v[22:25], v[26:29], v[50:53]
	v_mfma_f32_16x16x32_bf16 v[50:53], v[174:177], v[18:21], v[70:73]
	v_mfma_f32_16x16x32_bf16 v[114:117], v[194:197], v[26:29], v[50:53]
	v_mfma_f32_16x16x32_bf16 v[50:53], v[10:13], v[62:65], v[74:77]
	v_mfma_f32_16x16x32_bf16 v[106:109], v[22:25], v[102:105], v[50:53]
	v_mfma_f32_16x16x32_bf16 v[50:53], v[174:177], v[62:65], v[78:81]
	v_mfma_f32_16x16x32_bf16 v[98:101], v[194:197], v[102:105], v[50:53]
	v_mfma_f32_16x16x32_bf16 v[50:53], v[10:13], v[234:237], v[82:85]
	v_mfma_f32_16x16x32_bf16 v[90:93], v[22:25], v[238:241], v[50:53]
	v_mfma_f32_16x16x32_bf16 v[50:53], v[174:177], v[234:237], v[86:89]
	v_mfma_f32_16x16x32_bf16 v[82:85], v[194:197], v[238:241], v[50:53]
	v_mfma_f32_16x16x32_bf16 v[50:53], v[10:13], v[242:245], v[210:213]
	v_mfma_f32_16x16x32_bf16 v[58:61], v[22:25], v[246:249], v[50:53]
	v_mfma_f32_16x16x32_bf16 v[50:53], v[174:177], v[242:245], v[94:97]
	v_mfma_f32_16x16x32_bf16 v[50:53], v[194:197], v[246:249], v[50:53]
	v_mfma_f32_16x16x32_bf16 v[66:69], v[198:201], v[18:21], v[214:217]
	v_mfma_f32_16x16x32_bf16 v[18:21], v[226:229], v[18:21], v[34:37]
	v_mfma_f32_16x16x32_bf16 v[118:121], v[230:233], v[26:29], v[18:21]
	v_mfma_f32_16x16x32_bf16 v[18:21], v[198:201], v[62:65], v[38:41]
	v_mfma_f32_16x16x32_bf16 v[110:113], v[222:225], v[102:105], v[18:21]
	v_mfma_f32_16x16x32_bf16 v[18:21], v[226:229], v[62:65], v[42:45]
	v_mfma_f32_16x16x32_bf16 v[102:105], v[230:233], v[102:105], v[18:21]
	v_mfma_f32_16x16x32_bf16 v[18:21], v[198:201], v[234:237], v[46:49]
	v_mfma_f32_16x16x32_bf16 v[94:97], v[222:225], v[238:241], v[18:21]
	v_mfma_f32_16x16x32_bf16 v[18:21], v[226:229], v[234:237], v[178:181]
	v_mfma_f32_16x16x32_bf16 v[86:89], v[230:233], v[238:241], v[18:21]
	v_mfma_f32_16x16x32_bf16 v[18:21], v[198:201], v[242:245], v[54:57]
	v_mfma_f32_16x16x32_bf16 v[62:65], v[222:225], v[246:249], v[18:21]
	v_mfma_f32_16x16x32_bf16 v[18:21], v[226:229], v[242:245], v[182:185]
	v_mfma_f32_16x16x32_bf16 v[126:129], v[222:225], v[26:29], v[66:69]
	v_mfma_f32_16x16x32_bf16 v[54:57], v[230:233], v[246:249], v[18:21]
	s_barrier
	s_mov_b32 m0, s57
	s_nop 2
	v_lshl_add_u64 v[18:19], v[250:251], 0, s[6:7]
	s_add_u32 s28, s34, 0x10080
	ds_read_b128 v[38:41], v148 offset:49152
	ds_read_b128 v[46:49], v148 offset:50176
	ds_read_b128 v[178:181], v148 offset:51200
	ds_read_b128 v[182:185], v148 offset:52224
	ds_read_b128 v[210:213], v148 offset:53248
	ds_read_b128 v[214:217], v148 offset:54272
	ds_read_b128 v[234:237], v148 offset:55296
	ds_read_b128 v[238:241], v148 offset:56320
	global_load_lds_dwordx4 v[18:19], off
	v_lshl_add_u64 v[18:19], v[252:253], 0, s[6:7]
	s_mov_b32 m0, s55
	s_addc_u32 s29, s35, 0
	global_load_lds_dwordx4 v[18:19], off
	v_lshl_add_u64 v[18:19], s[28:29], 0, v[132:133]
	s_mov_b32 m0, s30
	s_nop 0
	global_load_lds_dwordx4 v[18:19], off
	v_lshl_add_u64 v[18:19], s[28:29], 0, v[136:137]
	s_mov_b32 m0, s31
	s_nop 0
	global_load_lds_dwordx4 v[18:19], off
	v_lshl_add_u64 v[18:19], v[138:139], 0, s[6:7]
	s_mov_b32 m0, s45
	s_nop 0
	global_load_lds_dwordx4 v[18:19], off
	v_lshl_add_u64 v[18:19], v[140:141], 0, s[6:7]
	s_mov_b32 m0, s46
	s_nop 0
	global_load_lds_dwordx4 v[18:19], off
	s_waitcnt vmcnt(8)
	s_waitcnt lgkmcnt(0)
	s_barrier
	s_waitcnt lgkmcnt(0)
	v_mfma_f32_16x16x32_bf16 v[18:21], v[10:13], v[38:41], v[142:145]
	v_mfma_f32_16x16x32_bf16 v[78:81], v[22:25], v[46:49], v[18:21]
	v_mfma_f32_16x16x32_bf16 v[18:21], v[174:177], v[38:41], v[150:153]
	v_mfma_f32_16x16x32_bf16 v[70:73], v[194:197], v[46:49], v[18:21]
	v_mfma_f32_16x16x32_bf16 v[18:21], v[10:13], v[178:181], v[154:157]
	v_mfma_f32_16x16x32_bf16 v[42:45], v[22:25], v[182:185], v[18:21]
	v_mfma_f32_16x16x32_bf16 v[18:21], v[174:177], v[178:181], v[158:161]
	v_mfma_f32_16x16x32_bf16 v[34:37], v[194:197], v[182:185], v[18:21]
	v_mfma_f32_16x16x32_bf16 v[18:21], v[10:13], v[210:213], v[162:165]
	v_mfma_f32_16x16x32_bf16 v[2:5], v[10:13], v[234:237], v[2:5]
	v_mfma_f32_16x16x32_bf16 v[26:29], v[22:25], v[214:217], v[18:21]
	v_mfma_f32_16x16x32_bf16 v[18:21], v[174:177], v[210:213], v[166:169]
	v_mfma_f32_16x16x32_bf16 v[10:13], v[22:25], v[238:241], v[2:5]
	v_mfma_f32_16x16x32_bf16 v[2:5], v[174:177], v[234:237], v[6:9]
	v_mfma_f32_16x16x32_bf16 v[18:21], v[194:197], v[214:217], v[18:21]
	v_mfma_f32_16x16x32_bf16 v[2:5], v[194:197], v[238:241], v[2:5]
	v_mfma_f32_16x16x32_bf16 v[6:9], v[198:201], v[38:41], v[202:205]
	v_mfma_f32_16x16x32_bf16 v[74:77], v[222:225], v[46:49], v[6:9]
	v_mfma_f32_16x16x32_bf16 v[6:9], v[226:229], v[38:41], v[14:17]
	v_mfma_f32_16x16x32_bf16 v[66:69], v[230:233], v[46:49], v[6:9]
	v_mfma_f32_16x16x32_bf16 v[6:9], v[198:201], v[178:181], v[206:209]
	v_mfma_f32_16x16x32_bf16 v[46:49], v[222:225], v[182:185], v[6:9]
	v_mfma_f32_16x16x32_bf16 v[6:9], v[226:229], v[178:181], v[30:33]
	v_mfma_f32_16x16x32_bf16 v[38:41], v[230:233], v[182:185], v[6:9]
	v_mfma_f32_16x16x32_bf16 v[6:9], v[198:201], v[210:213], v[218:221]
	v_mfma_f32_16x16x32_bf16 v[30:33], v[222:225], v[214:217], v[6:9]
	v_mfma_f32_16x16x32_bf16 v[6:9], v[226:229], v[210:213], v[186:189]
	v_mfma_f32_16x16x32_bf16 v[22:25], v[230:233], v[214:217], v[6:9]
	v_mfma_f32_16x16x32_bf16 v[6:9], v[198:201], v[234:237], v[190:193]
	v_mfma_f32_16x16x32_bf16 v[14:17], v[222:225], v[238:241], v[6:9]
	v_mfma_f32_16x16x32_bf16 v[6:9], v[226:229], v[234:237], v[170:173]
	v_mfma_f32_16x16x32_bf16 v[6:9], v[230:233], v[238:241], v[6:9]
	s_barrier
	s_andn2_b64 vcc, exec, s[8:9]
	s_cbranch_vccnz .LBB0_2246
	s_barrier

; __global__ void __launch_bounds__(NWAVES * 64, 2) mk_fwd(Args args) {
;     ...
;     if (IN(G_PLE)) {
;         pg8::Gemm g{(const bf16*)(ws + WS_X8D), (const bf16*)(ws + WS_W8P), M, D, D / 2, D / 2, D / 2, 0}; pg8::StaticOrder S; S.init(M, D, F.G, bx);
;         pg8::EpiF<1, true> E{F.out, F.out, (const float*)(ws + CTL_SS3), (const bf16*)(ws + WS_PP), nullptr, nullptr, nullptr, (const float*)(ws + WS_SX4), (const float*)(ws + WS_SWP)};
;         pg8::gemm_phase<pg8::EpiF<1, true>, pg8::StaticOrder, true, true, true>(F.lds + RING_OFF, g, S, E);
.LBB0_2304:
	s_cmp_lt_i32 s72, 15
	s_cselect_b64 s[0:1], -1, 0
	s_cmp_gt_i32 s73, 14
	s_cselect_b64 s[2:3], -1, 0
	s_and_b64 s[0:1], s[0:1], s[2:3]
	s_andn2_b64 vcc, exec, s[0:1]
	s_cbranch_vccnz .LBB0_2329
	v_readfirstlane_b32 s98, v0
	s_nop 3
	s_and_b32 s98, s98, 0x3ff
	s_lshr_b32 s98, s98, 6
	s_cmp_ge_u32 s98, 4
	s_cbranch_scc0 .Lprio_ple
	s_setprio 1

; #define PG8_STAGE(bufoff, gbase, voff) do { _Pragma("unroll") for (int _i = 0; _i < 2; ++_i) \
;         __builtin_amdgcn_global_load_lds((const unsigned*)((const char*)(gbase) + (voff)[_i]), (PG8_LAS unsigned*)(lds + (bufoff) + ldsw + _i * 8192), 16, 0, 0); } while (0)
; #define PG8_LDA(dst, b, h) do { _Pragma("unroll") for (int m = 0; m < 4; ++m) _Pragma("unroll") for (int k = 0; k < 2; ++k) dst[m][k] = *(const PG8_LAS bf16x8*)(lds + PG8_SA(b, h) + aoff + m * 2048 + k * 1024); } while (0)
; #define PG8_LDB(dst, b, h) do { _Pragma("unroll") for (int n = 0; n < 2; ++n) _Pragma("unroll") for (int k = 0; k < 2; ++k) dst[n][k] = *(const PG8_LAS bf16x8*)(lds + PG8_SB(b, h) + boff + n * 2048 + k * 1024); } while (0)
; #define PG8_MMA(ai, bj, At, Bt) do { __builtin_amdgcn_s_setprio(1); _Pragma("unroll") for (int m = 0; m < 4; ++m) _Pragma("unroll") for (int n = 0; n < 2; ++n) _Pragma("unroll") for (int k = 0; k < 2; ++k) \
;         acc[ai][bj][m][n] = mma_<I8>(Bt[n][k], At[m][k], acc[ai][bj][m][n]); __builtin_amdgcn_s_setprio(0); } while (0)
; #define PG8_WAIT_V(n) asm volatile("s_waitcnt vmcnt(" #n ")" ::: "memory")
; #define PG8_WAIT_L(n) asm volatile("s_waitcnt lgkmcnt(" #n ")" ::: "memory")
; template <class Epi, class Sched, bool ALIGN_EPI = false, bool SP2 = false, bool I8 = false>
; __device__ __forceinline__ void gemm_phase(PG8_LAS unsigned char* lds, const Gemm g, const Sched& S, const Epi& E) {
;     ...
;         for (int t = 0; t < nt; t += 2) {
;             const bool last = (t == nt - 2);
;             const char* a1 = cA + (size_t)(t + 1) * kstep;
;             const char* a2 = last ? nA : cA + (size_t)(t + 2) * kstep; const char* b2 = last ? nB : cB + (size_t)(t + 2) * kstep;
;             const char* a3 = a2 + kstep; const char* b3 = b2 + kstep;
;             if (last && has_next) S.a_ready(nxt);
;             if constexpr (SP2) {
;             PG8_LDB(B0, 0, 0); PG8_LDB(B1, 0, 1); PG8_SCHED; PG8_LDA(At, 0, 0); PG8_STAGE(PG8_SA(1, 1), a1 + hstepA, voffA);
;             PG8_WAIT_V(8); PG8_WAIT_L(0); PG8_BAR; PG8_MMA(0, 0, At, B0); PG8_MMA(0, 1, At, B1); PG8_BAR; PG8_SCHED;
;             PG8_LDA(At, 0, 1); PG8_STAGE(PG8_SB(0, 0), b2, voffB); PG8_STAGE(PG8_SB(0, 1), b2 + hstepB, voffB); PG8_STAGE(PG8_SA(0, 0), a2, voffA);
;             PG8_WAIT_V(8); PG8_WAIT_L(0); PG8_BAR; PG8_MMA(1, 0, At, B0); PG8_MMA(1, 1, At, B1); PG8_BAR; PG8_SCHED;
.LBB0_2322:
	ds_read_b128 v[58:61], v183
	ds_read_b128 v[66:69], v183 offset:1024
	ds_read_b128 v[74:77], v183 offset:2048
	ds_read_b128 v[78:81], v183 offset:3072
	ds_read_b128 v[146:149], v189
	ds_read_b128 v[150:153], v189 offset:1024
	ds_read_b128 v[154:157], v189 offset:2048
	ds_read_b128 v[158:161], v189 offset:3072
	s_add_u32 s28, s26, 0xfff80080
	s_addc_u32 s29, s27, -1
	s_cmp_eq_u32 s53, 28
	s_cselect_b32 s31, s21, s29
	s_cselect_b32 s30, s49, s28
	s_cselect_b32 s29, s19, s52
	s_cselect_b32 s28, s50, s51
	v_lshl_add_u64 v[190:191], s[26:27], 0, v[170:171]
	s_add_i32 m0, s3, 0xc000
	ds_read_b128 v[162:165], v193
	ds_read_b128 v[178:181], v193 offset:1024
	ds_read_b128 v[184:187], v193 offset:2048
	ds_read_b128 v[198:201], v193 offset:3072
	ds_read_b128 v[202:205], v193 offset:4096
	ds_read_b128 v[206:209], v193 offset:5120
	ds_read_b128 v[210:213], v193 offset:6144
	ds_read_b128 v[214:217], v193 offset:7168
	global_load_lds_dwordx4 v[190:191], off
	v_lshl_add_u64 v[190:191], s[26:27], 0, v[172:173]
	s_add_i32 m0, s3, 0xe000
	s_nop 0
	global_load_lds_dwordx4 v[190:191], off
	s_waitcnt vmcnt(8)
	s_waitcnt lgkmcnt(0)
	s_barrier
	s_waitcnt lgkmcnt(0)
	v_mfma_i32_16x16x64_i8 v[142:145], v[58:61], v[162:165], v[142:145]
	v_mfma_i32_16x16x64_i8 v[138:141], v[74:77], v[162:165], v[138:141]
	v_mfma_i32_16x16x64_i8 v[126:129], v[58:61], v[184:187], v[126:129]
	v_mfma_i32_16x16x64_i8 v[122:125], v[74:77], v[184:187], v[122:125]
	v_mfma_i32_16x16x64_i8 v[110:113], v[58:61], v[202:205], v[110:113]
	v_mfma_i32_16x16x64_i8 v[106:109], v[74:77], v[202:205], v[106:109]
	v_mfma_i32_16x16x64_i8 v[94:97], v[58:61], v[210:213], v[94:97]
	v_mfma_i32_16x16x64_i8 v[90:93], v[74:77], v[210:213], v[90:93]
	v_mfma_i32_16x16x64_i8 v[142:145], v[66:69], v[178:181], v[142:145]
	v_mfma_i32_16x16x64_i8 v[138:141], v[78:81], v[178:181], v[138:141]
	v_mfma_i32_16x16x64_i8 v[126:129], v[66:69], v[198:201], v[126:129]
	v_mfma_i32_16x16x64_i8 v[122:125], v[78:81], v[198:201], v[122:125]
	v_mfma_i32_16x16x64_i8 v[110:113], v[66:69], v[206:209], v[110:113]
	v_mfma_i32_16x16x64_i8 v[106:109], v[78:81], v[206:209], v[106:109]
	v_mfma_i32_16x16x64_i8 v[94:97], v[66:69], v[214:217], v[94:97]
	v_mfma_i32_16x16x64_i8 v[90:93], v[78:81], v[214:217], v[90:93]
	v_mfma_i32_16x16x64_i8 v[134:137], v[146:149], v[162:165], v[134:137]
	v_mfma_i32_16x16x64_i8 v[130:133], v[154:157], v[162:165], v[130:133]
	v_mfma_i32_16x16x64_i8 v[118:121], v[146:149], v[184:187], v[118:121]
	v_mfma_i32_16x16x64_i8 v[114:117], v[154:157], v[184:187], v[114:117]
	v_mfma_i32_16x16x64_i8 v[102:105], v[146:149], v[202:205], v[102:105]
	v_mfma_i32_16x16x64_i8 v[98:101], v[154:157], v[202:205], v[98:101]
	v_mfma_i32_16x16x64_i8 v[86:89], v[146:149], v[210:213], v[86:89]
	v_mfma_i32_16x16x64_i8 v[82:85], v[154:157], v[210:213], v[82:85]
	v_mfma_i32_16x16x64_i8 v[134:137], v[150:153], v[178:181], v[134:137]
	v_mfma_i32_16x16x64_i8 v[130:133], v[158:161], v[178:181], v[130:133]
	v_mfma_i32_16x16x64_i8 v[118:121], v[150:153], v[198:201], v[118:121]
	v_mfma_i32_16x16x64_i8 v[114:117], v[158:161], v[198:201], v[114:117]
	v_mfma_i32_16x16x64_i8 v[102:105], v[150:153], v[206:209], v[102:105]
	v_mfma_i32_16x16x64_i8 v[98:101], v[158:161], v[206:209], v[98:101]
	v_mfma_i32_16x16x64_i8 v[86:89], v[150:153], v[214:217], v[86:89]
	v_mfma_i32_16x16x64_i8 v[82:85], v[158:161], v[214:217], v[82:85]
	s_barrier
	s_add_i32 s54, s46, s38
	v_lshl_add_u64 v[190:191], s[28:29], 0, v[166:167]
	s_mov_b32 m0, s54
	ds_read_b128 v[162:165], v193 offset:16384
	ds_read_b128 v[178:181], v193 offset:17408
	ds_read_b128 v[184:187], v193 offset:18432
	ds_read_b128 v[198:201], v193 offset:19456
	ds_read_b128 v[202:205], v193 offset:20480
	ds_read_b128 v[206:209], v193 offset:21504
	ds_read_b128 v[210:213], v193 offset:22528
	ds_read_b128 v[214:217], v193 offset:23552
	global_load_lds_dwordx4 v[190:191], off
	s_add_i32 m0, s54, 0x2000
	s_add_u32 s54, s28, 0x80000
	v_lshl_add_u64 v[194:195], s[28:29], 0, v[168:169]
	s_addc_u32 s55, s29, 0
	s_add_i32 s56, s47, s38
	global_load_lds_dwordx4 v[194:195], off
	v_lshl_add_u64 v[218:219], s[54:55], 0, v[166:167]
	s_mov_b32 m0, s56
	v_lshl_add_u64 v[220:221], s[30:31], 0, v[168:169]
	global_load_lds_dwordx4 v[218:219], off
	v_lshl_add_u64 v[218:219], s[54:55], 0, v[168:169]
	s_add_i32 m0, s56, 0x2000
	s_nop 0
	global_load_lds_dwordx4 v[218:219], off
	v_lshl_add_u64 v[218:219], s[30:31], 0, v[166:167]
	s_mov_b32 m0, s3
	s_nop 0
	global_load_lds_dwordx4 v[218:219], off
	s_mov_b32 m0, s39
	s_nop 0
	global_load_lds_dwordx4 v[220:221], off
	s_waitcnt vmcnt(8)
	s_waitcnt lgkmcnt(0)
	s_barrier
; #define PG8_STAGE(bufoff, gbase, voff) do { _Pragma("unroll") for (int _i = 0; _i < 2; ++_i) \
;         __builtin_amdgcn_global_load_lds((const unsigned*)((const char*)(gbase) + (voff)[_i]), (PG8_LAS unsigned*)(lds + (bufoff) + ldsw + _i * 8192), 16, 0, 0); } while (0)
; #define PG8_LDA(dst, b, h) do { _Pragma("unroll") for (int m = 0; m < 4; ++m) _Pragma("unroll") for (int k = 0; k < 2; ++k) dst[m][k] = *(const PG8_LAS bf16x8*)(lds + PG8_SA(b, h) + aoff + m * 2048 + k * 1024); } while (0)
; #define PG8_LDB(dst, b, h) do { _Pragma("unroll") for (int n = 0; n < 2; ++n) _Pragma("unroll") for (int k = 0; k < 2; ++k) dst[n][k] = *(const PG8_LAS bf16x8*)(lds + PG8_SB(b, h) + boff + n * 2048 + k * 1024); } while (0)
; #define PG8_MMA(ai, bj, At, Bt) do { __builtin_amdgcn_s_setprio(1); _Pragma("unroll") for (int m = 0; m < 4; ++m) _Pragma("unroll") for (int n = 0; n < 2; ++n) _Pragma("unroll") for (int k = 0; k < 2; ++k) \
;         acc[ai][bj][m][n] = mma_<I8>(Bt[n][k], At[m][k], acc[ai][bj][m][n]); __builtin_amdgcn_s_setprio(0); } while (0)
; #define PG8_WAIT_V(n) asm volatile("s_waitcnt vmcnt(" #n ")" ::: "memory")
; #define PG8_WAIT_L(n) asm volatile("s_waitcnt lgkmcnt(" #n ")" ::: "memory")
; #define PG8_BAR __builtin_amdgcn_s_barrier()
; #define PG8_SCHED __builtin_amdgcn_sched_barrier(0)
; template <class Epi, class Sched, bool ALIGN_EPI = false, bool SP2 = false, bool I8 = false>
; __device__ __forceinline__ void gemm_phase(PG8_LAS unsigned char* lds, const Gemm g, const Sched& S, const Epi& E) {
;     ...
;             PG8_WAIT_V(8); PG8_WAIT_L(0); PG8_BAR; PG8_MMA(1, 0, At, B0); PG8_MMA(1, 1, At, B1); PG8_BAR; PG8_SCHED;
;             PG8_LDB(B0, 1, 0); PG8_LDB(B1, 1, 1); PG8_SCHED; PG8_LDA(At, 1, 0); PG8_STAGE(PG8_SA(0, 1), a2 + hstepA, voffA);
;             PG8_WAIT_V(8); PG8_WAIT_L(0); PG8_BAR; PG8_MMA(0, 0, At, B0); PG8_MMA(0, 1, At, B1); PG8_BAR; PG8_SCHED;
	s_waitcnt lgkmcnt(0)
	v_mfma_i32_16x16x64_i8 v[70:73], v[58:61], v[162:165], v[70:73]
	v_mfma_i32_16x16x64_i8 v[62:65], v[74:77], v[162:165], v[62:65]
	v_mfma_i32_16x16x64_i8 v[46:49], v[58:61], v[184:187], v[46:49]
	v_mfma_i32_16x16x64_i8 v[42:45], v[74:77], v[184:187], v[42:45]
	v_mfma_i32_16x16x64_i8 v[30:33], v[58:61], v[202:205], v[30:33]
	v_mfma_i32_16x16x64_i8 v[26:29], v[74:77], v[202:205], v[26:29]
	v_mfma_i32_16x16x64_i8 v[14:17], v[58:61], v[210:213], v[14:17]
	v_mfma_i32_16x16x64_i8 v[10:13], v[74:77], v[210:213], v[10:13]
	v_mfma_i32_16x16x64_i8 v[70:73], v[66:69], v[178:181], v[70:73]
	v_mfma_i32_16x16x64_i8 v[62:65], v[78:81], v[178:181], v[62:65]
	v_mfma_i32_16x16x64_i8 v[46:49], v[66:69], v[198:201], v[46:49]
	v_mfma_i32_16x16x64_i8 v[42:45], v[78:81], v[198:201], v[42:45]
	v_mfma_i32_16x16x64_i8 v[30:33], v[66:69], v[206:209], v[30:33]
	v_mfma_i32_16x16x64_i8 v[26:29], v[78:81], v[206:209], v[26:29]
	v_mfma_i32_16x16x64_i8 v[14:17], v[66:69], v[214:217], v[14:17]
	v_mfma_i32_16x16x64_i8 v[10:13], v[78:81], v[214:217], v[10:13]
	v_mfma_i32_16x16x64_i8 v[54:57], v[146:149], v[162:165], v[54:57]
	v_mfma_i32_16x16x64_i8 v[50:53], v[154:157], v[162:165], v[50:53]
	v_mfma_i32_16x16x64_i8 v[38:41], v[146:149], v[184:187], v[38:41]
	v_mfma_i32_16x16x64_i8 v[34:37], v[154:157], v[184:187], v[34:37]
	v_mfma_i32_16x16x64_i8 v[22:25], v[146:149], v[202:205], v[22:25]
	v_mfma_i32_16x16x64_i8 v[18:21], v[154:157], v[202:205], v[18:21]
	v_mfma_i32_16x16x64_i8 v[6:9], v[146:149], v[210:213], v[6:9]
	v_mfma_i32_16x16x64_i8 v[2:5], v[154:157], v[210:213], v[2:5]
	v_mfma_i32_16x16x64_i8 v[54:57], v[150:153], v[178:181], v[54:57]
	v_mfma_i32_16x16x64_i8 v[50:53], v[158:161], v[178:181], v[50:53]
	v_mfma_i32_16x16x64_i8 v[38:41], v[150:153], v[198:201], v[38:41]
	v_mfma_i32_16x16x64_i8 v[34:37], v[158:161], v[198:201], v[34:37]
	v_mfma_i32_16x16x64_i8 v[22:25], v[150:153], v[206:209], v[22:25]
	v_mfma_i32_16x16x64_i8 v[18:21], v[158:161], v[206:209], v[18:21]
	v_mfma_i32_16x16x64_i8 v[6:9], v[150:153], v[214:217], v[6:9]
	v_mfma_i32_16x16x64_i8 v[2:5], v[158:161], v[214:217], v[2:5]
	s_barrier
	s_add_i32 s54, 0, 0x18000
	s_add_i32 s55, 0, 0x1c000
	v_add_u32_e32 v78, s54, v1
	v_add_u32_e32 v158, s55, v1
	ds_read_b128 v[58:61], v78
	ds_read_b128 v[66:69], v78 offset:1024
	ds_read_b128 v[74:77], v78 offset:2048
	ds_read_b128 v[78:81], v78 offset:3072
	ds_read_b128 v[146:149], v158
	ds_read_b128 v[150:153], v158 offset:1024
	ds_read_b128 v[154:157], v158 offset:2048
	ds_read_b128 v[158:161], v158 offset:3072
	s_add_u32 s30, s30, 0x80000
	s_addc_u32 s31, s31, 0
	s_mov_b32 m0, s40
	v_lshl_add_u64 v[222:223], s[30:31], 0, v[166:167]
	ds_read_b128 v[162:165], v193 offset:32768
	ds_read_b128 v[178:181], v193 offset:33792
	ds_read_b128 v[184:187], v193 offset:34816
	ds_read_b128 v[198:201], v193 offset:35840
	ds_read_b128 v[202:205], v193 offset:36864
	ds_read_b128 v[206:209], v193 offset:37888
	ds_read_b128 v[210:213], v193 offset:38912
	ds_read_b128 v[214:217], v193 offset:39936
	global_load_lds_dwordx4 v[222:223], off
	v_lshl_add_u64 v[222:223], s[30:31], 0, v[168:169]
	s_mov_b32 m0, s41
	s_nop 0
	global_load_lds_dwordx4 v[222:223], off
	s_waitcnt vmcnt(8)
	s_waitcnt lgkmcnt(0)
	s_barrier
	s_waitcnt lgkmcnt(0)
	v_mfma_i32_16x16x64_i8 v[142:145], v[58:61], v[162:165], v[142:145]
	v_mfma_i32_16x16x64_i8 v[138:141], v[74:77], v[162:165], v[138:141]
	v_mfma_i32_16x16x64_i8 v[126:129], v[58:61], v[184:187], v[126:129]
	v_mfma_i32_16x16x64_i8 v[122:125], v[74:77], v[184:187], v[122:125]
	v_mfma_i32_16x16x64_i8 v[110:113], v[58:61], v[202:205], v[110:113]
	v_mfma_i32_16x16x64_i8 v[106:109], v[74:77], v[202:205], v[106:109]
	v_mfma_i32_16x16x64_i8 v[94:97], v[58:61], v[210:213], v[94:97]
	v_mfma_i32_16x16x64_i8 v[90:93], v[74:77], v[210:213], v[90:93]
	v_mfma_i32_16x16x64_i8 v[142:145], v[66:69], v[178:181], v[142:145]
	v_mfma_i32_16x16x64_i8 v[138:141], v[78:81], v[178:181], v[138:141]
	v_mfma_i32_16x16x64_i8 v[126:129], v[66:69], v[198:201], v[126:129]
	v_mfma_i32_16x16x64_i8 v[122:125], v[78:81], v[198:201], v[122:125]
	v_mfma_i32_16x16x64_i8 v[110:113], v[66:69], v[206:209], v[110:113]
	v_mfma_i32_16x16x64_i8 v[106:109], v[78:81], v[206:209], v[106:109]
	v_mfma_i32_16x16x64_i8 v[94:97], v[66:69], v[214:217], v[94:97]
	v_mfma_i32_16x16x64_i8 v[90:93], v[78:81], v[214:217], v[90:93]
	v_mfma_i32_16x16x64_i8 v[134:137], v[146:149], v[162:165], v[134:137]
	v_mfma_i32_16x16x64_i8 v[130:133], v[154:157], v[162:165], v[130:133]
	v_mfma_i32_16x16x64_i8 v[118:121], v[146:149], v[184:187], v[118:121]
	v_mfma_i32_16x16x64_i8 v[114:117], v[154:157], v[184:187], v[114:117]
	v_mfma_i32_16x16x64_i8 v[102:105], v[146:149], v[202:205], v[102:105]
	v_mfma_i32_16x16x64_i8 v[98:101], v[154:157], v[202:205], v[98:101]
	v_mfma_i32_16x16x64_i8 v[86:89], v[146:149], v[210:213], v[86:89]
	v_mfma_i32_16x16x64_i8 v[82:85], v[154:157], v[210:213], v[82:85]
	v_mfma_i32_16x16x64_i8 v[134:137], v[150:153], v[178:181], v[134:137]
	v_mfma_i32_16x16x64_i8 v[130:133], v[158:161], v[178:181], v[130:133]
	v_mfma_i32_16x16x64_i8 v[118:121], v[150:153], v[198:201], v[118:121]
	v_mfma_i32_16x16x64_i8 v[114:117], v[158:161], v[198:201], v[114:117]
	v_mfma_i32_16x16x64_i8 v[102:105], v[150:153], v[206:209], v[102:105]
	v_mfma_i32_16x16x64_i8 v[98:101], v[158:161], v[206:209], v[98:101]
	v_mfma_i32_16x16x64_i8 v[86:89], v[150:153], v[214:217], v[86:89]
	v_mfma_i32_16x16x64_i8 v[82:85], v[158:161], v[214:217], v[82:85]
	s_barrier
; #define PG8_STAGE(bufoff, gbase, voff) do { _Pragma("unroll") for (int _i = 0; _i < 2; ++_i) \
;         __builtin_amdgcn_global_load_lds((const unsigned*)((const char*)(gbase) + (voff)[_i]), (PG8_LAS unsigned*)(lds + (bufoff) + ldsw + _i * 8192), 16, 0, 0); } while (0)
; #define PG8_LDA(dst, b, h) do { _Pragma("unroll") for (int m = 0; m < 4; ++m) _Pragma("unroll") for (int k = 0; k < 2; ++k) dst[m][k] = *(const PG8_LAS bf16x8*)(lds + PG8_SA(b, h) + aoff + m * 2048 + k * 1024); } while (0)
; #define PG8_MMA(ai, bj, At, Bt) do { __builtin_amdgcn_s_setprio(1); _Pragma("unroll") for (int m = 0; m < 4; ++m) _Pragma("unroll") for (int n = 0; n < 2; ++n) _Pragma("unroll") for (int k = 0; k < 2; ++k) \
;         acc[ai][bj][m][n] = mma_<I8>(Bt[n][k], At[m][k], acc[ai][bj][m][n]); __builtin_amdgcn_s_setprio(0); } while (0)
; #define PG8_WAIT_V(n) asm volatile("s_waitcnt vmcnt(" #n ")" ::: "memory")
; #define PG8_WAIT_L(n) asm volatile("s_waitcnt lgkmcnt(" #n ")" ::: "memory")
; #define PG8_BAR __builtin_amdgcn_s_barrier()
; #define PG8_SCHED __builtin_amdgcn_sched_barrier(0)
; template <class Epi, class Sched, bool ALIGN_EPI = false, bool SP2 = false, bool I8 = false>
; __device__ __forceinline__ void gemm_phase(PG8_LAS unsigned char* lds, const Gemm g, const Sched& S, const Epi& E) {
;     ...
;             PG8_WAIT_V(8); PG8_WAIT_L(0); PG8_BAR; PG8_MMA(0, 0, At, B0); PG8_MMA(0, 1, At, B1); PG8_BAR; PG8_SCHED;
;             PG8_LDA(At, 1, 1); PG8_STAGE(PG8_SB(1, 0), b3, voffB); PG8_STAGE(PG8_SB(1, 1), b3 + hstepB, voffB); PG8_STAGE(PG8_SA(1, 0), a3, voffA);
;             PG8_WAIT_V(8); PG8_WAIT_L(0); PG8_BAR; PG8_MMA(1, 0, At, B0); PG8_MMA(1, 1, At, B1); PG8_BAR; PG8_SCHED;
;     ...
;         if constexpr (ALIGN_EPI) { if (wr == 0) PG8_BAR; }
	s_add_i32 s30, s54, s38
	v_lshl_add_u64 v[190:191], v[190:191], 0, s[14:15]
	s_mov_b32 m0, s30
	ds_read_b128 v[162:165], v193 offset:49152
	ds_read_b128 v[178:181], v193 offset:50176
	ds_read_b128 v[184:187], v193 offset:51200
	ds_read_b128 v[198:201], v193 offset:52224
	ds_read_b128 v[202:205], v193 offset:53248
	ds_read_b128 v[206:209], v193 offset:54272
	ds_read_b128 v[210:213], v193 offset:55296
	ds_read_b128 v[214:217], v193 offset:56320
	global_load_lds_dwordx4 v[190:191], off
	s_add_i32 m0, s30, 0x2000
	s_add_u32 s28, s28, 0x80080
	v_lshl_add_u64 v[190:191], v[194:195], 0, s[14:15]
	s_addc_u32 s29, s29, 0
	s_add_i32 s30, s55, s38
	global_load_lds_dwordx4 v[190:191], off
	v_lshl_add_u64 v[190:191], s[28:29], 0, v[166:167]
	s_mov_b32 m0, s30
	s_nop 0
	global_load_lds_dwordx4 v[190:191], off
	v_lshl_add_u64 v[190:191], s[28:29], 0, v[168:169]
	s_add_i32 m0, s30, 0x2000
	s_nop 0
	global_load_lds_dwordx4 v[190:191], off
	v_lshl_add_u64 v[190:191], v[218:219], 0, s[14:15]
	s_mov_b32 m0, s43
	s_nop 0
	global_load_lds_dwordx4 v[190:191], off
	v_lshl_add_u64 v[190:191], v[220:221], 0, s[14:15]
	s_mov_b32 m0, s44
	s_nop 0
	global_load_lds_dwordx4 v[190:191], off
	s_waitcnt vmcnt(8)
	s_waitcnt lgkmcnt(0)
	s_barrier
	s_waitcnt lgkmcnt(0)
	v_mfma_i32_16x16x64_i8 v[70:73], v[58:61], v[162:165], v[70:73]
	v_mfma_i32_16x16x64_i8 v[62:65], v[74:77], v[162:165], v[62:65]
	v_mfma_i32_16x16x64_i8 v[46:49], v[58:61], v[184:187], v[46:49]
	v_mfma_i32_16x16x64_i8 v[42:45], v[74:77], v[184:187], v[42:45]
	v_mfma_i32_16x16x64_i8 v[30:33], v[58:61], v[202:205], v[30:33]
	v_mfma_i32_16x16x64_i8 v[26:29], v[74:77], v[202:205], v[26:29]
	v_mfma_i32_16x16x64_i8 v[14:17], v[58:61], v[210:213], v[14:17]
	v_mfma_i32_16x16x64_i8 v[10:13], v[74:77], v[210:213], v[10:13]
	v_mfma_i32_16x16x64_i8 v[70:73], v[66:69], v[178:181], v[70:73]
	v_mfma_i32_16x16x64_i8 v[62:65], v[78:81], v[178:181], v[62:65]
	v_mfma_i32_16x16x64_i8 v[46:49], v[66:69], v[198:201], v[46:49]
	v_mfma_i32_16x16x64_i8 v[42:45], v[78:81], v[198:201], v[42:45]
	v_mfma_i32_16x16x64_i8 v[30:33], v[66:69], v[206:209], v[30:33]
	v_mfma_i32_16x16x64_i8 v[26:29], v[78:81], v[206:209], v[26:29]
	v_mfma_i32_16x16x64_i8 v[14:17], v[66:69], v[214:217], v[14:17]
	v_mfma_i32_16x16x64_i8 v[10:13], v[78:81], v[214:217], v[10:13]
	v_mfma_i32_16x16x64_i8 v[54:57], v[146:149], v[162:165], v[54:57]
	v_mfma_i32_16x16x64_i8 v[50:53], v[154:157], v[162:165], v[50:53]
	v_mfma_i32_16x16x64_i8 v[38:41], v[146:149], v[184:187], v[38:41]
	v_mfma_i32_16x16x64_i8 v[34:37], v[154:157], v[184:187], v[34:37]
	v_mfma_i32_16x16x64_i8 v[22:25], v[146:149], v[202:205], v[22:25]
	v_mfma_i32_16x16x64_i8 v[18:21], v[154:157], v[202:205], v[18:21]
	v_mfma_i32_16x16x64_i8 v[6:9], v[146:149], v[210:213], v[6:9]
	v_mfma_i32_16x16x64_i8 v[2:5], v[154:157], v[210:213], v[2:5]
	v_mfma_i32_16x16x64_i8 v[54:57], v[150:153], v[178:181], v[54:57]
	v_mfma_i32_16x16x64_i8 v[50:53], v[158:161], v[178:181], v[50:53]
	v_mfma_i32_16x16x64_i8 v[38:41], v[150:153], v[198:201], v[38:41]
	v_mfma_i32_16x16x64_i8 v[34:37], v[158:161], v[198:201], v[34:37]
	v_mfma_i32_16x16x64_i8 v[22:25], v[150:153], v[206:209], v[22:25]
	v_mfma_i32_16x16x64_i8 v[18:21], v[158:161], v[206:209], v[18:21]
	v_mfma_i32_16x16x64_i8 v[6:9], v[150:153], v[214:217], v[6:9]
	v_mfma_i32_16x16x64_i8 v[2:5], v[158:161], v[214:217], v[2:5]
	s_barrier
	s_add_i32 s53, s53, 2
	s_add_u32 s26, s26, 0x100
	s_addc_u32 s27, s27, 0
	s_add_u32 s51, s51, 0x100
	s_addc_u32 s52, s52, 0
	s_cmp_gt_u32 s53, 29
	s_cbranch_scc0 .LBB0_2322
	s_and_b64 vcc, exec, s[16:17]
	s_cbranch_vccz .LBB0_2325
	s_barrier

; __global__ void __launch_bounds__(NWAVES * 64, 2) mk_fwd(Args args) {
;     ...
;         pg8::gemm_phase<pg8::EpiF<1, true>, pg8::StaticOrder, true, true, true>(F.lds + RING_OFF, g, S, E);
;     }
;     ...
; }
.LBB0_2329:
	s_setprio 0
	s_endpgm
